# v69 plus GEMM load-segment trim: vmcnt/lgkmcnt waits merged into one s_waitcnt, M0 writes hoisted above the address add so the s_nop wait state is dropped (172 sites)
# speedup vs baseline: 1.0268x; 1.0013x over previous
.LBB0_196:
	s_cmp_lg_u32 s22, 0
	s_mov_b32 s22, 0
	s_cbranch_scc0 .LBB0_198
	ds_read_b128 v[2:5], v161
	ds_read_b128 v[6:9], v161 offset:1024
	ds_read_b128 v[10:13], v161 offset:2048
	ds_read_b128 v[14:17], v161 offset:3072
	ds_read_b128 v[18:21], v162
	ds_read_b128 v[22:25], v162 offset:1024
	ds_read_b128 v[26:29], v162 offset:2048
	ds_read_b128 v[30:33], v162 offset:3072
	s_add_u32 s0, s4, 0x10000
	s_addc_u32 s1, s5, 0
	ds_read_b128 v[34:37], v163
	ds_read_b128 v[38:41], v163 offset:1024
	ds_read_b128 v[42:45], v163 offset:2048
	ds_read_b128 v[46:49], v163 offset:3072
	ds_read_b128 v[50:53], v163 offset:4096
	ds_read_b128 v[54:57], v163 offset:5120
	ds_read_b128 v[58:61], v163 offset:6144
	ds_read_b128 v[62:65], v163 offset:7168
	s_waitcnt vmcnt(24) lgkmcnt(0)
	s_barrier
	v_mfma_f32_16x16x32_bf16 v[90:93], v[2:5], v[58:61], 0
	v_mfma_f32_16x16x32_bf16 v[66:69], v[2:5], v[34:37], 0
	v_mfma_f32_16x16x32_bf16 v[70:73], v[10:13], v[34:37], 0
	v_mfma_f32_16x16x32_bf16 v[74:77], v[2:5], v[42:45], 0
	v_mfma_f32_16x16x32_bf16 v[78:81], v[10:13], v[42:45], 0
	v_mfma_f32_16x16x32_bf16 v[82:85], v[2:5], v[50:53], 0
	v_mfma_f32_16x16x32_bf16 v[86:89], v[10:13], v[50:53], 0
	v_mfma_f32_16x16x32_bf16 v[100:103], v[6:9], v[62:65], v[90:93]
	v_mfma_f32_16x16x32_bf16 v[90:93], v[10:13], v[58:61], 0
	v_mfma_f32_16x16x32_bf16 v[66:69], v[6:9], v[38:41], v[66:69]
	v_mfma_f32_16x16x32_bf16 v[70:73], v[14:17], v[38:41], v[70:73]
	v_mfma_f32_16x16x32_bf16 v[74:77], v[6:9], v[46:49], v[74:77]
	v_mfma_f32_16x16x32_bf16 v[78:81], v[14:17], v[46:49], v[78:81]
	v_mfma_f32_16x16x32_bf16 v[82:85], v[6:9], v[54:57], v[82:85]
	v_mfma_f32_16x16x32_bf16 v[86:89], v[14:17], v[54:57], v[86:89]
	v_mfma_f32_16x16x32_bf16 v[104:107], v[14:17], v[62:65], v[90:93]
	v_mfma_f32_16x16x32_bf16 v[90:93], v[18:21], v[34:37], 0
	v_mfma_f32_16x16x32_bf16 v[34:37], v[26:29], v[34:37], 0
	v_mfma_f32_16x16x32_bf16 v[116:119], v[22:25], v[38:41], v[90:93]
	v_mfma_f32_16x16x32_bf16 v[34:37], v[30:33], v[38:41], v[34:37]
	v_mfma_f32_16x16x32_bf16 v[38:41], v[18:21], v[42:45], 0
	v_mfma_f32_16x16x32_bf16 v[42:45], v[26:29], v[42:45], 0
	v_mfma_f32_16x16x32_bf16 v[38:41], v[22:25], v[46:49], v[38:41]
	v_mfma_f32_16x16x32_bf16 v[42:45], v[30:33], v[46:49], v[42:45]
	v_mfma_f32_16x16x32_bf16 v[46:49], v[18:21], v[50:53], 0
	v_mfma_f32_16x16x32_bf16 v[50:53], v[26:29], v[50:53], 0
	v_mfma_f32_16x16x32_bf16 v[46:49], v[22:25], v[54:57], v[46:49]
	v_mfma_f32_16x16x32_bf16 v[50:53], v[30:33], v[54:57], v[50:53]
	v_mfma_f32_16x16x32_bf16 v[54:57], v[18:21], v[58:61], 0
	v_mfma_f32_16x16x32_bf16 v[58:61], v[26:29], v[58:61], 0
	v_mfma_f32_16x16x32_bf16 v[54:57], v[22:25], v[62:65], v[54:57]
	v_mfma_f32_16x16x32_bf16 v[58:61], v[30:33], v[62:65], v[58:61]
	s_barrier
	s_add_i32 s12, s60, s17
	v_lshl_add_u64 v[98:99], s[0:1], 0, v[134:135]
	s_mov_b32 m0, s12
	ds_read_b128 v[62:65], v163 offset:16384
	ds_read_b128 v[90:93], v163 offset:17408
	ds_read_b128 v[94:97], v163 offset:18432
	ds_read_b128 v[108:111], v163 offset:19456
	ds_read_b128 v[112:115], v163 offset:20480
	ds_read_b128 v[120:123], v163 offset:21504
	ds_read_b128 v[124:127], v163 offset:22528
	ds_read_b128 v[128:131], v163 offset:23552
	global_load_lds_dwordx4 v[98:99], off
	s_add_i32 m0, s12, 0x2000
	v_lshl_add_u64 v[98:99], s[0:1], 0, v[138:139]
	s_add_u32 s0, s4, 0x14000
	s_addc_u32 s1, s5, 0
	s_add_i32 s12, s61, s17
	global_load_lds_dwordx4 v[98:99], off
	v_lshl_add_u64 v[98:99], s[0:1], 0, v[134:135]
	s_mov_b32 m0, s12
	v_lshl_add_u64 v[156:157], s[8:9], 0, v[132:133]
	global_load_lds_dwordx4 v[98:99], off
	v_lshl_add_u64 v[98:99], s[0:1], 0, v[138:139]
	s_add_i32 m0, s12, 0x2000
	v_lshl_add_u64 v[144:145], s[8:9], 0, v[136:137]
	global_load_lds_dwordx4 v[98:99], off
	s_mov_b32 m0, s18
	v_lshl_add_u64 v[98:99], v[156:157], 0, s[36:37]
	global_load_lds_dwordx4 v[98:99], off
	s_mov_b32 m0, s19
	v_lshl_add_u64 v[98:99], v[144:145], 0, s[36:37]
	global_load_lds_dwordx4 v[98:99], off
	s_waitcnt vmcnt(24) lgkmcnt(0)
	s_barrier
	v_mfma_f32_16x16x32_bf16 v[148:151], v[2:5], v[62:65], 0
	v_mfma_f32_16x16x32_bf16 v[166:169], v[2:5], v[94:97], 0
	v_mfma_f32_16x16x32_bf16 v[174:177], v[2:5], v[112:115], 0
	v_mfma_f32_16x16x32_bf16 v[2:5], v[2:5], v[124:127], 0
	v_mfma_f32_16x16x32_bf16 v[148:151], v[6:9], v[90:93], v[148:151]
	v_mfma_f32_16x16x32_bf16 v[166:169], v[6:9], v[108:111], v[166:169]
	v_mfma_f32_16x16x32_bf16 v[174:177], v[6:9], v[120:123], v[174:177]
	v_mfma_f32_16x16x32_bf16 v[2:5], v[6:9], v[128:131], v[2:5]
	v_mfma_f32_16x16x32_bf16 v[6:9], v[10:13], v[124:127], 0
	v_mfma_f32_16x16x32_bf16 v[152:155], v[10:13], v[62:65], 0
	v_mfma_f32_16x16x32_bf16 v[170:173], v[10:13], v[94:97], 0
	v_mfma_f32_16x16x32_bf16 v[178:181], v[10:13], v[112:115], 0
	v_mfma_f32_16x16x32_bf16 v[6:9], v[14:17], v[128:131], v[6:9]
	v_mfma_f32_16x16x32_bf16 v[152:155], v[14:17], v[90:93], v[152:155]
	v_mfma_f32_16x16x32_bf16 v[170:173], v[14:17], v[108:111], v[170:173]
	v_mfma_f32_16x16x32_bf16 v[178:181], v[14:17], v[120:123], v[178:181]
	v_mfma_f32_16x16x32_bf16 v[10:13], v[18:21], v[62:65], 0
	v_mfma_f32_16x16x32_bf16 v[182:185], v[22:25], v[90:93], v[10:13]
	v_mfma_f32_16x16x32_bf16 v[10:13], v[26:29], v[62:65], 0
	v_mfma_f32_16x16x32_bf16 v[186:189], v[30:33], v[90:93], v[10:13]
	v_mfma_f32_16x16x32_bf16 v[10:13], v[18:21], v[94:97], 0
	v_mfma_f32_16x16x32_bf16 v[190:193], v[22:25], v[108:111], v[10:13]
	v_mfma_f32_16x16x32_bf16 v[10:13], v[26:29], v[94:97], 0
	v_mfma_f32_16x16x32_bf16 v[194:197], v[30:33], v[108:111], v[10:13]
	v_mfma_f32_16x16x32_bf16 v[10:13], v[18:21], v[112:115], 0
	v_mfma_f32_16x16x32_bf16 v[198:201], v[22:25], v[120:123], v[10:13]
	v_mfma_f32_16x16x32_bf16 v[10:13], v[26:29], v[112:115], 0
	v_mfma_f32_16x16x32_bf16 v[202:205], v[30:33], v[120:123], v[10:13]
	v_mfma_f32_16x16x32_bf16 v[10:13], v[18:21], v[124:127], 0
	v_mfma_f32_16x16x32_bf16 v[206:209], v[22:25], v[128:131], v[10:13]
	v_mfma_f32_16x16x32_bf16 v[10:13], v[26:29], v[124:127], 0
	v_mfma_f32_16x16x32_bf16 v[210:213], v[30:33], v[128:131], v[10:13]
	s_barrier
	s_add_i32 s12, 0, 0x18000
	v_add_u32_e32 v1, s12, v160
	s_add_i32 s13, 0, 0x1c000
	s_nop 1
	ds_read_b128 v[10:13], v1
	ds_read_b128 v[14:17], v1 offset:1024
	ds_read_b128 v[20:23], v1 offset:2048
	ds_read_b128 v[24:27], v1 offset:3072
	v_add_u32_e32 v1, s13, v160
	ds_read_b128 v[214:217], v1
	ds_read_b128 v[218:221], v1 offset:1024
	ds_read_b128 v[222:225], v1 offset:2048
	ds_read_b128 v[226:229], v1 offset:3072
	s_add_u32 s0, s8, 0x100100
	s_addc_u32 s1, s9, 0
	s_mov_b32 m0, s20
	v_lshl_add_u64 v[18:19], s[0:1], 0, v[132:133]
	ds_read_b128 v[28:31], v163 offset:32768
	ds_read_b128 v[62:65], v163 offset:33792
	ds_read_b128 v[230:233], v163 offset:34816
	ds_read_b128 v[234:237], v163 offset:35840
	ds_read_b128 v[238:241], v163 offset:36864
	ds_read_b128 v[242:245], v163 offset:37888
	ds_read_b128 v[246:249], v163 offset:38912
	ds_read_b128 v[250:253], v163 offset:39936
	global_load_lds_dwordx4 v[18:19], off
	s_mov_b32 m0, s21
	v_lshl_add_u64 v[18:19], s[0:1], 0, v[136:137]
	global_load_lds_dwordx4 v[18:19], off
	s_waitcnt vmcnt(24) lgkmcnt(0)
	s_barrier
	v_mfma_f32_16x16x32_bf16 v[66:69], v[10:13], v[28:31], v[66:69]
	v_mfma_f32_16x16x32_bf16 v[128:131], v[14:17], v[62:65], v[66:69]
	v_mfma_f32_16x16x32_bf16 v[66:69], v[20:23], v[28:31], v[70:73]
	v_mfma_f32_16x16x32_bf16 v[124:127], v[24:27], v[62:65], v[66:69]
	v_mfma_f32_16x16x32_bf16 v[66:69], v[10:13], v[230:233], v[74:77]
	v_mfma_f32_16x16x32_bf16 v[112:115], v[14:17], v[234:237], v[66:69]
	v_mfma_f32_16x16x32_bf16 v[66:69], v[20:23], v[230:233], v[78:81]
	v_mfma_f32_16x16x32_bf16 v[108:111], v[24:27], v[234:237], v[66:69]
	v_mfma_f32_16x16x32_bf16 v[66:69], v[10:13], v[238:241], v[82:85]
	v_mfma_f32_16x16x32_bf16 v[96:99], v[14:17], v[242:245], v[66:69]
	v_mfma_f32_16x16x32_bf16 v[66:69], v[20:23], v[238:241], v[86:89]
	v_mfma_f32_16x16x32_bf16 v[92:95], v[24:27], v[242:245], v[66:69]
	v_mfma_f32_16x16x32_bf16 v[66:69], v[10:13], v[246:249], v[100:103]
	v_mfma_f32_16x16x32_bf16 v[80:83], v[14:17], v[250:253], v[66:69]
	v_mfma_f32_16x16x32_bf16 v[66:69], v[20:23], v[246:249], v[104:107]
	v_mfma_f32_16x16x32_bf16 v[76:79], v[24:27], v[250:253], v[66:69]
	v_mfma_f32_16x16x32_bf16 v[66:69], v[214:217], v[28:31], v[116:119]
	v_mfma_f32_16x16x32_bf16 v[28:31], v[222:225], v[28:31], v[34:37]
	v_mfma_f32_16x16x32_bf16 v[116:119], v[226:229], v[62:65], v[28:31]
	v_mfma_f32_16x16x32_bf16 v[28:31], v[214:217], v[230:233], v[38:41]
	v_mfma_f32_16x16x32_bf16 v[104:107], v[218:221], v[234:237], v[28:31]
	v_mfma_f32_16x16x32_bf16 v[28:31], v[222:225], v[230:233], v[42:45]
	v_mfma_f32_16x16x32_bf16 v[100:103], v[226:229], v[234:237], v[28:31]
	v_mfma_f32_16x16x32_bf16 v[28:31], v[214:217], v[238:241], v[46:49]
	v_mfma_f32_16x16x32_bf16 v[88:91], v[218:221], v[242:245], v[28:31]
	v_mfma_f32_16x16x32_bf16 v[28:31], v[222:225], v[238:241], v[50:53]
	v_mfma_f32_16x16x32_bf16 v[84:87], v[226:229], v[242:245], v[28:31]
	v_mfma_f32_16x16x32_bf16 v[28:31], v[214:217], v[246:249], v[54:57]
	v_mfma_f32_16x16x32_bf16 v[72:75], v[218:221], v[250:253], v[28:31]
	v_mfma_f32_16x16x32_bf16 v[28:31], v[222:225], v[246:249], v[58:61]
	v_mfma_f32_16x16x32_bf16 v[120:123], v[218:221], v[62:65], v[66:69]
	v_mfma_f32_16x16x32_bf16 v[68:71], v[226:229], v[250:253], v[28:31]
	s_barrier
	s_add_u32 s0, s4, 0x18000
	s_addc_u32 s1, s5, 0
	s_add_i32 s12, s12, s17
	v_lshl_add_u64 v[18:19], s[0:1], 0, v[134:135]
	s_mov_b32 m0, s12
	ds_read_b128 v[36:39], v163 offset:49152
	ds_read_b128 v[40:43], v163 offset:50176
	ds_read_b128 v[230:233], v163 offset:51200
	ds_read_b128 v[234:237], v163 offset:52224
	ds_read_b128 v[238:241], v163 offset:53248
	ds_read_b128 v[242:245], v163 offset:54272
	ds_read_b128 v[246:249], v163 offset:55296
	ds_read_b128 v[250:253], v163 offset:56320
	global_load_lds_dwordx4 v[18:19], off
	s_add_i32 m0, s12, 0x2000
	v_lshl_add_u64 v[18:19], s[0:1], 0, v[138:139]
	s_add_u32 s0, s4, 0x1c000
	s_addc_u32 s1, s5, 0
	s_add_i32 s12, s13, s17
	global_load_lds_dwordx4 v[18:19], off
	s_mov_b32 m0, s12
	v_lshl_add_u64 v[18:19], s[0:1], 0, v[134:135]
	global_load_lds_dwordx4 v[18:19], off
	s_add_i32 m0, s12, 0x2000
	v_lshl_add_u64 v[18:19], s[0:1], 0, v[138:139]
	global_load_lds_dwordx4 v[18:19], off
	s_mov_b32 m0, s51
	v_lshl_add_u64 v[18:19], v[156:157], 0, s[38:39]
	global_load_lds_dwordx4 v[18:19], off
	s_mov_b32 m0, s56
	v_lshl_add_u64 v[18:19], v[144:145], 0, s[38:39]
	global_load_lds_dwordx4 v[18:19], off
	s_waitcnt vmcnt(8) lgkmcnt(0)
	s_barrier
	v_mfma_f32_16x16x32_bf16 v[28:31], v[10:13], v[36:39], v[148:151]
	v_mfma_f32_16x16x32_bf16 v[64:67], v[14:17], v[40:43], v[28:31]
	v_mfma_f32_16x16x32_bf16 v[28:31], v[20:23], v[36:39], v[152:155]
	v_mfma_f32_16x16x32_bf16 v[60:63], v[24:27], v[40:43], v[28:31]
	v_mfma_f32_16x16x32_bf16 v[28:31], v[10:13], v[230:233], v[166:169]
	v_mfma_f32_16x16x32_bf16 v[48:51], v[14:17], v[234:237], v[28:31]
	v_mfma_f32_16x16x32_bf16 v[28:31], v[20:23], v[230:233], v[170:173]
	v_mfma_f32_16x16x32_bf16 v[44:47], v[24:27], v[234:237], v[28:31]
	v_mfma_f32_16x16x32_bf16 v[28:31], v[10:13], v[238:241], v[174:177]
	v_mfma_f32_16x16x32_bf16 v[2:5], v[10:13], v[246:249], v[2:5]
	v_mfma_f32_16x16x32_bf16 v[32:35], v[14:17], v[242:245], v[28:31]
	v_mfma_f32_16x16x32_bf16 v[28:31], v[20:23], v[238:241], v[178:181]
	v_mfma_f32_16x16x32_bf16 v[16:19], v[14:17], v[250:253], v[2:5]
	v_mfma_f32_16x16x32_bf16 v[2:5], v[20:23], v[246:249], v[6:9]
	v_mfma_f32_16x16x32_bf16 v[28:31], v[24:27], v[242:245], v[28:31]
	v_mfma_f32_16x16x32_bf16 v[12:15], v[24:27], v[250:253], v[2:5]
	v_mfma_f32_16x16x32_bf16 v[2:5], v[214:217], v[36:39], v[182:185]
	v_mfma_f32_16x16x32_bf16 v[56:59], v[218:221], v[40:43], v[2:5]
	v_mfma_f32_16x16x32_bf16 v[2:5], v[222:225], v[36:39], v[186:189]
	v_mfma_f32_16x16x32_bf16 v[52:55], v[226:229], v[40:43], v[2:5]
	v_mfma_f32_16x16x32_bf16 v[2:5], v[214:217], v[230:233], v[190:193]
	v_mfma_f32_16x16x32_bf16 v[40:43], v[218:221], v[234:237], v[2:5]
	v_mfma_f32_16x16x32_bf16 v[2:5], v[222:225], v[230:233], v[194:197]
	v_mfma_f32_16x16x32_bf16 v[36:39], v[226:229], v[234:237], v[2:5]
	v_mfma_f32_16x16x32_bf16 v[2:5], v[214:217], v[238:241], v[198:201]
	v_mfma_f32_16x16x32_bf16 v[24:27], v[218:221], v[242:245], v[2:5]
	v_mfma_f32_16x16x32_bf16 v[2:5], v[222:225], v[238:241], v[202:205]
	v_mfma_f32_16x16x32_bf16 v[20:23], v[226:229], v[242:245], v[2:5]
	v_mfma_f32_16x16x32_bf16 v[2:5], v[214:217], v[246:249], v[206:209]
	v_mfma_f32_16x16x32_bf16 v[8:11], v[218:221], v[250:253], v[2:5]
	v_mfma_f32_16x16x32_bf16 v[2:5], v[222:225], v[246:249], v[210:213]
	v_mfma_f32_16x16x32_bf16 v[4:7], v[226:229], v[250:253], v[2:5]
	s_barrier
	s_mov_b32 s22, 2
	s_branch .LBB0_199

.LBB0_200:
	ds_read_b128 v[150:153], v161
	ds_read_b128 v[154:157], v161 offset:1024
	ds_read_b128 v[166:169], v161 offset:2048
	ds_read_b128 v[170:173], v161 offset:3072
	ds_read_b128 v[174:177], v162
	ds_read_b128 v[178:181], v162 offset:1024
	ds_read_b128 v[182:185], v162 offset:2048
	ds_read_b128 v[186:189], v162 offset:3072
	s_add_u32 s8, s55, s26
	s_addc_u32 s9, s63, 0
	s_cmp_eq_u32 s26, s4
	s_cselect_b32 s23, s0, s9
	s_cselect_b32 s22, s1, s8
	s_cselect_b32 s9, s41, s54
	s_cselect_b32 s8, s43, s53
	s_add_i32 s65, s18, 0xc000
	v_lshl_add_u64 v[144:145], v[2:3], 0, s[26:27]
	s_mov_b32 m0, s65
	s_add_i32 s64, s18, 0xe000
	ds_read_b128 v[190:193], v163
	ds_read_b128 v[194:197], v163 offset:1024
	ds_read_b128 v[198:201], v163 offset:2048
	ds_read_b128 v[202:205], v163 offset:3072
	ds_read_b128 v[206:209], v163 offset:4096
	ds_read_b128 v[210:213], v163 offset:5120
	ds_read_b128 v[214:217], v163 offset:6144
	ds_read_b128 v[218:221], v163 offset:7168
	global_load_lds_dwordx4 v[144:145], off
	s_mov_b32 m0, s64
	v_lshl_add_u64 v[144:145], v[148:149], 0, s[26:27]
	global_load_lds_dwordx4 v[144:145], off
	s_waitcnt vmcnt(8) lgkmcnt(0)
	s_barrier
	v_mfma_f32_16x16x32_bf16 v[128:131], v[150:153], v[190:193], v[128:131]
	v_mfma_f32_16x16x32_bf16 v[128:131], v[154:157], v[194:197], v[128:131]
	v_mfma_f32_16x16x32_bf16 v[124:127], v[166:169], v[190:193], v[124:127]
	v_mfma_f32_16x16x32_bf16 v[124:127], v[170:173], v[194:197], v[124:127]
	v_mfma_f32_16x16x32_bf16 v[108:111], v[166:169], v[198:201], v[108:111]
	v_mfma_f32_16x16x32_bf16 v[108:111], v[170:173], v[202:205], v[108:111]
	v_mfma_f32_16x16x32_bf16 v[112:115], v[150:153], v[198:201], v[112:115]
	v_mfma_f32_16x16x32_bf16 v[112:115], v[154:157], v[202:205], v[112:115]
	v_mfma_f32_16x16x32_bf16 v[96:99], v[150:153], v[206:209], v[96:99]
	v_mfma_f32_16x16x32_bf16 v[96:99], v[154:157], v[210:213], v[96:99]
	v_mfma_f32_16x16x32_bf16 v[92:95], v[166:169], v[206:209], v[92:95]
	v_mfma_f32_16x16x32_bf16 v[92:95], v[170:173], v[210:213], v[92:95]
	v_mfma_f32_16x16x32_bf16 v[76:79], v[166:169], v[214:217], v[76:79]
	v_mfma_f32_16x16x32_bf16 v[76:79], v[170:173], v[218:221], v[76:79]
	v_mfma_f32_16x16x32_bf16 v[80:83], v[150:153], v[214:217], v[80:83]
	v_mfma_f32_16x16x32_bf16 v[80:83], v[154:157], v[218:221], v[80:83]
	v_mfma_f32_16x16x32_bf16 v[72:75], v[174:177], v[214:217], v[72:75]
	v_mfma_f32_16x16x32_bf16 v[72:75], v[178:181], v[218:221], v[72:75]
	v_mfma_f32_16x16x32_bf16 v[68:71], v[182:185], v[214:217], v[68:71]
	v_mfma_f32_16x16x32_bf16 v[68:71], v[186:189], v[218:221], v[68:71]
	v_mfma_f32_16x16x32_bf16 v[84:87], v[182:185], v[206:209], v[84:87]
	v_mfma_f32_16x16x32_bf16 v[84:87], v[186:189], v[210:213], v[84:87]
	v_mfma_f32_16x16x32_bf16 v[88:91], v[174:177], v[206:209], v[88:91]
	v_mfma_f32_16x16x32_bf16 v[88:91], v[178:181], v[210:213], v[88:91]
	v_mfma_f32_16x16x32_bf16 v[104:107], v[174:177], v[198:201], v[104:107]
	v_mfma_f32_16x16x32_bf16 v[104:107], v[178:181], v[202:205], v[104:107]
	v_mfma_f32_16x16x32_bf16 v[100:103], v[182:185], v[198:201], v[100:103]
	v_mfma_f32_16x16x32_bf16 v[100:103], v[186:189], v[202:205], v[100:103]
	v_mfma_f32_16x16x32_bf16 v[116:119], v[182:185], v[190:193], v[116:119]
	v_mfma_f32_16x16x32_bf16 v[116:119], v[186:189], v[194:197], v[116:119]
	v_mfma_f32_16x16x32_bf16 v[120:123], v[174:177], v[190:193], v[120:123]
	v_mfma_f32_16x16x32_bf16 v[120:123], v[178:181], v[194:197], v[120:123]
	s_barrier
	s_add_i32 s12, s60, s17
	v_lshl_add_u64 v[144:145], s[8:9], 0, v[134:135]
	s_mov_b32 m0, s12
	ds_read_b128 v[190:193], v163 offset:16384
	ds_read_b128 v[194:197], v163 offset:17408
	ds_read_b128 v[198:201], v163 offset:18432
	ds_read_b128 v[202:205], v163 offset:19456
	ds_read_b128 v[206:209], v163 offset:20480
	ds_read_b128 v[210:213], v163 offset:21504
	ds_read_b128 v[214:217], v163 offset:22528
	ds_read_b128 v[218:221], v163 offset:23552
	global_load_lds_dwordx4 v[144:145], off
	s_add_i32 m0, s12, 0x2000
	s_add_u32 s12, s8, 0x4000
	v_lshl_add_u64 v[144:145], s[8:9], 0, v[138:139]
	s_addc_u32 s13, s9, 0
	s_add_i32 s14, s61, s17
	global_load_lds_dwordx4 v[144:145], off
	v_lshl_add_u64 v[144:145], s[12:13], 0, v[134:135]
	s_mov_b32 m0, s14
	v_lshl_add_u64 v[222:223], s[22:23], 0, v[136:137]
	global_load_lds_dwordx4 v[144:145], off
	s_add_i32 m0, s14, 0x2000
	v_lshl_add_u64 v[144:145], s[12:13], 0, v[138:139]
	global_load_lds_dwordx4 v[144:145], off
	s_mov_b32 m0, s18
	v_lshl_add_u64 v[144:145], s[22:23], 0, v[132:133]
	global_load_lds_dwordx4 v[144:145], off
	s_mov_b32 m0, s19
	s_nop 0
	global_load_lds_dwordx4 v[222:223], off
	s_waitcnt vmcnt(8) lgkmcnt(0)
	s_barrier
	v_mfma_f32_16x16x32_bf16 v[64:67], v[150:153], v[190:193], v[64:67]
	v_mfma_f32_16x16x32_bf16 v[64:67], v[154:157], v[194:197], v[64:67]
	v_mfma_f32_16x16x32_bf16 v[60:63], v[166:169], v[190:193], v[60:63]
	v_mfma_f32_16x16x32_bf16 v[60:63], v[170:173], v[194:197], v[60:63]
	v_mfma_f32_16x16x32_bf16 v[44:47], v[166:169], v[198:201], v[44:47]
	v_mfma_f32_16x16x32_bf16 v[44:47], v[170:173], v[202:205], v[44:47]
	v_mfma_f32_16x16x32_bf16 v[48:51], v[150:153], v[198:201], v[48:51]
	v_mfma_f32_16x16x32_bf16 v[48:51], v[154:157], v[202:205], v[48:51]
	v_mfma_f32_16x16x32_bf16 v[32:35], v[150:153], v[206:209], v[32:35]
	v_mfma_f32_16x16x32_bf16 v[32:35], v[154:157], v[210:213], v[32:35]
	v_mfma_f32_16x16x32_bf16 v[28:31], v[166:169], v[206:209], v[28:31]
	v_mfma_f32_16x16x32_bf16 v[28:31], v[170:173], v[210:213], v[28:31]
	v_mfma_f32_16x16x32_bf16 v[12:15], v[166:169], v[214:217], v[12:15]
	v_mfma_f32_16x16x32_bf16 v[12:15], v[170:173], v[218:221], v[12:15]
	v_mfma_f32_16x16x32_bf16 v[16:19], v[150:153], v[214:217], v[16:19]
	v_mfma_f32_16x16x32_bf16 v[16:19], v[154:157], v[218:221], v[16:19]
	v_mfma_f32_16x16x32_bf16 v[8:11], v[174:177], v[214:217], v[8:11]
	v_mfma_f32_16x16x32_bf16 v[8:11], v[178:181], v[218:221], v[8:11]
	v_mfma_f32_16x16x32_bf16 v[4:7], v[182:185], v[214:217], v[4:7]
	v_mfma_f32_16x16x32_bf16 v[4:7], v[186:189], v[218:221], v[4:7]
	v_mfma_f32_16x16x32_bf16 v[20:23], v[182:185], v[206:209], v[20:23]
	v_mfma_f32_16x16x32_bf16 v[20:23], v[186:189], v[210:213], v[20:23]
	v_mfma_f32_16x16x32_bf16 v[24:27], v[174:177], v[206:209], v[24:27]
	v_mfma_f32_16x16x32_bf16 v[24:27], v[178:181], v[210:213], v[24:27]
	v_mfma_f32_16x16x32_bf16 v[40:43], v[174:177], v[198:201], v[40:43]
	v_mfma_f32_16x16x32_bf16 v[40:43], v[178:181], v[202:205], v[40:43]
	v_mfma_f32_16x16x32_bf16 v[36:39], v[182:185], v[198:201], v[36:39]
	v_mfma_f32_16x16x32_bf16 v[36:39], v[186:189], v[202:205], v[36:39]
	v_mfma_f32_16x16x32_bf16 v[52:55], v[182:185], v[190:193], v[52:55]
	v_mfma_f32_16x16x32_bf16 v[52:55], v[186:189], v[194:197], v[52:55]
	v_mfma_f32_16x16x32_bf16 v[56:59], v[174:177], v[190:193], v[56:59]
	v_mfma_f32_16x16x32_bf16 v[56:59], v[178:181], v[194:197], v[56:59]
	s_barrier
	s_add_i32 s14, 0, 0x18000
	v_add_u32_e32 v1, s14, v160
	s_add_i32 s66, 0, 0x1c000
	ds_read_b128 v[150:153], v1
	ds_read_b128 v[154:157], v1 offset:1024
	ds_read_b128 v[166:169], v1 offset:2048
	ds_read_b128 v[170:173], v1 offset:3072
	v_add_u32_e32 v1, s66, v160
	ds_read_b128 v[174:177], v1
	ds_read_b128 v[178:181], v1 offset:1024
	ds_read_b128 v[182:185], v1 offset:2048
	ds_read_b128 v[186:189], v1 offset:3072
	s_add_u32 s12, s22, 0x100000
	s_addc_u32 s13, s23, 0
	s_mov_b32 m0, s20
	v_lshl_add_u64 v[224:225], s[12:13], 0, v[132:133]
	ds_read_b128 v[190:193], v163 offset:32768
	ds_read_b128 v[194:197], v163 offset:33792
	ds_read_b128 v[198:201], v163 offset:34816
	ds_read_b128 v[202:205], v163 offset:35840
	ds_read_b128 v[206:209], v163 offset:36864
	ds_read_b128 v[210:213], v163 offset:37888
	ds_read_b128 v[214:217], v163 offset:38912
	ds_read_b128 v[218:221], v163 offset:39936
	global_load_lds_dwordx4 v[224:225], off
	s_mov_b32 m0, s21
	v_lshl_add_u64 v[224:225], s[12:13], 0, v[136:137]
	global_load_lds_dwordx4 v[224:225], off
	s_waitcnt vmcnt(8) lgkmcnt(0)
	s_barrier
	v_mfma_f32_16x16x32_bf16 v[128:131], v[150:153], v[190:193], v[128:131]
	v_mfma_f32_16x16x32_bf16 v[128:131], v[154:157], v[194:197], v[128:131]
	v_mfma_f32_16x16x32_bf16 v[124:127], v[166:169], v[190:193], v[124:127]
	v_mfma_f32_16x16x32_bf16 v[124:127], v[170:173], v[194:197], v[124:127]
	v_mfma_f32_16x16x32_bf16 v[108:111], v[166:169], v[198:201], v[108:111]
	v_mfma_f32_16x16x32_bf16 v[108:111], v[170:173], v[202:205], v[108:111]
	v_mfma_f32_16x16x32_bf16 v[112:115], v[150:153], v[198:201], v[112:115]
	v_mfma_f32_16x16x32_bf16 v[112:115], v[154:157], v[202:205], v[112:115]
	v_mfma_f32_16x16x32_bf16 v[96:99], v[150:153], v[206:209], v[96:99]
	v_mfma_f32_16x16x32_bf16 v[96:99], v[154:157], v[210:213], v[96:99]
	v_mfma_f32_16x16x32_bf16 v[92:95], v[166:169], v[206:209], v[92:95]
	v_mfma_f32_16x16x32_bf16 v[92:95], v[170:173], v[210:213], v[92:95]
	v_mfma_f32_16x16x32_bf16 v[76:79], v[166:169], v[214:217], v[76:79]
	v_mfma_f32_16x16x32_bf16 v[76:79], v[170:173], v[218:221], v[76:79]
	v_mfma_f32_16x16x32_bf16 v[80:83], v[150:153], v[214:217], v[80:83]
	v_mfma_f32_16x16x32_bf16 v[80:83], v[154:157], v[218:221], v[80:83]
	v_mfma_f32_16x16x32_bf16 v[72:75], v[174:177], v[214:217], v[72:75]
	v_mfma_f32_16x16x32_bf16 v[72:75], v[178:181], v[218:221], v[72:75]
	v_mfma_f32_16x16x32_bf16 v[68:71], v[182:185], v[214:217], v[68:71]
	v_mfma_f32_16x16x32_bf16 v[68:71], v[186:189], v[218:221], v[68:71]
	v_mfma_f32_16x16x32_bf16 v[84:87], v[182:185], v[206:209], v[84:87]
	v_mfma_f32_16x16x32_bf16 v[84:87], v[186:189], v[210:213], v[84:87]
	v_mfma_f32_16x16x32_bf16 v[88:91], v[174:177], v[206:209], v[88:91]
	v_mfma_f32_16x16x32_bf16 v[88:91], v[178:181], v[210:213], v[88:91]
	v_mfma_f32_16x16x32_bf16 v[104:107], v[174:177], v[198:201], v[104:107]
	v_mfma_f32_16x16x32_bf16 v[104:107], v[178:181], v[202:205], v[104:107]
	v_mfma_f32_16x16x32_bf16 v[100:103], v[182:185], v[198:201], v[100:103]
	v_mfma_f32_16x16x32_bf16 v[100:103], v[186:189], v[202:205], v[100:103]
	v_mfma_f32_16x16x32_bf16 v[116:119], v[182:185], v[190:193], v[116:119]
	v_mfma_f32_16x16x32_bf16 v[116:119], v[186:189], v[194:197], v[116:119]
	v_mfma_f32_16x16x32_bf16 v[120:123], v[174:177], v[190:193], v[120:123]
	v_mfma_f32_16x16x32_bf16 v[120:123], v[178:181], v[194:197], v[120:123]
	s_barrier
	s_add_u32 s12, s8, 0x8000
	s_addc_u32 s13, s9, 0
	s_add_i32 s14, s14, s17
	v_lshl_add_u64 v[224:225], s[12:13], 0, v[134:135]
	s_mov_b32 m0, s14
	ds_read_b128 v[190:193], v163 offset:49152
	ds_read_b128 v[194:197], v163 offset:50176
	ds_read_b128 v[198:201], v163 offset:51200
	ds_read_b128 v[202:205], v163 offset:52224
	ds_read_b128 v[206:209], v163 offset:53248
	ds_read_b128 v[210:213], v163 offset:54272
	ds_read_b128 v[214:217], v163 offset:55296
	ds_read_b128 v[218:221], v163 offset:56320
	global_load_lds_dwordx4 v[224:225], off
	s_add_i32 m0, s14, 0x2000
	s_add_u32 s8, s8, 0xc000
	v_lshl_add_u64 v[224:225], s[12:13], 0, v[138:139]
	s_addc_u32 s9, s9, 0
	s_add_i32 s12, s66, s17
	global_load_lds_dwordx4 v[224:225], off
	v_lshl_add_u64 v[224:225], s[8:9], 0, v[134:135]
	s_mov_b32 m0, s12
	v_lshl_add_u64 v[144:145], v[144:145], 0, s[30:31]
	global_load_lds_dwordx4 v[224:225], off
	s_add_i32 m0, s12, 0x2000
	v_lshl_add_u64 v[224:225], s[8:9], 0, v[138:139]
	global_load_lds_dwordx4 v[224:225], off
	s_mov_b32 m0, s51
	s_nop 0
	global_load_lds_dwordx4 v[144:145], off
	s_mov_b32 m0, s56
	v_lshl_add_u64 v[144:145], v[222:223], 0, s[30:31]
	global_load_lds_dwordx4 v[144:145], off
	s_waitcnt vmcnt(8) lgkmcnt(0)
	s_barrier
	v_mfma_f32_16x16x32_bf16 v[64:67], v[150:153], v[190:193], v[64:67]
	v_mfma_f32_16x16x32_bf16 v[64:67], v[154:157], v[194:197], v[64:67]
	v_mfma_f32_16x16x32_bf16 v[60:63], v[166:169], v[190:193], v[60:63]
	v_mfma_f32_16x16x32_bf16 v[60:63], v[170:173], v[194:197], v[60:63]
	v_mfma_f32_16x16x32_bf16 v[44:47], v[166:169], v[198:201], v[44:47]
	v_mfma_f32_16x16x32_bf16 v[44:47], v[170:173], v[202:205], v[44:47]
	v_mfma_f32_16x16x32_bf16 v[48:51], v[150:153], v[198:201], v[48:51]
	v_mfma_f32_16x16x32_bf16 v[48:51], v[154:157], v[202:205], v[48:51]
	v_mfma_f32_16x16x32_bf16 v[32:35], v[150:153], v[206:209], v[32:35]
	v_mfma_f32_16x16x32_bf16 v[32:35], v[154:157], v[210:213], v[32:35]
	v_mfma_f32_16x16x32_bf16 v[28:31], v[166:169], v[206:209], v[28:31]
	v_mfma_f32_16x16x32_bf16 v[28:31], v[170:173], v[210:213], v[28:31]
	v_mfma_f32_16x16x32_bf16 v[12:15], v[166:169], v[214:217], v[12:15]
	v_mfma_f32_16x16x32_bf16 v[12:15], v[170:173], v[218:221], v[12:15]
	v_mfma_f32_16x16x32_bf16 v[16:19], v[150:153], v[214:217], v[16:19]
	v_mfma_f32_16x16x32_bf16 v[16:19], v[154:157], v[218:221], v[16:19]
	v_mfma_f32_16x16x32_bf16 v[8:11], v[174:177], v[214:217], v[8:11]
	v_mfma_f32_16x16x32_bf16 v[8:11], v[178:181], v[218:221], v[8:11]
	v_mfma_f32_16x16x32_bf16 v[4:7], v[182:185], v[214:217], v[4:7]
	v_mfma_f32_16x16x32_bf16 v[4:7], v[186:189], v[218:221], v[4:7]
	v_mfma_f32_16x16x32_bf16 v[20:23], v[182:185], v[206:209], v[20:23]
	v_mfma_f32_16x16x32_bf16 v[20:23], v[186:189], v[210:213], v[20:23]
	v_mfma_f32_16x16x32_bf16 v[24:27], v[174:177], v[206:209], v[24:27]
	v_mfma_f32_16x16x32_bf16 v[24:27], v[178:181], v[210:213], v[24:27]
	v_mfma_f32_16x16x32_bf16 v[40:43], v[174:177], v[198:201], v[40:43]
	v_mfma_f32_16x16x32_bf16 v[40:43], v[178:181], v[202:205], v[40:43]
	v_mfma_f32_16x16x32_bf16 v[36:39], v[182:185], v[198:201], v[36:39]
	v_mfma_f32_16x16x32_bf16 v[36:39], v[186:189], v[202:205], v[36:39]
	v_mfma_f32_16x16x32_bf16 v[52:55], v[182:185], v[190:193], v[52:55]
	v_mfma_f32_16x16x32_bf16 v[52:55], v[186:189], v[194:197], v[52:55]
	v_mfma_f32_16x16x32_bf16 v[56:59], v[174:177], v[190:193], v[56:59]
	v_mfma_f32_16x16x32_bf16 v[56:59], v[178:181], v[194:197], v[56:59]
	s_barrier
	s_add_i32 s52, s52, 2
	s_add_u32 s53, s53, 0x10000
	s_addc_u32 s54, s54, 0
	s_add_u32 s55, s55, 0x100
	s_addc_u32 s63, s63, 0
	s_add_u32 s4, s4, 0xffffff00
	s_addc_u32 s5, s5, -1
	v_lshl_add_u64 v[2:3], v[2:3], 0, s[36:37]
	s_cmp_gt_u32 s52, 61
	v_lshl_add_u64 v[148:149], v[148:149], 0, s[36:37]
	s_cbranch_scc0 .LBB0_200
	s_and_b64 vcc, exec, s[34:35]
	s_cbranch_vccz .LBB0_203
	s_barrier

.LBB0_506:
	s_cmp_eq_u32 s22, 0
	s_mov_b32 s22, 0
	s_cbranch_scc1 .LBB0_508
	ds_read_b128 v[2:5], v153
	ds_read_b128 v[6:9], v153 offset:1024
	ds_read_b128 v[10:13], v153 offset:2048
	ds_read_b128 v[14:17], v153 offset:3072
	ds_read_b128 v[18:21], v154
	ds_read_b128 v[22:25], v154 offset:1024
	ds_read_b128 v[26:29], v154 offset:2048
	ds_read_b128 v[30:33], v154 offset:3072
	s_add_u32 s0, s8, 0x10000
	s_addc_u32 s1, s9, 0
	ds_read_b128 v[34:37], v155
	ds_read_b128 v[38:41], v155 offset:1024
	ds_read_b128 v[42:45], v155 offset:2048
	ds_read_b128 v[46:49], v155 offset:3072
	ds_read_b128 v[50:53], v155 offset:4096
	ds_read_b128 v[54:57], v155 offset:5120
	ds_read_b128 v[58:61], v155 offset:6144
	ds_read_b128 v[62:65], v155 offset:7168
	s_waitcnt vmcnt(24) lgkmcnt(0)
	s_barrier
	v_mfma_f32_16x16x32_bf16 v[66:69], v[2:5], v[34:37], 0
	v_mfma_f32_16x16x32_bf16 v[70:73], v[10:13], v[34:37], 0
	v_mfma_f32_16x16x32_bf16 v[74:77], v[2:5], v[42:45], 0
	v_mfma_f32_16x16x32_bf16 v[78:81], v[10:13], v[42:45], 0
	v_mfma_f32_16x16x32_bf16 v[82:85], v[2:5], v[50:53], 0
	v_mfma_f32_16x16x32_bf16 v[86:89], v[10:13], v[50:53], 0
	v_mfma_f32_16x16x32_bf16 v[90:93], v[2:5], v[58:61], 0
	v_mfma_f32_16x16x32_bf16 v[94:97], v[10:13], v[58:61], 0
	v_mfma_f32_16x16x32_bf16 v[66:69], v[6:9], v[38:41], v[66:69]
	v_mfma_f32_16x16x32_bf16 v[70:73], v[14:17], v[38:41], v[70:73]
	v_mfma_f32_16x16x32_bf16 v[74:77], v[6:9], v[46:49], v[74:77]
	v_mfma_f32_16x16x32_bf16 v[78:81], v[14:17], v[46:49], v[78:81]
	v_mfma_f32_16x16x32_bf16 v[82:85], v[6:9], v[54:57], v[82:85]
	v_mfma_f32_16x16x32_bf16 v[86:89], v[14:17], v[54:57], v[86:89]
	v_mfma_f32_16x16x32_bf16 v[90:93], v[6:9], v[62:65], v[90:93]
	v_mfma_f32_16x16x32_bf16 v[104:107], v[14:17], v[62:65], v[94:97]
	v_mfma_f32_16x16x32_bf16 v[94:97], v[18:21], v[34:37], 0
	v_mfma_f32_16x16x32_bf16 v[34:37], v[26:29], v[34:37], 0
	v_mfma_f32_16x16x32_bf16 v[108:111], v[22:25], v[38:41], v[94:97]
	v_mfma_f32_16x16x32_bf16 v[34:37], v[30:33], v[38:41], v[34:37]
	v_mfma_f32_16x16x32_bf16 v[38:41], v[18:21], v[42:45], 0
	v_mfma_f32_16x16x32_bf16 v[42:45], v[26:29], v[42:45], 0
	v_mfma_f32_16x16x32_bf16 v[38:41], v[22:25], v[46:49], v[38:41]
	v_mfma_f32_16x16x32_bf16 v[42:45], v[30:33], v[46:49], v[42:45]
	v_mfma_f32_16x16x32_bf16 v[46:49], v[18:21], v[50:53], 0
	v_mfma_f32_16x16x32_bf16 v[50:53], v[26:29], v[50:53], 0
	v_mfma_f32_16x16x32_bf16 v[46:49], v[22:25], v[54:57], v[46:49]
	v_mfma_f32_16x16x32_bf16 v[50:53], v[30:33], v[54:57], v[50:53]
	v_mfma_f32_16x16x32_bf16 v[54:57], v[18:21], v[58:61], 0
	v_mfma_f32_16x16x32_bf16 v[58:61], v[26:29], v[58:61], 0
	v_mfma_f32_16x16x32_bf16 v[54:57], v[22:25], v[62:65], v[54:57]
	v_mfma_f32_16x16x32_bf16 v[58:61], v[30:33], v[62:65], v[58:61]
	s_barrier
	s_add_i32 s12, s58, s17
	v_lshl_add_u64 v[102:103], s[0:1], 0, v[134:135]
	s_mov_b32 m0, s12
	ds_read_b128 v[62:65], v155 offset:16384
	ds_read_b128 v[94:97], v155 offset:17408
	ds_read_b128 v[98:101], v155 offset:18432
	ds_read_b128 v[112:115], v155 offset:19456
	ds_read_b128 v[116:119], v155 offset:20480
	ds_read_b128 v[120:123], v155 offset:21504
	ds_read_b128 v[124:127], v155 offset:22528
	ds_read_b128 v[128:131], v155 offset:23552
	global_load_lds_dwordx4 v[102:103], off
	s_add_i32 m0, s12, 0x2000
	v_lshl_add_u64 v[102:103], s[0:1], 0, v[138:139]
	s_add_u32 s0, s8, 0x14000
	s_addc_u32 s1, s9, 0
	s_add_i32 s12, s59, s17
	global_load_lds_dwordx4 v[102:103], off
	v_lshl_add_u64 v[102:103], s[0:1], 0, v[134:135]
	s_mov_b32 m0, s12
	v_lshl_add_u64 v[148:149], s[56:57], 0, v[132:133]
	global_load_lds_dwordx4 v[102:103], off
	v_lshl_add_u64 v[102:103], s[0:1], 0, v[138:139]
	s_add_i32 m0, s12, 0x2000
	v_lshl_add_u64 v[144:145], s[56:57], 0, v[136:137]
	global_load_lds_dwordx4 v[102:103], off
	s_mov_b32 m0, s18
	v_lshl_add_u64 v[102:103], v[148:149], 0, s[40:41]
	global_load_lds_dwordx4 v[102:103], off
	s_mov_b32 m0, s19
	v_lshl_add_u64 v[102:103], v[144:145], 0, s[40:41]
	global_load_lds_dwordx4 v[102:103], off
	s_waitcnt vmcnt(24) lgkmcnt(0)
	s_barrier
	v_mfma_f32_16x16x32_bf16 v[158:161], v[2:5], v[62:65], 0
	v_mfma_f32_16x16x32_bf16 v[166:169], v[2:5], v[98:101], 0
	v_mfma_f32_16x16x32_bf16 v[174:177], v[2:5], v[116:119], 0
	v_mfma_f32_16x16x32_bf16 v[2:5], v[2:5], v[124:127], 0
	v_mfma_f32_16x16x32_bf16 v[158:161], v[6:9], v[94:97], v[158:161]
	v_mfma_f32_16x16x32_bf16 v[166:169], v[6:9], v[112:115], v[166:169]
	v_mfma_f32_16x16x32_bf16 v[174:177], v[6:9], v[120:123], v[174:177]
	v_mfma_f32_16x16x32_bf16 v[2:5], v[6:9], v[128:131], v[2:5]
	v_mfma_f32_16x16x32_bf16 v[6:9], v[10:13], v[124:127], 0
	v_mfma_f32_16x16x32_bf16 v[162:165], v[10:13], v[62:65], 0
	v_mfma_f32_16x16x32_bf16 v[170:173], v[10:13], v[98:101], 0
	v_mfma_f32_16x16x32_bf16 v[178:181], v[10:13], v[116:119], 0
	v_mfma_f32_16x16x32_bf16 v[6:9], v[14:17], v[128:131], v[6:9]
	v_mfma_f32_16x16x32_bf16 v[162:165], v[14:17], v[94:97], v[162:165]
	v_mfma_f32_16x16x32_bf16 v[170:173], v[14:17], v[112:115], v[170:173]
	v_mfma_f32_16x16x32_bf16 v[178:181], v[14:17], v[120:123], v[178:181]
	v_mfma_f32_16x16x32_bf16 v[14:17], v[26:29], v[62:65], 0
	v_mfma_f32_16x16x32_bf16 v[182:185], v[30:33], v[94:97], v[14:17]
	v_mfma_f32_16x16x32_bf16 v[14:17], v[18:21], v[98:101], 0
	v_mfma_f32_16x16x32_bf16 v[186:189], v[22:25], v[112:115], v[14:17]
	v_mfma_f32_16x16x32_bf16 v[14:17], v[26:29], v[98:101], 0
	v_mfma_f32_16x16x32_bf16 v[190:193], v[30:33], v[112:115], v[14:17]
	v_mfma_f32_16x16x32_bf16 v[14:17], v[18:21], v[116:119], 0
	v_mfma_f32_16x16x32_bf16 v[194:197], v[22:25], v[120:123], v[14:17]
	v_mfma_f32_16x16x32_bf16 v[14:17], v[26:29], v[116:119], 0
	v_mfma_f32_16x16x32_bf16 v[10:13], v[18:21], v[62:65], 0
	v_mfma_f32_16x16x32_bf16 v[198:201], v[30:33], v[120:123], v[14:17]
	v_mfma_f32_16x16x32_bf16 v[14:17], v[18:21], v[124:127], 0
	v_mfma_f32_16x16x32_bf16 v[10:13], v[22:25], v[94:97], v[10:13]
	v_mfma_f32_16x16x32_bf16 v[202:205], v[22:25], v[128:131], v[14:17]
	v_mfma_f32_16x16x32_bf16 v[14:17], v[26:29], v[124:127], 0
	v_mfma_f32_16x16x32_bf16 v[206:209], v[30:33], v[128:131], v[14:17]
	s_barrier
	s_add_i32 s12, 0, 0x18000
	v_add_u32_e32 v1, s12, v151
	s_add_i32 s13, 0, 0x1c000
	s_nop 1
	ds_read_b128 v[14:17], v1
	ds_read_b128 v[24:27], v1 offset:1024
	ds_read_b128 v[28:31], v1 offset:2048
	ds_read_b128 v[210:213], v1 offset:3072
	v_add_u32_e32 v1, s13, v151
	ds_read_b128 v[214:217], v1
	ds_read_b128 v[218:221], v1 offset:1024
	ds_read_b128 v[222:225], v1 offset:2048
	ds_read_b128 v[226:229], v1 offset:3072
	s_add_u32 s0, s56, 0x100100
	s_addc_u32 s1, s57, 0
	s_mov_b32 m0, s20
	v_lshl_add_u64 v[22:23], s[0:1], 0, v[132:133]
	ds_read_b128 v[18:21], v155 offset:32768
	ds_read_b128 v[120:123], v155 offset:33792
	ds_read_b128 v[230:233], v155 offset:34816
	ds_read_b128 v[234:237], v155 offset:35840
	ds_read_b128 v[238:241], v155 offset:36864
	ds_read_b128 v[242:245], v155 offset:37888
	ds_read_b128 v[246:249], v155 offset:38912
	ds_read_b128 v[250:253], v155 offset:39936
	global_load_lds_dwordx4 v[22:23], off
	s_mov_b32 m0, s21
	v_lshl_add_u64 v[22:23], s[0:1], 0, v[136:137]
	global_load_lds_dwordx4 v[22:23], off
	s_waitcnt vmcnt(24) lgkmcnt(0)
	s_barrier
	v_mfma_f32_16x16x32_bf16 v[62:65], v[14:17], v[18:21], v[66:69]
	v_mfma_f32_16x16x32_bf16 v[128:131], v[24:27], v[120:123], v[62:65]
	v_mfma_f32_16x16x32_bf16 v[62:65], v[28:31], v[18:21], v[70:73]
	v_mfma_f32_16x16x32_bf16 v[116:119], v[210:213], v[120:123], v[62:65]
	v_mfma_f32_16x16x32_bf16 v[62:65], v[14:17], v[230:233], v[74:77]
	v_mfma_f32_16x16x32_bf16 v[112:115], v[24:27], v[234:237], v[62:65]
	v_mfma_f32_16x16x32_bf16 v[62:65], v[28:31], v[230:233], v[78:81]
	v_mfma_f32_16x16x32_bf16 v[100:103], v[210:213], v[234:237], v[62:65]
	v_mfma_f32_16x16x32_bf16 v[62:65], v[14:17], v[238:241], v[82:85]
	v_mfma_f32_16x16x32_bf16 v[96:99], v[24:27], v[242:245], v[62:65]
	v_mfma_f32_16x16x32_bf16 v[62:65], v[28:31], v[238:241], v[86:89]
	v_mfma_f32_16x16x32_bf16 v[84:87], v[210:213], v[242:245], v[62:65]
	v_mfma_f32_16x16x32_bf16 v[62:65], v[14:17], v[246:249], v[90:93]
	v_mfma_f32_16x16x32_bf16 v[80:83], v[24:27], v[250:253], v[62:65]
	v_mfma_f32_16x16x32_bf16 v[62:65], v[28:31], v[246:249], v[104:107]
	v_mfma_f32_16x16x32_bf16 v[64:67], v[210:213], v[250:253], v[62:65]
	v_mfma_f32_16x16x32_bf16 v[68:71], v[214:217], v[18:21], v[108:111]
	v_mfma_f32_16x16x32_bf16 v[18:21], v[222:225], v[18:21], v[34:37]
	v_mfma_f32_16x16x32_bf16 v[124:127], v[218:221], v[120:123], v[68:71]
	v_mfma_f32_16x16x32_bf16 v[120:123], v[226:229], v[120:123], v[18:21]
	v_mfma_f32_16x16x32_bf16 v[18:21], v[214:217], v[230:233], v[38:41]
	v_mfma_f32_16x16x32_bf16 v[108:111], v[218:221], v[234:237], v[18:21]
	v_mfma_f32_16x16x32_bf16 v[18:21], v[222:225], v[230:233], v[42:45]
	v_mfma_f32_16x16x32_bf16 v[104:107], v[226:229], v[234:237], v[18:21]
	v_mfma_f32_16x16x32_bf16 v[18:21], v[214:217], v[238:241], v[46:49]
	v_mfma_f32_16x16x32_bf16 v[92:95], v[218:221], v[242:245], v[18:21]
	v_mfma_f32_16x16x32_bf16 v[18:21], v[222:225], v[238:241], v[50:53]
	v_mfma_f32_16x16x32_bf16 v[88:91], v[226:229], v[242:245], v[18:21]
	v_mfma_f32_16x16x32_bf16 v[18:21], v[214:217], v[246:249], v[54:57]
	v_mfma_f32_16x16x32_bf16 v[72:75], v[218:221], v[250:253], v[18:21]
	v_mfma_f32_16x16x32_bf16 v[18:21], v[222:225], v[246:249], v[58:61]
	v_mfma_f32_16x16x32_bf16 v[68:71], v[226:229], v[250:253], v[18:21]
	s_barrier
	s_add_u32 s0, s8, 0x18000
	s_addc_u32 s1, s9, 0
	s_add_i32 s12, s12, s17
	s_nop 1
	v_lshl_add_u64 v[18:19], s[0:1], 0, v[134:135]
	s_mov_b32 m0, s12
	ds_read_b128 v[40:43], v155 offset:49152
	ds_read_b128 v[44:47], v155 offset:50176
	ds_read_b128 v[230:233], v155 offset:51200
	ds_read_b128 v[234:237], v155 offset:52224
	ds_read_b128 v[238:241], v155 offset:53248
	ds_read_b128 v[242:245], v155 offset:54272
	ds_read_b128 v[246:249], v155 offset:55296
	ds_read_b128 v[250:253], v155 offset:56320
	global_load_lds_dwordx4 v[18:19], off
	s_add_i32 m0, s12, 0x2000
	v_lshl_add_u64 v[18:19], s[0:1], 0, v[138:139]
	s_add_u32 s0, s8, 0x1c000
	s_addc_u32 s1, s9, 0
	s_add_i32 s12, s13, s17
	global_load_lds_dwordx4 v[18:19], off
	s_mov_b32 m0, s12
	v_lshl_add_u64 v[18:19], s[0:1], 0, v[134:135]
	global_load_lds_dwordx4 v[18:19], off
	s_add_i32 m0, s12, 0x2000
	v_lshl_add_u64 v[18:19], s[0:1], 0, v[138:139]
	global_load_lds_dwordx4 v[18:19], off
	s_mov_b32 m0, s25
	v_lshl_add_u64 v[18:19], v[148:149], 0, s[42:43]
	global_load_lds_dwordx4 v[18:19], off
	s_mov_b32 m0, s33
	v_lshl_add_u64 v[18:19], v[144:145], 0, s[42:43]
	global_load_lds_dwordx4 v[18:19], off
	s_waitcnt vmcnt(8) lgkmcnt(0)
	s_barrier
	v_mfma_f32_16x16x32_bf16 v[18:21], v[14:17], v[40:43], v[158:161]
	v_mfma_f32_16x16x32_bf16 v[76:79], v[24:27], v[44:47], v[18:21]
	v_mfma_f32_16x16x32_bf16 v[18:21], v[28:31], v[40:43], v[162:165]
	v_mfma_f32_16x16x32_bf16 v[52:55], v[210:213], v[44:47], v[18:21]
	v_mfma_f32_16x16x32_bf16 v[18:21], v[14:17], v[230:233], v[166:169]
	v_mfma_f32_16x16x32_bf16 v[48:51], v[24:27], v[234:237], v[18:21]
	v_mfma_f32_16x16x32_bf16 v[18:21], v[28:31], v[230:233], v[170:173]
	v_mfma_f32_16x16x32_bf16 v[36:39], v[210:213], v[234:237], v[18:21]
	v_mfma_f32_16x16x32_bf16 v[18:21], v[14:17], v[238:241], v[174:177]
	v_mfma_f32_16x16x32_bf16 v[32:35], v[24:27], v[242:245], v[18:21]
	v_mfma_f32_16x16x32_bf16 v[18:21], v[28:31], v[238:241], v[178:181]
	v_mfma_f32_16x16x32_bf16 v[2:5], v[14:17], v[246:249], v[2:5]
	v_mfma_f32_16x16x32_bf16 v[20:23], v[210:213], v[242:245], v[18:21]
	v_mfma_f32_16x16x32_bf16 v[16:19], v[24:27], v[250:253], v[2:5]
	v_mfma_f32_16x16x32_bf16 v[2:5], v[28:31], v[246:249], v[6:9]
	v_mfma_f32_16x16x32_bf16 v[4:7], v[210:213], v[250:253], v[2:5]
	v_mfma_f32_16x16x32_bf16 v[8:11], v[214:217], v[40:43], v[10:13]
	v_mfma_f32_16x16x32_bf16 v[60:63], v[218:221], v[44:47], v[8:11]
	v_mfma_f32_16x16x32_bf16 v[8:11], v[222:225], v[40:43], v[182:185]
	v_mfma_f32_16x16x32_bf16 v[56:59], v[226:229], v[44:47], v[8:11]
	v_mfma_f32_16x16x32_bf16 v[8:11], v[214:217], v[230:233], v[186:189]
	v_mfma_f32_16x16x32_bf16 v[44:47], v[218:221], v[234:237], v[8:11]
	v_mfma_f32_16x16x32_bf16 v[8:11], v[222:225], v[230:233], v[190:193]
	v_mfma_f32_16x16x32_bf16 v[40:43], v[226:229], v[234:237], v[8:11]
	v_mfma_f32_16x16x32_bf16 v[8:11], v[214:217], v[238:241], v[194:197]
	v_mfma_f32_16x16x32_bf16 v[28:31], v[218:221], v[242:245], v[8:11]
	v_mfma_f32_16x16x32_bf16 v[8:11], v[222:225], v[238:241], v[198:201]
	v_mfma_f32_16x16x32_bf16 v[24:27], v[226:229], v[242:245], v[8:11]
	v_mfma_f32_16x16x32_bf16 v[8:11], v[214:217], v[246:249], v[202:205]
	v_mfma_f32_16x16x32_bf16 v[12:15], v[218:221], v[250:253], v[8:11]
	v_mfma_f32_16x16x32_bf16 v[8:11], v[222:225], v[246:249], v[206:209]
	v_mfma_f32_16x16x32_bf16 v[8:11], v[226:229], v[250:253], v[8:11]
	s_barrier
	s_mov_b32 s22, 2
	s_branch .LBB0_509

.LBB0_510:
	ds_read_b128 v[158:161], v153
	ds_read_b128 v[162:165], v153 offset:1024
	ds_read_b128 v[166:169], v153 offset:2048
	ds_read_b128 v[170:173], v153 offset:3072
	ds_read_b128 v[174:177], v154
	ds_read_b128 v[178:181], v154 offset:1024
	ds_read_b128 v[182:185], v154 offset:2048
	ds_read_b128 v[186:189], v154 offset:3072
	s_add_u32 s12, s64, s26
	s_addc_u32 s13, s65, 0
	s_cmp_eq_u32 s26, s8
	s_cselect_b32 s23, s0, s13
	s_cselect_b32 s22, s1, s12
	s_cselect_b32 s57, s45, s63
	s_cselect_b32 s56, s47, s62
	s_add_i32 s67, s18, 0xc000
	v_lshl_add_u64 v[144:145], v[2:3], 0, s[26:27]
	s_mov_b32 m0, s67
	s_add_i32 s66, s18, 0xe000
	ds_read_b128 v[190:193], v155
	ds_read_b128 v[194:197], v155 offset:1024
	ds_read_b128 v[198:201], v155 offset:2048
	ds_read_b128 v[202:205], v155 offset:3072
	ds_read_b128 v[206:209], v155 offset:4096
	ds_read_b128 v[210:213], v155 offset:5120
	ds_read_b128 v[214:217], v155 offset:6144
	ds_read_b128 v[218:221], v155 offset:7168
	global_load_lds_dwordx4 v[144:145], off
	s_mov_b32 m0, s66
	v_lshl_add_u64 v[144:145], v[148:149], 0, s[26:27]
	global_load_lds_dwordx4 v[144:145], off
	s_waitcnt vmcnt(8) lgkmcnt(0)
	s_barrier
	v_mfma_f32_16x16x32_bf16 v[128:131], v[158:161], v[190:193], v[128:131]
	v_mfma_f32_16x16x32_bf16 v[128:131], v[162:165], v[194:197], v[128:131]
	v_mfma_f32_16x16x32_bf16 v[116:119], v[166:169], v[190:193], v[116:119]
	v_mfma_f32_16x16x32_bf16 v[116:119], v[170:173], v[194:197], v[116:119]
	v_mfma_f32_16x16x32_bf16 v[100:103], v[166:169], v[198:201], v[100:103]
	v_mfma_f32_16x16x32_bf16 v[100:103], v[170:173], v[202:205], v[100:103]
	v_mfma_f32_16x16x32_bf16 v[112:115], v[158:161], v[198:201], v[112:115]
	v_mfma_f32_16x16x32_bf16 v[112:115], v[162:165], v[202:205], v[112:115]
	v_mfma_f32_16x16x32_bf16 v[96:99], v[158:161], v[206:209], v[96:99]
	v_mfma_f32_16x16x32_bf16 v[96:99], v[162:165], v[210:213], v[96:99]
	v_mfma_f32_16x16x32_bf16 v[84:87], v[166:169], v[206:209], v[84:87]
	v_mfma_f32_16x16x32_bf16 v[84:87], v[170:173], v[210:213], v[84:87]
	v_mfma_f32_16x16x32_bf16 v[64:67], v[166:169], v[214:217], v[64:67]
	v_mfma_f32_16x16x32_bf16 v[64:67], v[170:173], v[218:221], v[64:67]
	v_mfma_f32_16x16x32_bf16 v[80:83], v[158:161], v[214:217], v[80:83]
	v_mfma_f32_16x16x32_bf16 v[80:83], v[162:165], v[218:221], v[80:83]
	v_mfma_f32_16x16x32_bf16 v[72:75], v[174:177], v[214:217], v[72:75]
	v_mfma_f32_16x16x32_bf16 v[72:75], v[178:181], v[218:221], v[72:75]
	v_mfma_f32_16x16x32_bf16 v[68:71], v[182:185], v[214:217], v[68:71]
	v_mfma_f32_16x16x32_bf16 v[68:71], v[186:189], v[218:221], v[68:71]
	v_mfma_f32_16x16x32_bf16 v[88:91], v[182:185], v[206:209], v[88:91]
	v_mfma_f32_16x16x32_bf16 v[88:91], v[186:189], v[210:213], v[88:91]
	v_mfma_f32_16x16x32_bf16 v[92:95], v[174:177], v[206:209], v[92:95]
	v_mfma_f32_16x16x32_bf16 v[92:95], v[178:181], v[210:213], v[92:95]
	v_mfma_f32_16x16x32_bf16 v[108:111], v[174:177], v[198:201], v[108:111]
	v_mfma_f32_16x16x32_bf16 v[108:111], v[178:181], v[202:205], v[108:111]
	v_mfma_f32_16x16x32_bf16 v[104:107], v[182:185], v[198:201], v[104:107]
	v_mfma_f32_16x16x32_bf16 v[104:107], v[186:189], v[202:205], v[104:107]
	v_mfma_f32_16x16x32_bf16 v[120:123], v[182:185], v[190:193], v[120:123]
	v_mfma_f32_16x16x32_bf16 v[120:123], v[186:189], v[194:197], v[120:123]
	v_mfma_f32_16x16x32_bf16 v[124:127], v[174:177], v[190:193], v[124:127]
	v_mfma_f32_16x16x32_bf16 v[124:127], v[178:181], v[194:197], v[124:127]
	s_barrier
	s_add_i32 s12, s58, s17
	v_lshl_add_u64 v[144:145], s[56:57], 0, v[134:135]
	s_mov_b32 m0, s12
	ds_read_b128 v[190:193], v155 offset:16384
	ds_read_b128 v[194:197], v155 offset:17408
	ds_read_b128 v[198:201], v155 offset:18432
	ds_read_b128 v[202:205], v155 offset:19456
	ds_read_b128 v[206:209], v155 offset:20480
	ds_read_b128 v[210:213], v155 offset:21504
	ds_read_b128 v[214:217], v155 offset:22528
	ds_read_b128 v[218:221], v155 offset:23552
	global_load_lds_dwordx4 v[144:145], off
	s_add_i32 m0, s12, 0x2000
	s_add_u32 s12, s56, 0x4000
	v_lshl_add_u64 v[144:145], s[56:57], 0, v[138:139]
	s_addc_u32 s13, s57, 0
	s_add_i32 s14, s59, s17
	global_load_lds_dwordx4 v[144:145], off
	v_lshl_add_u64 v[144:145], s[12:13], 0, v[134:135]
	s_mov_b32 m0, s14
	v_lshl_add_u64 v[222:223], s[22:23], 0, v[136:137]
	global_load_lds_dwordx4 v[144:145], off
	s_add_i32 m0, s14, 0x2000
	v_lshl_add_u64 v[144:145], s[12:13], 0, v[138:139]
	global_load_lds_dwordx4 v[144:145], off
	s_mov_b32 m0, s18
	v_lshl_add_u64 v[144:145], s[22:23], 0, v[132:133]
	global_load_lds_dwordx4 v[144:145], off
	s_mov_b32 m0, s19
	s_nop 0
	global_load_lds_dwordx4 v[222:223], off
	s_waitcnt vmcnt(8) lgkmcnt(0)
	s_barrier
	v_mfma_f32_16x16x32_bf16 v[76:79], v[158:161], v[190:193], v[76:79]
	v_mfma_f32_16x16x32_bf16 v[76:79], v[162:165], v[194:197], v[76:79]
	v_mfma_f32_16x16x32_bf16 v[52:55], v[166:169], v[190:193], v[52:55]
	v_mfma_f32_16x16x32_bf16 v[52:55], v[170:173], v[194:197], v[52:55]
	v_mfma_f32_16x16x32_bf16 v[36:39], v[166:169], v[198:201], v[36:39]
	v_mfma_f32_16x16x32_bf16 v[36:39], v[170:173], v[202:205], v[36:39]
	v_mfma_f32_16x16x32_bf16 v[48:51], v[158:161], v[198:201], v[48:51]
	v_mfma_f32_16x16x32_bf16 v[48:51], v[162:165], v[202:205], v[48:51]
	v_mfma_f32_16x16x32_bf16 v[32:35], v[158:161], v[206:209], v[32:35]
	v_mfma_f32_16x16x32_bf16 v[32:35], v[162:165], v[210:213], v[32:35]
	v_mfma_f32_16x16x32_bf16 v[20:23], v[166:169], v[206:209], v[20:23]
	v_mfma_f32_16x16x32_bf16 v[20:23], v[170:173], v[210:213], v[20:23]
	v_mfma_f32_16x16x32_bf16 v[4:7], v[166:169], v[214:217], v[4:7]
	v_mfma_f32_16x16x32_bf16 v[4:7], v[170:173], v[218:221], v[4:7]
	v_mfma_f32_16x16x32_bf16 v[16:19], v[158:161], v[214:217], v[16:19]
	v_mfma_f32_16x16x32_bf16 v[16:19], v[162:165], v[218:221], v[16:19]
	v_mfma_f32_16x16x32_bf16 v[12:15], v[174:177], v[214:217], v[12:15]
	v_mfma_f32_16x16x32_bf16 v[12:15], v[178:181], v[218:221], v[12:15]
	v_mfma_f32_16x16x32_bf16 v[8:11], v[182:185], v[214:217], v[8:11]
	v_mfma_f32_16x16x32_bf16 v[8:11], v[186:189], v[218:221], v[8:11]
	v_mfma_f32_16x16x32_bf16 v[24:27], v[182:185], v[206:209], v[24:27]
	v_mfma_f32_16x16x32_bf16 v[24:27], v[186:189], v[210:213], v[24:27]
	v_mfma_f32_16x16x32_bf16 v[28:31], v[174:177], v[206:209], v[28:31]
	v_mfma_f32_16x16x32_bf16 v[28:31], v[178:181], v[210:213], v[28:31]
	v_mfma_f32_16x16x32_bf16 v[44:47], v[174:177], v[198:201], v[44:47]
	v_mfma_f32_16x16x32_bf16 v[44:47], v[178:181], v[202:205], v[44:47]
	v_mfma_f32_16x16x32_bf16 v[40:43], v[182:185], v[198:201], v[40:43]
	v_mfma_f32_16x16x32_bf16 v[40:43], v[186:189], v[202:205], v[40:43]
	v_mfma_f32_16x16x32_bf16 v[56:59], v[182:185], v[190:193], v[56:59]
	v_mfma_f32_16x16x32_bf16 v[56:59], v[186:189], v[194:197], v[56:59]
	v_mfma_f32_16x16x32_bf16 v[60:63], v[174:177], v[190:193], v[60:63]
	v_mfma_f32_16x16x32_bf16 v[60:63], v[178:181], v[194:197], v[60:63]
	s_barrier
	s_add_i32 s14, 0, 0x18000
	v_add_u32_e32 v1, s14, v151
	s_add_i32 s68, 0, 0x1c000
	ds_read_b128 v[158:161], v1
	ds_read_b128 v[162:165], v1 offset:1024
	ds_read_b128 v[166:169], v1 offset:2048
	ds_read_b128 v[170:173], v1 offset:3072
	v_add_u32_e32 v1, s68, v151
	ds_read_b128 v[174:177], v1
	ds_read_b128 v[178:181], v1 offset:1024
	ds_read_b128 v[182:185], v1 offset:2048
	ds_read_b128 v[186:189], v1 offset:3072
	s_add_u32 s12, s22, 0x100000
	s_addc_u32 s13, s23, 0
	s_mov_b32 m0, s20
	v_lshl_add_u64 v[224:225], s[12:13], 0, v[132:133]
	ds_read_b128 v[190:193], v155 offset:32768
	ds_read_b128 v[194:197], v155 offset:33792
	ds_read_b128 v[198:201], v155 offset:34816
	ds_read_b128 v[202:205], v155 offset:35840
	ds_read_b128 v[206:209], v155 offset:36864
	ds_read_b128 v[210:213], v155 offset:37888
	ds_read_b128 v[214:217], v155 offset:38912
	ds_read_b128 v[218:221], v155 offset:39936
	global_load_lds_dwordx4 v[224:225], off
	s_mov_b32 m0, s21
	v_lshl_add_u64 v[224:225], s[12:13], 0, v[136:137]
	global_load_lds_dwordx4 v[224:225], off
	s_waitcnt vmcnt(8) lgkmcnt(0)
	s_barrier
	v_mfma_f32_16x16x32_bf16 v[128:131], v[158:161], v[190:193], v[128:131]
	v_mfma_f32_16x16x32_bf16 v[128:131], v[162:165], v[194:197], v[128:131]
	v_mfma_f32_16x16x32_bf16 v[116:119], v[166:169], v[190:193], v[116:119]
	v_mfma_f32_16x16x32_bf16 v[116:119], v[170:173], v[194:197], v[116:119]
	v_mfma_f32_16x16x32_bf16 v[100:103], v[166:169], v[198:201], v[100:103]
	v_mfma_f32_16x16x32_bf16 v[100:103], v[170:173], v[202:205], v[100:103]
	v_mfma_f32_16x16x32_bf16 v[112:115], v[158:161], v[198:201], v[112:115]
	v_mfma_f32_16x16x32_bf16 v[112:115], v[162:165], v[202:205], v[112:115]
	v_mfma_f32_16x16x32_bf16 v[96:99], v[158:161], v[206:209], v[96:99]
	v_mfma_f32_16x16x32_bf16 v[96:99], v[162:165], v[210:213], v[96:99]
	v_mfma_f32_16x16x32_bf16 v[84:87], v[166:169], v[206:209], v[84:87]
	v_mfma_f32_16x16x32_bf16 v[84:87], v[170:173], v[210:213], v[84:87]
	v_mfma_f32_16x16x32_bf16 v[64:67], v[166:169], v[214:217], v[64:67]
	v_mfma_f32_16x16x32_bf16 v[64:67], v[170:173], v[218:221], v[64:67]
	v_mfma_f32_16x16x32_bf16 v[80:83], v[158:161], v[214:217], v[80:83]
	v_mfma_f32_16x16x32_bf16 v[80:83], v[162:165], v[218:221], v[80:83]
	v_mfma_f32_16x16x32_bf16 v[72:75], v[174:177], v[214:217], v[72:75]
	v_mfma_f32_16x16x32_bf16 v[72:75], v[178:181], v[218:221], v[72:75]
	v_mfma_f32_16x16x32_bf16 v[68:71], v[182:185], v[214:217], v[68:71]
	v_mfma_f32_16x16x32_bf16 v[68:71], v[186:189], v[218:221], v[68:71]
	v_mfma_f32_16x16x32_bf16 v[88:91], v[182:185], v[206:209], v[88:91]
	v_mfma_f32_16x16x32_bf16 v[88:91], v[186:189], v[210:213], v[88:91]
	v_mfma_f32_16x16x32_bf16 v[92:95], v[174:177], v[206:209], v[92:95]
	v_mfma_f32_16x16x32_bf16 v[92:95], v[178:181], v[210:213], v[92:95]
	v_mfma_f32_16x16x32_bf16 v[108:111], v[174:177], v[198:201], v[108:111]
	v_mfma_f32_16x16x32_bf16 v[108:111], v[178:181], v[202:205], v[108:111]
	v_mfma_f32_16x16x32_bf16 v[104:107], v[182:185], v[198:201], v[104:107]
	v_mfma_f32_16x16x32_bf16 v[104:107], v[186:189], v[202:205], v[104:107]
	v_mfma_f32_16x16x32_bf16 v[120:123], v[182:185], v[190:193], v[120:123]
	v_mfma_f32_16x16x32_bf16 v[120:123], v[186:189], v[194:197], v[120:123]
	v_mfma_f32_16x16x32_bf16 v[124:127], v[174:177], v[190:193], v[124:127]
	v_mfma_f32_16x16x32_bf16 v[124:127], v[178:181], v[194:197], v[124:127]
	s_barrier
	s_add_u32 s12, s56, 0x8000
	s_addc_u32 s13, s57, 0
	s_add_i32 s14, s14, s17
	v_lshl_add_u64 v[224:225], s[12:13], 0, v[134:135]
	s_mov_b32 m0, s14
	ds_read_b128 v[190:193], v155 offset:49152
	ds_read_b128 v[194:197], v155 offset:50176
	ds_read_b128 v[198:201], v155 offset:51200
	ds_read_b128 v[202:205], v155 offset:52224
	ds_read_b128 v[206:209], v155 offset:53248
	ds_read_b128 v[210:213], v155 offset:54272
	ds_read_b128 v[214:217], v155 offset:55296
	ds_read_b128 v[218:221], v155 offset:56320
	global_load_lds_dwordx4 v[224:225], off
	s_add_i32 m0, s14, 0x2000
	v_lshl_add_u64 v[224:225], s[12:13], 0, v[138:139]
	s_add_u32 s12, s56, 0xc000
	s_addc_u32 s13, s57, 0
	s_add_i32 s14, s68, s17
	global_load_lds_dwordx4 v[224:225], off
	v_lshl_add_u64 v[224:225], s[12:13], 0, v[134:135]
	s_mov_b32 m0, s14
	v_lshl_add_u64 v[144:145], v[144:145], 0, s[36:37]
	global_load_lds_dwordx4 v[224:225], off
	s_add_i32 m0, s14, 0x2000
	v_lshl_add_u64 v[224:225], s[12:13], 0, v[138:139]
	global_load_lds_dwordx4 v[224:225], off
	s_mov_b32 m0, s25
	s_nop 0
	global_load_lds_dwordx4 v[144:145], off
	s_mov_b32 m0, s33
	v_lshl_add_u64 v[144:145], v[222:223], 0, s[36:37]
	global_load_lds_dwordx4 v[144:145], off
	s_waitcnt vmcnt(8) lgkmcnt(0)
	s_barrier
	v_mfma_f32_16x16x32_bf16 v[76:79], v[158:161], v[190:193], v[76:79]
	v_mfma_f32_16x16x32_bf16 v[76:79], v[162:165], v[194:197], v[76:79]
	v_mfma_f32_16x16x32_bf16 v[52:55], v[166:169], v[190:193], v[52:55]
	v_mfma_f32_16x16x32_bf16 v[52:55], v[170:173], v[194:197], v[52:55]
	v_mfma_f32_16x16x32_bf16 v[36:39], v[166:169], v[198:201], v[36:39]
	v_mfma_f32_16x16x32_bf16 v[36:39], v[170:173], v[202:205], v[36:39]
	v_mfma_f32_16x16x32_bf16 v[48:51], v[158:161], v[198:201], v[48:51]
	v_mfma_f32_16x16x32_bf16 v[48:51], v[162:165], v[202:205], v[48:51]
	v_mfma_f32_16x16x32_bf16 v[32:35], v[158:161], v[206:209], v[32:35]
	v_mfma_f32_16x16x32_bf16 v[32:35], v[162:165], v[210:213], v[32:35]
	v_mfma_f32_16x16x32_bf16 v[20:23], v[166:169], v[206:209], v[20:23]
	v_mfma_f32_16x16x32_bf16 v[20:23], v[170:173], v[210:213], v[20:23]
	v_mfma_f32_16x16x32_bf16 v[4:7], v[166:169], v[214:217], v[4:7]
	v_mfma_f32_16x16x32_bf16 v[4:7], v[170:173], v[218:221], v[4:7]
	v_mfma_f32_16x16x32_bf16 v[16:19], v[158:161], v[214:217], v[16:19]
	v_mfma_f32_16x16x32_bf16 v[16:19], v[162:165], v[218:221], v[16:19]
	v_mfma_f32_16x16x32_bf16 v[12:15], v[174:177], v[214:217], v[12:15]
	v_mfma_f32_16x16x32_bf16 v[12:15], v[178:181], v[218:221], v[12:15]
	v_mfma_f32_16x16x32_bf16 v[8:11], v[182:185], v[214:217], v[8:11]
	v_mfma_f32_16x16x32_bf16 v[8:11], v[186:189], v[218:221], v[8:11]
	v_mfma_f32_16x16x32_bf16 v[24:27], v[182:185], v[206:209], v[24:27]
	v_mfma_f32_16x16x32_bf16 v[24:27], v[186:189], v[210:213], v[24:27]
	v_mfma_f32_16x16x32_bf16 v[28:31], v[174:177], v[206:209], v[28:31]
	v_mfma_f32_16x16x32_bf16 v[28:31], v[178:181], v[210:213], v[28:31]
	v_mfma_f32_16x16x32_bf16 v[44:47], v[174:177], v[198:201], v[44:47]
	v_mfma_f32_16x16x32_bf16 v[44:47], v[178:181], v[202:205], v[44:47]
	v_mfma_f32_16x16x32_bf16 v[40:43], v[182:185], v[198:201], v[40:43]
	v_mfma_f32_16x16x32_bf16 v[40:43], v[186:189], v[202:205], v[40:43]
	v_mfma_f32_16x16x32_bf16 v[56:59], v[182:185], v[190:193], v[56:59]
	v_mfma_f32_16x16x32_bf16 v[56:59], v[186:189], v[194:197], v[56:59]
	v_mfma_f32_16x16x32_bf16 v[60:63], v[174:177], v[190:193], v[60:63]
	v_mfma_f32_16x16x32_bf16 v[60:63], v[178:181], v[194:197], v[60:63]
	s_barrier
	s_add_i32 s61, s61, 2
	s_add_u32 s62, s62, 0x10000
	s_addc_u32 s63, s63, 0
	s_add_u32 s64, s64, 0x100
	s_addc_u32 s65, s65, 0
	s_add_u32 s8, s8, 0xffffff00
	s_addc_u32 s9, s9, -1
	v_lshl_add_u64 v[2:3], v[2:3], 0, s[40:41]
	s_cmp_gt_u32 s61, 61
	v_lshl_add_u64 v[148:149], v[148:149], 0, s[40:41]
	s_cbranch_scc0 .LBB0_510
	s_and_b64 vcc, exec, s[38:39]
	s_cbranch_vccz .LBB0_513
	s_barrier

.LBB0_664:
	s_cmp_lg_u32 s65, 0
	s_mov_b32 s22, 0
	s_cbranch_scc0 .LBB0_666
	ds_read_b128 v[2:5], v155
	ds_read_b128 v[6:9], v155 offset:1024
	ds_read_b128 v[10:13], v155 offset:2048
	ds_read_b128 v[14:17], v155 offset:3072
	ds_read_b128 v[18:21], v156
	ds_read_b128 v[22:25], v156 offset:1024
	ds_read_b128 v[26:29], v156 offset:2048
	ds_read_b128 v[30:33], v156 offset:3072
	s_add_u32 s0, s54, 0x10000
	s_addc_u32 s1, s55, 0
	ds_read_b128 v[34:37], v157
	ds_read_b128 v[38:41], v157 offset:1024
	ds_read_b128 v[42:45], v157 offset:2048
	ds_read_b128 v[46:49], v157 offset:3072
	ds_read_b128 v[50:53], v157 offset:4096
	ds_read_b128 v[54:57], v157 offset:5120
	ds_read_b128 v[58:61], v157 offset:6144
	ds_read_b128 v[62:65], v157 offset:7168
	s_waitcnt vmcnt(16) lgkmcnt(0)
	s_barrier
	v_mfma_f32_16x16x32_bf16 v[86:89], v[10:13], v[50:53], 0
	v_mfma_f32_16x16x32_bf16 v[92:95], v[14:17], v[54:57], v[86:89]
	v_mfma_f32_16x16x32_bf16 v[86:89], v[2:5], v[58:61], 0
	v_mfma_f32_16x16x32_bf16 v[66:69], v[2:5], v[34:37], 0
	v_mfma_f32_16x16x32_bf16 v[70:73], v[10:13], v[34:37], 0
	v_mfma_f32_16x16x32_bf16 v[74:77], v[2:5], v[42:45], 0
	v_mfma_f32_16x16x32_bf16 v[78:81], v[10:13], v[42:45], 0
	v_mfma_f32_16x16x32_bf16 v[82:85], v[2:5], v[50:53], 0
	v_mfma_f32_16x16x32_bf16 v[96:99], v[6:9], v[62:65], v[86:89]
	v_mfma_f32_16x16x32_bf16 v[86:89], v[10:13], v[58:61], 0
	v_mfma_f32_16x16x32_bf16 v[66:69], v[6:9], v[38:41], v[66:69]
	v_mfma_f32_16x16x32_bf16 v[70:73], v[14:17], v[38:41], v[70:73]
	v_mfma_f32_16x16x32_bf16 v[74:77], v[6:9], v[46:49], v[74:77]
	v_mfma_f32_16x16x32_bf16 v[78:81], v[14:17], v[46:49], v[78:81]
	v_mfma_f32_16x16x32_bf16 v[82:85], v[6:9], v[54:57], v[82:85]
	v_mfma_f32_16x16x32_bf16 v[108:111], v[14:17], v[62:65], v[86:89]
	v_mfma_f32_16x16x32_bf16 v[86:89], v[18:21], v[34:37], 0
	v_mfma_f32_16x16x32_bf16 v[34:37], v[26:29], v[34:37], 0
	v_mfma_f32_16x16x32_bf16 v[112:115], v[22:25], v[38:41], v[86:89]
	v_mfma_f32_16x16x32_bf16 v[34:37], v[30:33], v[38:41], v[34:37]
	v_mfma_f32_16x16x32_bf16 v[38:41], v[18:21], v[42:45], 0
	v_mfma_f32_16x16x32_bf16 v[42:45], v[26:29], v[42:45], 0
	v_mfma_f32_16x16x32_bf16 v[38:41], v[22:25], v[46:49], v[38:41]
	v_mfma_f32_16x16x32_bf16 v[42:45], v[30:33], v[46:49], v[42:45]
	v_mfma_f32_16x16x32_bf16 v[46:49], v[18:21], v[50:53], 0
	v_mfma_f32_16x16x32_bf16 v[50:53], v[26:29], v[50:53], 0
	v_mfma_f32_16x16x32_bf16 v[46:49], v[22:25], v[54:57], v[46:49]
	v_mfma_f32_16x16x32_bf16 v[50:53], v[30:33], v[54:57], v[50:53]
	v_mfma_f32_16x16x32_bf16 v[54:57], v[18:21], v[58:61], 0
	v_mfma_f32_16x16x32_bf16 v[58:61], v[26:29], v[58:61], 0
	v_mfma_f32_16x16x32_bf16 v[54:57], v[22:25], v[62:65], v[54:57]
	v_mfma_f32_16x16x32_bf16 v[58:61], v[30:33], v[62:65], v[58:61]
	s_barrier
	s_add_i32 s12, s58, s20
	v_lshl_add_u64 v[90:91], s[0:1], 0, v[134:135]
	s_mov_b32 m0, s12
	ds_read_b128 v[62:65], v157 offset:16384
	ds_read_b128 v[86:89], v157 offset:17408
	ds_read_b128 v[100:103], v157 offset:18432
	ds_read_b128 v[104:107], v157 offset:19456
	ds_read_b128 v[116:119], v157 offset:20480
	ds_read_b128 v[120:123], v157 offset:21504
	ds_read_b128 v[124:127], v157 offset:22528
	ds_read_b128 v[128:131], v157 offset:23552
	global_load_lds_dwordx4 v[90:91], off
	s_add_i32 m0, s12, 0x2000
	v_lshl_add_u64 v[90:91], s[0:1], 0, v[138:139]
	s_add_u32 s0, s54, 0x14000
	s_addc_u32 s1, s55, 0
	s_add_i32 s12, s59, s20
	global_load_lds_dwordx4 v[90:91], off
	v_lshl_add_u64 v[90:91], s[0:1], 0, v[134:135]
	s_mov_b32 m0, s12
	v_lshl_add_u64 v[148:149], s[6:7], 0, v[132:133]
	global_load_lds_dwordx4 v[90:91], off
	v_lshl_add_u64 v[90:91], s[0:1], 0, v[138:139]
	s_add_i32 m0, s12, 0x2000
	v_lshl_add_u64 v[144:145], s[6:7], 0, v[136:137]
	global_load_lds_dwordx4 v[90:91], off
	s_mov_b32 m0, s21
	v_lshl_add_u64 v[90:91], v[148:149], 0, s[38:39]
	global_load_lds_dwordx4 v[90:91], off
	s_mov_b32 m0, s24
	v_lshl_add_u64 v[90:91], v[144:145], 0, s[38:39]
	global_load_lds_dwordx4 v[90:91], off
	s_waitcnt vmcnt(16) lgkmcnt(0)
	s_barrier
	v_mfma_f32_16x16x32_bf16 v[158:161], v[2:5], v[62:65], 0
	v_mfma_f32_16x16x32_bf16 v[166:169], v[2:5], v[100:103], 0
	v_mfma_f32_16x16x32_bf16 v[174:177], v[2:5], v[116:119], 0
	v_mfma_f32_16x16x32_bf16 v[2:5], v[2:5], v[124:127], 0
	v_mfma_f32_16x16x32_bf16 v[158:161], v[6:9], v[86:89], v[158:161]
	v_mfma_f32_16x16x32_bf16 v[162:165], v[10:13], v[62:65], 0
	v_mfma_f32_16x16x32_bf16 v[166:169], v[6:9], v[104:107], v[166:169]
	v_mfma_f32_16x16x32_bf16 v[170:173], v[10:13], v[100:103], 0
	v_mfma_f32_16x16x32_bf16 v[174:177], v[6:9], v[120:123], v[174:177]
	v_mfma_f32_16x16x32_bf16 v[178:181], v[10:13], v[116:119], 0
	v_mfma_f32_16x16x32_bf16 v[2:5], v[6:9], v[128:131], v[2:5]
	v_mfma_f32_16x16x32_bf16 v[6:9], v[10:13], v[124:127], 0
	v_mfma_f32_16x16x32_bf16 v[162:165], v[14:17], v[86:89], v[162:165]
	v_mfma_f32_16x16x32_bf16 v[170:173], v[14:17], v[104:107], v[170:173]
	v_mfma_f32_16x16x32_bf16 v[178:181], v[14:17], v[120:123], v[178:181]
	v_mfma_f32_16x16x32_bf16 v[12:15], v[14:17], v[128:131], v[6:9]
	v_mfma_f32_16x16x32_bf16 v[6:9], v[18:21], v[62:65], 0
	v_mfma_f32_16x16x32_bf16 v[182:185], v[22:25], v[86:89], v[6:9]
	v_mfma_f32_16x16x32_bf16 v[6:9], v[26:29], v[62:65], 0
	v_mfma_f32_16x16x32_bf16 v[186:189], v[30:33], v[86:89], v[6:9]
	v_mfma_f32_16x16x32_bf16 v[6:9], v[18:21], v[100:103], 0
	v_mfma_f32_16x16x32_bf16 v[190:193], v[22:25], v[104:107], v[6:9]
	v_mfma_f32_16x16x32_bf16 v[6:9], v[26:29], v[100:103], 0
	v_mfma_f32_16x16x32_bf16 v[194:197], v[30:33], v[104:107], v[6:9]
	v_mfma_f32_16x16x32_bf16 v[6:9], v[18:21], v[116:119], 0
	v_mfma_f32_16x16x32_bf16 v[198:201], v[22:25], v[120:123], v[6:9]
	v_mfma_f32_16x16x32_bf16 v[6:9], v[26:29], v[116:119], 0
	v_mfma_f32_16x16x32_bf16 v[202:205], v[30:33], v[120:123], v[6:9]
	v_mfma_f32_16x16x32_bf16 v[6:9], v[18:21], v[124:127], 0
	v_mfma_f32_16x16x32_bf16 v[16:19], v[22:25], v[128:131], v[6:9]
	v_mfma_f32_16x16x32_bf16 v[6:9], v[26:29], v[124:127], 0
	v_mfma_f32_16x16x32_bf16 v[206:209], v[30:33], v[128:131], v[6:9]
	s_barrier
	s_add_i32 s12, 0, 0x18000
	v_add_u32_e32 v1, s12, v152
	s_add_i32 s13, 0, 0x1c000
	s_nop 1
	ds_read_b128 v[6:9], v1
	ds_read_b128 v[28:31], v1 offset:1024
	ds_read_b128 v[62:65], v1 offset:2048
	ds_read_b128 v[210:213], v1 offset:3072
	v_add_u32_e32 v1, s13, v152
	ds_read_b128 v[214:217], v1
	ds_read_b128 v[218:221], v1 offset:1024
	ds_read_b128 v[222:225], v1 offset:2048
	ds_read_b128 v[226:229], v1 offset:3072
	s_add_u32 s0, s6, 0x100100
	s_addc_u32 s1, s7, 0
	s_mov_b32 m0, s25
	v_lshl_add_u64 v[10:11], s[0:1], 0, v[132:133]
	ds_read_b128 v[20:23], v157 offset:32768
	ds_read_b128 v[24:27], v157 offset:33792
	ds_read_b128 v[230:233], v157 offset:34816
	ds_read_b128 v[234:237], v157 offset:35840
	ds_read_b128 v[238:241], v157 offset:36864
	ds_read_b128 v[242:245], v157 offset:37888
	ds_read_b128 v[246:249], v157 offset:38912
	ds_read_b128 v[250:253], v157 offset:39936
	global_load_lds_dwordx4 v[10:11], off
	s_mov_b32 m0, s33
	v_lshl_add_u64 v[10:11], s[0:1], 0, v[136:137]
	global_load_lds_dwordx4 v[10:11], off
	s_waitcnt vmcnt(16) lgkmcnt(0)
	s_barrier
	v_mfma_f32_16x16x32_bf16 v[66:69], v[6:9], v[20:23], v[66:69]
	v_mfma_f32_16x16x32_bf16 v[120:123], v[28:31], v[24:27], v[66:69]
	v_mfma_f32_16x16x32_bf16 v[66:69], v[62:65], v[20:23], v[70:73]
	v_mfma_f32_16x16x32_bf16 v[116:119], v[210:213], v[24:27], v[66:69]
	v_mfma_f32_16x16x32_bf16 v[66:69], v[6:9], v[230:233], v[74:77]
	v_mfma_f32_16x16x32_bf16 v[104:107], v[28:31], v[234:237], v[66:69]
	v_mfma_f32_16x16x32_bf16 v[66:69], v[62:65], v[230:233], v[78:81]
	v_mfma_f32_16x16x32_bf16 v[100:103], v[210:213], v[234:237], v[66:69]
	v_mfma_f32_16x16x32_bf16 v[66:69], v[6:9], v[238:241], v[82:85]
	v_mfma_f32_16x16x32_bf16 v[88:91], v[28:31], v[242:245], v[66:69]
	v_mfma_f32_16x16x32_bf16 v[66:69], v[62:65], v[238:241], v[92:95]
	v_mfma_f32_16x16x32_bf16 v[84:87], v[210:213], v[242:245], v[66:69]
	v_mfma_f32_16x16x32_bf16 v[66:69], v[6:9], v[246:249], v[96:99]
	v_mfma_f32_16x16x32_bf16 v[72:75], v[28:31], v[250:253], v[66:69]
	v_mfma_f32_16x16x32_bf16 v[66:69], v[62:65], v[246:249], v[108:111]
	v_mfma_f32_16x16x32_bf16 v[68:71], v[210:213], v[250:253], v[66:69]
	v_mfma_f32_16x16x32_bf16 v[76:79], v[214:217], v[20:23], v[112:115]
	v_mfma_f32_16x16x32_bf16 v[20:23], v[222:225], v[20:23], v[34:37]
	v_mfma_f32_16x16x32_bf16 v[124:127], v[226:229], v[24:27], v[20:23]
	v_mfma_f32_16x16x32_bf16 v[20:23], v[214:217], v[230:233], v[38:41]
	v_mfma_f32_16x16x32_bf16 v[112:115], v[218:221], v[234:237], v[20:23]
	v_mfma_f32_16x16x32_bf16 v[20:23], v[222:225], v[230:233], v[42:45]
	v_mfma_f32_16x16x32_bf16 v[108:111], v[226:229], v[234:237], v[20:23]
	v_mfma_f32_16x16x32_bf16 v[20:23], v[214:217], v[238:241], v[46:49]
	v_mfma_f32_16x16x32_bf16 v[96:99], v[218:221], v[242:245], v[20:23]
	v_mfma_f32_16x16x32_bf16 v[20:23], v[222:225], v[238:241], v[50:53]
	v_mfma_f32_16x16x32_bf16 v[92:95], v[226:229], v[242:245], v[20:23]
	v_mfma_f32_16x16x32_bf16 v[20:23], v[214:217], v[246:249], v[54:57]
	v_mfma_f32_16x16x32_bf16 v[80:83], v[218:221], v[250:253], v[20:23]
	v_mfma_f32_16x16x32_bf16 v[20:23], v[222:225], v[246:249], v[58:61]
	v_mfma_f32_16x16x32_bf16 v[128:131], v[218:221], v[24:27], v[76:79]
	v_mfma_f32_16x16x32_bf16 v[76:79], v[226:229], v[250:253], v[20:23]
	s_barrier
	s_add_u32 s0, s54, 0x18000
	s_addc_u32 s1, s55, 0
	s_add_i32 s12, s12, s20
	v_lshl_add_u64 v[10:11], s[0:1], 0, v[134:135]
	s_mov_b32 m0, s12
	ds_read_b128 v[32:35], v157 offset:49152
	ds_read_b128 v[44:47], v157 offset:50176
	ds_read_b128 v[230:233], v157 offset:51200
	ds_read_b128 v[234:237], v157 offset:52224
	ds_read_b128 v[238:241], v157 offset:53248
	ds_read_b128 v[242:245], v157 offset:54272
	ds_read_b128 v[246:249], v157 offset:55296
	ds_read_b128 v[250:253], v157 offset:56320
	global_load_lds_dwordx4 v[10:11], off
	s_add_i32 m0, s12, 0x2000
	v_lshl_add_u64 v[10:11], s[0:1], 0, v[138:139]
	s_add_u32 s0, s54, 0x1c000
	s_addc_u32 s1, s55, 0
	s_add_i32 s12, s13, s20
	global_load_lds_dwordx4 v[10:11], off
	s_mov_b32 m0, s12
	v_lshl_add_u64 v[10:11], s[0:1], 0, v[134:135]
	global_load_lds_dwordx4 v[10:11], off
	s_add_i32 m0, s12, 0x2000
	v_lshl_add_u64 v[10:11], s[0:1], 0, v[138:139]
	global_load_lds_dwordx4 v[10:11], off
	s_mov_b32 m0, s51
	v_lshl_add_u64 v[10:11], v[148:149], 0, s[40:41]
	global_load_lds_dwordx4 v[10:11], off
	s_mov_b32 m0, s53
	v_lshl_add_u64 v[10:11], v[144:145], 0, s[40:41]
	global_load_lds_dwordx4 v[10:11], off
	s_waitcnt vmcnt(8) lgkmcnt(0)
	s_barrier
	v_mfma_f32_16x16x32_bf16 v[20:23], v[6:9], v[32:35], v[158:161]
	v_mfma_f32_16x16x32_bf16 v[56:59], v[28:31], v[44:47], v[20:23]
	v_mfma_f32_16x16x32_bf16 v[20:23], v[62:65], v[32:35], v[162:165]
	v_mfma_f32_16x16x32_bf16 v[52:55], v[210:213], v[44:47], v[20:23]
	v_mfma_f32_16x16x32_bf16 v[20:23], v[6:9], v[230:233], v[166:169]
	v_mfma_f32_16x16x32_bf16 v[40:43], v[28:31], v[234:237], v[20:23]
	v_mfma_f32_16x16x32_bf16 v[20:23], v[62:65], v[230:233], v[170:173]
	v_mfma_f32_16x16x32_bf16 v[36:39], v[210:213], v[234:237], v[20:23]
	v_mfma_f32_16x16x32_bf16 v[20:23], v[6:9], v[238:241], v[174:177]
	v_mfma_f32_16x16x32_bf16 v[2:5], v[6:9], v[246:249], v[2:5]
	v_mfma_f32_16x16x32_bf16 v[24:27], v[28:31], v[242:245], v[20:23]
	v_mfma_f32_16x16x32_bf16 v[20:23], v[62:65], v[238:241], v[178:181]
	v_mfma_f32_16x16x32_bf16 v[8:11], v[28:31], v[250:253], v[2:5]
	v_mfma_f32_16x16x32_bf16 v[2:5], v[62:65], v[246:249], v[12:15]
	v_mfma_f32_16x16x32_bf16 v[20:23], v[210:213], v[242:245], v[20:23]
	v_mfma_f32_16x16x32_bf16 v[4:7], v[210:213], v[250:253], v[2:5]
	v_mfma_f32_16x16x32_bf16 v[12:15], v[214:217], v[32:35], v[182:185]
	v_mfma_f32_16x16x32_bf16 v[64:67], v[218:221], v[44:47], v[12:15]
	v_mfma_f32_16x16x32_bf16 v[12:15], v[222:225], v[32:35], v[186:189]
	v_mfma_f32_16x16x32_bf16 v[60:63], v[226:229], v[44:47], v[12:15]
	v_mfma_f32_16x16x32_bf16 v[12:15], v[214:217], v[230:233], v[190:193]
	v_mfma_f32_16x16x32_bf16 v[48:51], v[218:221], v[234:237], v[12:15]
	v_mfma_f32_16x16x32_bf16 v[12:15], v[222:225], v[230:233], v[194:197]
	v_mfma_f32_16x16x32_bf16 v[44:47], v[226:229], v[234:237], v[12:15]
	v_mfma_f32_16x16x32_bf16 v[12:15], v[214:217], v[238:241], v[198:201]
	v_mfma_f32_16x16x32_bf16 v[32:35], v[218:221], v[242:245], v[12:15]
	v_mfma_f32_16x16x32_bf16 v[12:15], v[222:225], v[238:241], v[202:205]
	v_mfma_f32_16x16x32_bf16 v[28:31], v[226:229], v[242:245], v[12:15]
	v_mfma_f32_16x16x32_bf16 v[12:15], v[214:217], v[246:249], v[16:19]
	v_mfma_f32_16x16x32_bf16 v[16:19], v[218:221], v[250:253], v[12:15]
	v_mfma_f32_16x16x32_bf16 v[12:15], v[222:225], v[246:249], v[206:209]
	v_mfma_f32_16x16x32_bf16 v[12:15], v[226:229], v[250:253], v[12:15]
	s_barrier
	s_mov_b32 s22, 2
	s_branch .LBB0_667

.LBB0_668:
	ds_read_b128 v[158:161], v155
	ds_read_b128 v[162:165], v155 offset:1024
	ds_read_b128 v[166:169], v155 offset:2048
	ds_read_b128 v[170:173], v155 offset:3072
	ds_read_b128 v[174:177], v156
	ds_read_b128 v[178:181], v156 offset:1024
	ds_read_b128 v[182:185], v156 offset:2048
	ds_read_b128 v[186:189], v156 offset:3072
	s_add_u32 s12, s70, s34
	s_addc_u32 s13, s71, 0
	s_cmp_eq_u32 s34, s6
	s_cselect_b32 s23, s0, s13
	s_cselect_b32 s22, s1, s12
	s_cselect_b32 s55, s43, s69
	s_cselect_b32 s54, s66, s68
	s_add_i32 s73, s21, 0xc000
	v_lshl_add_u64 v[144:145], v[2:3], 0, s[34:35]
	s_mov_b32 m0, s73
	s_add_i32 s72, s21, 0xe000
	ds_read_b128 v[190:193], v157
	ds_read_b128 v[194:197], v157 offset:1024
	ds_read_b128 v[198:201], v157 offset:2048
	ds_read_b128 v[202:205], v157 offset:3072
	ds_read_b128 v[206:209], v157 offset:4096
	ds_read_b128 v[210:213], v157 offset:5120
	ds_read_b128 v[214:217], v157 offset:6144
	ds_read_b128 v[218:221], v157 offset:7168
	global_load_lds_dwordx4 v[144:145], off
	s_mov_b32 m0, s72
	v_lshl_add_u64 v[144:145], v[148:149], 0, s[34:35]
	global_load_lds_dwordx4 v[144:145], off
	s_waitcnt vmcnt(8) lgkmcnt(0)
	s_barrier
	v_mfma_f32_16x16x32_bf16 v[120:123], v[158:161], v[190:193], v[120:123]
	v_mfma_f32_16x16x32_bf16 v[120:123], v[162:165], v[194:197], v[120:123]
	v_mfma_f32_16x16x32_bf16 v[116:119], v[166:169], v[190:193], v[116:119]
	v_mfma_f32_16x16x32_bf16 v[116:119], v[170:173], v[194:197], v[116:119]
	v_mfma_f32_16x16x32_bf16 v[100:103], v[166:169], v[198:201], v[100:103]
	v_mfma_f32_16x16x32_bf16 v[100:103], v[170:173], v[202:205], v[100:103]
	v_mfma_f32_16x16x32_bf16 v[104:107], v[158:161], v[198:201], v[104:107]
	v_mfma_f32_16x16x32_bf16 v[104:107], v[162:165], v[202:205], v[104:107]
	v_mfma_f32_16x16x32_bf16 v[88:91], v[158:161], v[206:209], v[88:91]
	v_mfma_f32_16x16x32_bf16 v[88:91], v[162:165], v[210:213], v[88:91]
	v_mfma_f32_16x16x32_bf16 v[84:87], v[166:169], v[206:209], v[84:87]
	v_mfma_f32_16x16x32_bf16 v[84:87], v[170:173], v[210:213], v[84:87]
	v_mfma_f32_16x16x32_bf16 v[68:71], v[166:169], v[214:217], v[68:71]
	v_mfma_f32_16x16x32_bf16 v[68:71], v[170:173], v[218:221], v[68:71]
	v_mfma_f32_16x16x32_bf16 v[72:75], v[158:161], v[214:217], v[72:75]
	v_mfma_f32_16x16x32_bf16 v[72:75], v[162:165], v[218:221], v[72:75]
	v_mfma_f32_16x16x32_bf16 v[80:83], v[174:177], v[214:217], v[80:83]
	v_mfma_f32_16x16x32_bf16 v[80:83], v[178:181], v[218:221], v[80:83]
	v_mfma_f32_16x16x32_bf16 v[76:79], v[182:185], v[214:217], v[76:79]
	v_mfma_f32_16x16x32_bf16 v[76:79], v[186:189], v[218:221], v[76:79]
	v_mfma_f32_16x16x32_bf16 v[92:95], v[182:185], v[206:209], v[92:95]
	v_mfma_f32_16x16x32_bf16 v[92:95], v[186:189], v[210:213], v[92:95]
	v_mfma_f32_16x16x32_bf16 v[96:99], v[174:177], v[206:209], v[96:99]
	v_mfma_f32_16x16x32_bf16 v[96:99], v[178:181], v[210:213], v[96:99]
	v_mfma_f32_16x16x32_bf16 v[112:115], v[174:177], v[198:201], v[112:115]
	v_mfma_f32_16x16x32_bf16 v[112:115], v[178:181], v[202:205], v[112:115]
	v_mfma_f32_16x16x32_bf16 v[108:111], v[182:185], v[198:201], v[108:111]
	v_mfma_f32_16x16x32_bf16 v[108:111], v[186:189], v[202:205], v[108:111]
	v_mfma_f32_16x16x32_bf16 v[124:127], v[182:185], v[190:193], v[124:127]
	v_mfma_f32_16x16x32_bf16 v[124:127], v[186:189], v[194:197], v[124:127]
	v_mfma_f32_16x16x32_bf16 v[128:131], v[174:177], v[190:193], v[128:131]
	v_mfma_f32_16x16x32_bf16 v[128:131], v[178:181], v[194:197], v[128:131]
	s_barrier
	s_add_i32 s12, s58, s20
	v_lshl_add_u64 v[144:145], s[54:55], 0, v[134:135]
	s_mov_b32 m0, s12
	ds_read_b128 v[190:193], v157 offset:16384
	ds_read_b128 v[194:197], v157 offset:17408
	ds_read_b128 v[198:201], v157 offset:18432
	ds_read_b128 v[202:205], v157 offset:19456
	ds_read_b128 v[206:209], v157 offset:20480
	ds_read_b128 v[210:213], v157 offset:21504
	ds_read_b128 v[214:217], v157 offset:22528
	ds_read_b128 v[218:221], v157 offset:23552
	global_load_lds_dwordx4 v[144:145], off
	s_add_i32 m0, s12, 0x2000
	s_add_u32 s12, s54, 0x4000
	v_lshl_add_u64 v[144:145], s[54:55], 0, v[138:139]
	s_addc_u32 s13, s55, 0
	s_add_i32 s14, s59, s20
	global_load_lds_dwordx4 v[144:145], off
	v_lshl_add_u64 v[144:145], s[12:13], 0, v[134:135]
	s_mov_b32 m0, s14
	v_lshl_add_u64 v[222:223], s[22:23], 0, v[136:137]
	global_load_lds_dwordx4 v[144:145], off
	s_add_i32 m0, s14, 0x2000
	v_lshl_add_u64 v[144:145], s[12:13], 0, v[138:139]
	global_load_lds_dwordx4 v[144:145], off
	s_mov_b32 m0, s21
	v_lshl_add_u64 v[144:145], s[22:23], 0, v[132:133]
	global_load_lds_dwordx4 v[144:145], off
	s_mov_b32 m0, s24
	s_nop 0
	global_load_lds_dwordx4 v[222:223], off
	s_waitcnt vmcnt(8) lgkmcnt(0)
	s_barrier
	v_mfma_f32_16x16x32_bf16 v[56:59], v[158:161], v[190:193], v[56:59]
	v_mfma_f32_16x16x32_bf16 v[56:59], v[162:165], v[194:197], v[56:59]
	v_mfma_f32_16x16x32_bf16 v[52:55], v[166:169], v[190:193], v[52:55]
	v_mfma_f32_16x16x32_bf16 v[52:55], v[170:173], v[194:197], v[52:55]
	v_mfma_f32_16x16x32_bf16 v[36:39], v[166:169], v[198:201], v[36:39]
	v_mfma_f32_16x16x32_bf16 v[36:39], v[170:173], v[202:205], v[36:39]
	v_mfma_f32_16x16x32_bf16 v[40:43], v[158:161], v[198:201], v[40:43]
	v_mfma_f32_16x16x32_bf16 v[40:43], v[162:165], v[202:205], v[40:43]
	v_mfma_f32_16x16x32_bf16 v[24:27], v[158:161], v[206:209], v[24:27]
	v_mfma_f32_16x16x32_bf16 v[24:27], v[162:165], v[210:213], v[24:27]
	v_mfma_f32_16x16x32_bf16 v[20:23], v[166:169], v[206:209], v[20:23]
	v_mfma_f32_16x16x32_bf16 v[20:23], v[170:173], v[210:213], v[20:23]
	v_mfma_f32_16x16x32_bf16 v[4:7], v[166:169], v[214:217], v[4:7]
	v_mfma_f32_16x16x32_bf16 v[4:7], v[170:173], v[218:221], v[4:7]
	v_mfma_f32_16x16x32_bf16 v[8:11], v[158:161], v[214:217], v[8:11]
	v_mfma_f32_16x16x32_bf16 v[8:11], v[162:165], v[218:221], v[8:11]
	v_mfma_f32_16x16x32_bf16 v[16:19], v[174:177], v[214:217], v[16:19]
	v_mfma_f32_16x16x32_bf16 v[16:19], v[178:181], v[218:221], v[16:19]
	v_mfma_f32_16x16x32_bf16 v[12:15], v[182:185], v[214:217], v[12:15]
	v_mfma_f32_16x16x32_bf16 v[12:15], v[186:189], v[218:221], v[12:15]
	v_mfma_f32_16x16x32_bf16 v[28:31], v[182:185], v[206:209], v[28:31]
	v_mfma_f32_16x16x32_bf16 v[28:31], v[186:189], v[210:213], v[28:31]
	v_mfma_f32_16x16x32_bf16 v[32:35], v[174:177], v[206:209], v[32:35]
	v_mfma_f32_16x16x32_bf16 v[32:35], v[178:181], v[210:213], v[32:35]
	v_mfma_f32_16x16x32_bf16 v[48:51], v[174:177], v[198:201], v[48:51]
	v_mfma_f32_16x16x32_bf16 v[48:51], v[178:181], v[202:205], v[48:51]
	v_mfma_f32_16x16x32_bf16 v[44:47], v[182:185], v[198:201], v[44:47]
	v_mfma_f32_16x16x32_bf16 v[44:47], v[186:189], v[202:205], v[44:47]
	v_mfma_f32_16x16x32_bf16 v[60:63], v[182:185], v[190:193], v[60:63]
	v_mfma_f32_16x16x32_bf16 v[60:63], v[186:189], v[194:197], v[60:63]
	v_mfma_f32_16x16x32_bf16 v[64:67], v[174:177], v[190:193], v[64:67]
	v_mfma_f32_16x16x32_bf16 v[64:67], v[178:181], v[194:197], v[64:67]
	s_barrier
	s_add_i32 s14, 0, 0x18000
	v_add_u32_e32 v1, s14, v152
	s_add_i32 s74, 0, 0x1c000
	ds_read_b128 v[158:161], v1
	ds_read_b128 v[162:165], v1 offset:1024
	ds_read_b128 v[166:169], v1 offset:2048
	ds_read_b128 v[170:173], v1 offset:3072
	v_add_u32_e32 v1, s74, v152
	ds_read_b128 v[174:177], v1
	ds_read_b128 v[178:181], v1 offset:1024
	ds_read_b128 v[182:185], v1 offset:2048
	ds_read_b128 v[186:189], v1 offset:3072
	s_add_u32 s12, s22, 0x100000
	s_addc_u32 s13, s23, 0
	s_mov_b32 m0, s25
	v_lshl_add_u64 v[224:225], s[12:13], 0, v[132:133]
	ds_read_b128 v[190:193], v157 offset:32768
	ds_read_b128 v[194:197], v157 offset:33792
	ds_read_b128 v[198:201], v157 offset:34816
	ds_read_b128 v[202:205], v157 offset:35840
	ds_read_b128 v[206:209], v157 offset:36864
	ds_read_b128 v[210:213], v157 offset:37888
	ds_read_b128 v[214:217], v157 offset:38912
	ds_read_b128 v[218:221], v157 offset:39936
	global_load_lds_dwordx4 v[224:225], off
	s_mov_b32 m0, s33
	v_lshl_add_u64 v[224:225], s[12:13], 0, v[136:137]
	global_load_lds_dwordx4 v[224:225], off
	s_waitcnt vmcnt(8) lgkmcnt(0)
	s_barrier
	v_mfma_f32_16x16x32_bf16 v[120:123], v[158:161], v[190:193], v[120:123]
	v_mfma_f32_16x16x32_bf16 v[120:123], v[162:165], v[194:197], v[120:123]
	v_mfma_f32_16x16x32_bf16 v[116:119], v[166:169], v[190:193], v[116:119]
	v_mfma_f32_16x16x32_bf16 v[116:119], v[170:173], v[194:197], v[116:119]
	v_mfma_f32_16x16x32_bf16 v[100:103], v[166:169], v[198:201], v[100:103]
	v_mfma_f32_16x16x32_bf16 v[100:103], v[170:173], v[202:205], v[100:103]
	v_mfma_f32_16x16x32_bf16 v[104:107], v[158:161], v[198:201], v[104:107]
	v_mfma_f32_16x16x32_bf16 v[104:107], v[162:165], v[202:205], v[104:107]
	v_mfma_f32_16x16x32_bf16 v[88:91], v[158:161], v[206:209], v[88:91]
	v_mfma_f32_16x16x32_bf16 v[88:91], v[162:165], v[210:213], v[88:91]
	v_mfma_f32_16x16x32_bf16 v[84:87], v[166:169], v[206:209], v[84:87]
	v_mfma_f32_16x16x32_bf16 v[84:87], v[170:173], v[210:213], v[84:87]
	v_mfma_f32_16x16x32_bf16 v[68:71], v[166:169], v[214:217], v[68:71]
	v_mfma_f32_16x16x32_bf16 v[68:71], v[170:173], v[218:221], v[68:71]
	v_mfma_f32_16x16x32_bf16 v[72:75], v[158:161], v[214:217], v[72:75]
	v_mfma_f32_16x16x32_bf16 v[72:75], v[162:165], v[218:221], v[72:75]
	v_mfma_f32_16x16x32_bf16 v[80:83], v[174:177], v[214:217], v[80:83]
	v_mfma_f32_16x16x32_bf16 v[80:83], v[178:181], v[218:221], v[80:83]
	v_mfma_f32_16x16x32_bf16 v[76:79], v[182:185], v[214:217], v[76:79]
	v_mfma_f32_16x16x32_bf16 v[76:79], v[186:189], v[218:221], v[76:79]
	v_mfma_f32_16x16x32_bf16 v[92:95], v[182:185], v[206:209], v[92:95]
	v_mfma_f32_16x16x32_bf16 v[92:95], v[186:189], v[210:213], v[92:95]
	v_mfma_f32_16x16x32_bf16 v[96:99], v[174:177], v[206:209], v[96:99]
	v_mfma_f32_16x16x32_bf16 v[96:99], v[178:181], v[210:213], v[96:99]
	v_mfma_f32_16x16x32_bf16 v[112:115], v[174:177], v[198:201], v[112:115]
	v_mfma_f32_16x16x32_bf16 v[112:115], v[178:181], v[202:205], v[112:115]
	v_mfma_f32_16x16x32_bf16 v[108:111], v[182:185], v[198:201], v[108:111]
	v_mfma_f32_16x16x32_bf16 v[108:111], v[186:189], v[202:205], v[108:111]
	v_mfma_f32_16x16x32_bf16 v[124:127], v[182:185], v[190:193], v[124:127]
	v_mfma_f32_16x16x32_bf16 v[124:127], v[186:189], v[194:197], v[124:127]
	v_mfma_f32_16x16x32_bf16 v[128:131], v[174:177], v[190:193], v[128:131]
	v_mfma_f32_16x16x32_bf16 v[128:131], v[178:181], v[194:197], v[128:131]
	s_barrier
	s_add_u32 s12, s54, 0x8000
	s_addc_u32 s13, s55, 0
	s_add_i32 s14, s14, s20
	v_lshl_add_u64 v[224:225], s[12:13], 0, v[134:135]
	s_mov_b32 m0, s14
	ds_read_b128 v[190:193], v157 offset:49152
	ds_read_b128 v[194:197], v157 offset:50176
	ds_read_b128 v[198:201], v157 offset:51200
	ds_read_b128 v[202:205], v157 offset:52224
	ds_read_b128 v[206:209], v157 offset:53248
	ds_read_b128 v[210:213], v157 offset:54272
	ds_read_b128 v[214:217], v157 offset:55296
	ds_read_b128 v[218:221], v157 offset:56320
	global_load_lds_dwordx4 v[224:225], off
	s_add_i32 m0, s14, 0x2000
	v_lshl_add_u64 v[224:225], s[12:13], 0, v[138:139]
	s_add_u32 s12, s54, 0xc000
	s_addc_u32 s13, s55, 0
	s_add_i32 s14, s74, s20
	global_load_lds_dwordx4 v[224:225], off
	v_lshl_add_u64 v[224:225], s[12:13], 0, v[134:135]
	s_mov_b32 m0, s14
	v_lshl_add_u64 v[144:145], v[144:145], 0, s[30:31]
	global_load_lds_dwordx4 v[224:225], off
	s_add_i32 m0, s14, 0x2000
	v_lshl_add_u64 v[224:225], s[12:13], 0, v[138:139]
	global_load_lds_dwordx4 v[224:225], off
	s_mov_b32 m0, s51
	s_nop 0
	global_load_lds_dwordx4 v[144:145], off
	s_mov_b32 m0, s53
	v_lshl_add_u64 v[144:145], v[222:223], 0, s[30:31]
	global_load_lds_dwordx4 v[144:145], off
	s_waitcnt vmcnt(8) lgkmcnt(0)
	s_barrier
	v_mfma_f32_16x16x32_bf16 v[56:59], v[158:161], v[190:193], v[56:59]
	v_mfma_f32_16x16x32_bf16 v[56:59], v[162:165], v[194:197], v[56:59]
	v_mfma_f32_16x16x32_bf16 v[52:55], v[166:169], v[190:193], v[52:55]
	v_mfma_f32_16x16x32_bf16 v[52:55], v[170:173], v[194:197], v[52:55]
	v_mfma_f32_16x16x32_bf16 v[36:39], v[166:169], v[198:201], v[36:39]
	v_mfma_f32_16x16x32_bf16 v[36:39], v[170:173], v[202:205], v[36:39]
	v_mfma_f32_16x16x32_bf16 v[40:43], v[158:161], v[198:201], v[40:43]
	v_mfma_f32_16x16x32_bf16 v[40:43], v[162:165], v[202:205], v[40:43]
	v_mfma_f32_16x16x32_bf16 v[24:27], v[158:161], v[206:209], v[24:27]
	v_mfma_f32_16x16x32_bf16 v[24:27], v[162:165], v[210:213], v[24:27]
	v_mfma_f32_16x16x32_bf16 v[20:23], v[166:169], v[206:209], v[20:23]
	v_mfma_f32_16x16x32_bf16 v[20:23], v[170:173], v[210:213], v[20:23]
	v_mfma_f32_16x16x32_bf16 v[4:7], v[166:169], v[214:217], v[4:7]
	v_mfma_f32_16x16x32_bf16 v[4:7], v[170:173], v[218:221], v[4:7]
	v_mfma_f32_16x16x32_bf16 v[8:11], v[158:161], v[214:217], v[8:11]
	v_mfma_f32_16x16x32_bf16 v[8:11], v[162:165], v[218:221], v[8:11]
	v_mfma_f32_16x16x32_bf16 v[16:19], v[174:177], v[214:217], v[16:19]
	v_mfma_f32_16x16x32_bf16 v[16:19], v[178:181], v[218:221], v[16:19]
	v_mfma_f32_16x16x32_bf16 v[12:15], v[182:185], v[214:217], v[12:15]
	v_mfma_f32_16x16x32_bf16 v[12:15], v[186:189], v[218:221], v[12:15]
	v_mfma_f32_16x16x32_bf16 v[28:31], v[182:185], v[206:209], v[28:31]
	v_mfma_f32_16x16x32_bf16 v[28:31], v[186:189], v[210:213], v[28:31]
	v_mfma_f32_16x16x32_bf16 v[32:35], v[174:177], v[206:209], v[32:35]
	v_mfma_f32_16x16x32_bf16 v[32:35], v[178:181], v[210:213], v[32:35]
	v_mfma_f32_16x16x32_bf16 v[48:51], v[174:177], v[198:201], v[48:51]
	v_mfma_f32_16x16x32_bf16 v[48:51], v[178:181], v[202:205], v[48:51]
	v_mfma_f32_16x16x32_bf16 v[44:47], v[182:185], v[198:201], v[44:47]
	v_mfma_f32_16x16x32_bf16 v[44:47], v[186:189], v[202:205], v[44:47]
	v_mfma_f32_16x16x32_bf16 v[60:63], v[182:185], v[190:193], v[60:63]
	v_mfma_f32_16x16x32_bf16 v[60:63], v[186:189], v[194:197], v[60:63]
	v_mfma_f32_16x16x32_bf16 v[64:67], v[174:177], v[190:193], v[64:67]
	v_mfma_f32_16x16x32_bf16 v[64:67], v[178:181], v[194:197], v[64:67]
	s_barrier
	s_add_i32 s67, s67, 2
	s_add_u32 s68, s68, 0x10000
	s_addc_u32 s69, s69, 0
	s_add_u32 s70, s70, 0x100
	s_addc_u32 s71, s71, 0
	s_add_u32 s6, s6, 0xffffff00
	s_addc_u32 s7, s7, -1
	v_lshl_add_u64 v[2:3], v[2:3], 0, s[38:39]
	s_cmp_gt_u32 s67, 61
	v_lshl_add_u64 v[148:149], v[148:149], 0, s[38:39]
	s_cbranch_scc0 .LBB0_668
	s_and_b64 vcc, exec, s[36:37]
	s_cbranch_vccnz .LBB0_676
	s_and_b64 s[0:1], s[10:11], s[4:5]
	s_andn2_b64 vcc, exec, s[0:1]
	s_cbranch_vccz .LBB0_677

.LBB0_757:
	ds_read_b128 v[2:5], v153
	ds_read_b128 v[6:9], v153 offset:1024
	ds_read_b128 v[10:13], v153 offset:2048
	ds_read_b128 v[14:17], v153 offset:3072
	ds_read_b128 v[18:21], v154
	ds_read_b128 v[22:25], v154 offset:1024
	ds_read_b128 v[26:29], v154 offset:2048
	ds_read_b128 v[30:33], v154 offset:3072
	s_add_u32 s0, s50, 0x10000
	s_addc_u32 s1, s51, 0
	ds_read_b128 v[34:37], v155
	ds_read_b128 v[38:41], v155 offset:1024
	ds_read_b128 v[42:45], v155 offset:2048
	ds_read_b128 v[46:49], v155 offset:3072
	ds_read_b128 v[50:53], v155 offset:4096
	ds_read_b128 v[54:57], v155 offset:5120
	ds_read_b128 v[58:61], v155 offset:6144
	ds_read_b128 v[62:65], v155 offset:7168
	s_waitcnt vmcnt(24) lgkmcnt(0)
	s_barrier
	v_mfma_f32_16x16x32_bf16 v[66:69], v[2:5], v[34:37], 0
	v_mfma_f32_16x16x32_bf16 v[70:73], v[10:13], v[34:37], 0
	v_mfma_f32_16x16x32_bf16 v[74:77], v[2:5], v[42:45], 0
	v_mfma_f32_16x16x32_bf16 v[78:81], v[10:13], v[42:45], 0
	v_mfma_f32_16x16x32_bf16 v[82:85], v[2:5], v[50:53], 0
	v_mfma_f32_16x16x32_bf16 v[86:89], v[10:13], v[50:53], 0
	v_mfma_f32_16x16x32_bf16 v[90:93], v[2:5], v[58:61], 0
	v_mfma_f32_16x16x32_bf16 v[94:97], v[10:13], v[58:61], 0
	v_mfma_f32_16x16x32_bf16 v[66:69], v[6:9], v[38:41], v[66:69]
	v_mfma_f32_16x16x32_bf16 v[70:73], v[14:17], v[38:41], v[70:73]
	v_mfma_f32_16x16x32_bf16 v[74:77], v[6:9], v[46:49], v[74:77]
	v_mfma_f32_16x16x32_bf16 v[78:81], v[14:17], v[46:49], v[78:81]
	v_mfma_f32_16x16x32_bf16 v[82:85], v[6:9], v[54:57], v[82:85]
	v_mfma_f32_16x16x32_bf16 v[86:89], v[14:17], v[54:57], v[86:89]
	v_mfma_f32_16x16x32_bf16 v[90:93], v[6:9], v[62:65], v[90:93]
	v_mfma_f32_16x16x32_bf16 v[104:107], v[14:17], v[62:65], v[94:97]
	v_mfma_f32_16x16x32_bf16 v[94:97], v[18:21], v[34:37], 0
	v_mfma_f32_16x16x32_bf16 v[34:37], v[26:29], v[34:37], 0
	v_mfma_f32_16x16x32_bf16 v[108:111], v[22:25], v[38:41], v[94:97]
	v_mfma_f32_16x16x32_bf16 v[34:37], v[30:33], v[38:41], v[34:37]
	v_mfma_f32_16x16x32_bf16 v[38:41], v[18:21], v[42:45], 0
	v_mfma_f32_16x16x32_bf16 v[42:45], v[26:29], v[42:45], 0
	v_mfma_f32_16x16x32_bf16 v[38:41], v[22:25], v[46:49], v[38:41]
	v_mfma_f32_16x16x32_bf16 v[42:45], v[30:33], v[46:49], v[42:45]
	v_mfma_f32_16x16x32_bf16 v[46:49], v[18:21], v[50:53], 0
	v_mfma_f32_16x16x32_bf16 v[50:53], v[26:29], v[50:53], 0
	v_mfma_f32_16x16x32_bf16 v[46:49], v[22:25], v[54:57], v[46:49]
	v_mfma_f32_16x16x32_bf16 v[50:53], v[30:33], v[54:57], v[50:53]
	v_mfma_f32_16x16x32_bf16 v[54:57], v[18:21], v[58:61], 0
	v_mfma_f32_16x16x32_bf16 v[58:61], v[26:29], v[58:61], 0
	v_mfma_f32_16x16x32_bf16 v[54:57], v[22:25], v[62:65], v[54:57]
	v_mfma_f32_16x16x32_bf16 v[58:61], v[30:33], v[62:65], v[58:61]
	s_barrier
	s_add_i32 s12, s57, s2
	v_lshl_add_u64 v[102:103], s[0:1], 0, v[134:135]
	s_mov_b32 m0, s12
	ds_read_b128 v[62:65], v155 offset:16384
	ds_read_b128 v[94:97], v155 offset:17408
	ds_read_b128 v[98:101], v155 offset:18432
	ds_read_b128 v[112:115], v155 offset:19456
	ds_read_b128 v[116:119], v155 offset:20480
	ds_read_b128 v[120:123], v155 offset:21504
	ds_read_b128 v[124:127], v155 offset:22528
	ds_read_b128 v[128:131], v155 offset:23552
	global_load_lds_dwordx4 v[102:103], off
	s_add_i32 m0, s12, 0x2000
	v_lshl_add_u64 v[102:103], s[0:1], 0, v[138:139]
	s_add_u32 s0, s50, 0x14000
	s_addc_u32 s1, s51, 0
	s_add_i32 s12, s58, s2
	global_load_lds_dwordx4 v[102:103], off
	v_lshl_add_u64 v[102:103], s[0:1], 0, v[134:135]
	s_mov_b32 m0, s12
	v_lshl_add_u64 v[148:149], s[52:53], 0, v[132:133]
	global_load_lds_dwordx4 v[102:103], off
	v_lshl_add_u64 v[102:103], s[0:1], 0, v[138:139]
	s_add_i32 m0, s12, 0x2000
	v_lshl_add_u64 v[144:145], s[52:53], 0, v[136:137]
	global_load_lds_dwordx4 v[102:103], off
	s_mov_b32 m0, s19
	v_lshl_add_u64 v[102:103], v[148:149], 0, s[44:45]
	global_load_lds_dwordx4 v[102:103], off
	s_mov_b32 m0, s20
	v_lshl_add_u64 v[102:103], v[144:145], 0, s[44:45]
	global_load_lds_dwordx4 v[102:103], off
	s_waitcnt vmcnt(24) lgkmcnt(0)
	s_barrier
	v_mfma_f32_16x16x32_bf16 v[158:161], v[2:5], v[62:65], 0
	v_mfma_f32_16x16x32_bf16 v[166:169], v[2:5], v[98:101], 0
	v_mfma_f32_16x16x32_bf16 v[174:177], v[2:5], v[116:119], 0
	v_mfma_f32_16x16x32_bf16 v[2:5], v[2:5], v[124:127], 0
	v_mfma_f32_16x16x32_bf16 v[158:161], v[6:9], v[94:97], v[158:161]
	v_mfma_f32_16x16x32_bf16 v[166:169], v[6:9], v[112:115], v[166:169]
	v_mfma_f32_16x16x32_bf16 v[174:177], v[6:9], v[120:123], v[174:177]
	v_mfma_f32_16x16x32_bf16 v[2:5], v[6:9], v[128:131], v[2:5]
	v_mfma_f32_16x16x32_bf16 v[6:9], v[10:13], v[124:127], 0
	v_mfma_f32_16x16x32_bf16 v[162:165], v[10:13], v[62:65], 0
	v_mfma_f32_16x16x32_bf16 v[170:173], v[10:13], v[98:101], 0
	v_mfma_f32_16x16x32_bf16 v[178:181], v[10:13], v[116:119], 0
	v_mfma_f32_16x16x32_bf16 v[6:9], v[14:17], v[128:131], v[6:9]
	v_mfma_f32_16x16x32_bf16 v[162:165], v[14:17], v[94:97], v[162:165]
	v_mfma_f32_16x16x32_bf16 v[170:173], v[14:17], v[112:115], v[170:173]
	v_mfma_f32_16x16x32_bf16 v[178:181], v[14:17], v[120:123], v[178:181]
	v_mfma_f32_16x16x32_bf16 v[14:17], v[26:29], v[62:65], 0
	v_mfma_f32_16x16x32_bf16 v[182:185], v[30:33], v[94:97], v[14:17]
	v_mfma_f32_16x16x32_bf16 v[14:17], v[18:21], v[98:101], 0
	v_mfma_f32_16x16x32_bf16 v[186:189], v[22:25], v[112:115], v[14:17]
	v_mfma_f32_16x16x32_bf16 v[14:17], v[26:29], v[98:101], 0
	v_mfma_f32_16x16x32_bf16 v[190:193], v[30:33], v[112:115], v[14:17]
	v_mfma_f32_16x16x32_bf16 v[14:17], v[18:21], v[116:119], 0
	v_mfma_f32_16x16x32_bf16 v[194:197], v[22:25], v[120:123], v[14:17]
	v_mfma_f32_16x16x32_bf16 v[14:17], v[26:29], v[116:119], 0
	v_mfma_f32_16x16x32_bf16 v[10:13], v[18:21], v[62:65], 0
	v_mfma_f32_16x16x32_bf16 v[198:201], v[30:33], v[120:123], v[14:17]
	v_mfma_f32_16x16x32_bf16 v[14:17], v[18:21], v[124:127], 0
	v_mfma_f32_16x16x32_bf16 v[10:13], v[22:25], v[94:97], v[10:13]
	v_mfma_f32_16x16x32_bf16 v[202:205], v[22:25], v[128:131], v[14:17]
	v_mfma_f32_16x16x32_bf16 v[14:17], v[26:29], v[124:127], 0
	v_mfma_f32_16x16x32_bf16 v[206:209], v[30:33], v[128:131], v[14:17]
	s_barrier
	s_add_i32 s12, 0, 0x18000
	v_add_u32_e32 v1, s12, v151
	s_add_i32 s13, 0, 0x1c000
	s_nop 1
	ds_read_b128 v[14:17], v1
	ds_read_b128 v[24:27], v1 offset:1024
	ds_read_b128 v[28:31], v1 offset:2048
	ds_read_b128 v[210:213], v1 offset:3072
	v_add_u32_e32 v1, s13, v151
	ds_read_b128 v[214:217], v1
	ds_read_b128 v[218:221], v1 offset:1024
	ds_read_b128 v[222:225], v1 offset:2048
	ds_read_b128 v[226:229], v1 offset:3072
	s_add_u32 s0, s52, 0x2b0100
	s_addc_u32 s1, s53, 0
	s_mov_b32 m0, s21
	v_lshl_add_u64 v[22:23], s[0:1], 0, v[132:133]
	ds_read_b128 v[18:21], v155 offset:32768
	ds_read_b128 v[120:123], v155 offset:33792
	ds_read_b128 v[230:233], v155 offset:34816
	ds_read_b128 v[234:237], v155 offset:35840
	ds_read_b128 v[238:241], v155 offset:36864
	ds_read_b128 v[242:245], v155 offset:37888
	ds_read_b128 v[246:249], v155 offset:38912
	ds_read_b128 v[250:253], v155 offset:39936
	global_load_lds_dwordx4 v[22:23], off
	s_mov_b32 m0, s24
	v_lshl_add_u64 v[22:23], s[0:1], 0, v[136:137]
	global_load_lds_dwordx4 v[22:23], off
	s_waitcnt vmcnt(24) lgkmcnt(0)
	s_barrier
	v_mfma_f32_16x16x32_bf16 v[62:65], v[14:17], v[18:21], v[66:69]
	v_mfma_f32_16x16x32_bf16 v[128:131], v[24:27], v[120:123], v[62:65]
	v_mfma_f32_16x16x32_bf16 v[62:65], v[28:31], v[18:21], v[70:73]
	v_mfma_f32_16x16x32_bf16 v[116:119], v[210:213], v[120:123], v[62:65]
	v_mfma_f32_16x16x32_bf16 v[62:65], v[14:17], v[230:233], v[74:77]
	v_mfma_f32_16x16x32_bf16 v[112:115], v[24:27], v[234:237], v[62:65]
	v_mfma_f32_16x16x32_bf16 v[62:65], v[28:31], v[230:233], v[78:81]
	v_mfma_f32_16x16x32_bf16 v[100:103], v[210:213], v[234:237], v[62:65]
	v_mfma_f32_16x16x32_bf16 v[62:65], v[14:17], v[238:241], v[82:85]
	v_mfma_f32_16x16x32_bf16 v[96:99], v[24:27], v[242:245], v[62:65]
	v_mfma_f32_16x16x32_bf16 v[62:65], v[28:31], v[238:241], v[86:89]
	v_mfma_f32_16x16x32_bf16 v[84:87], v[210:213], v[242:245], v[62:65]
	v_mfma_f32_16x16x32_bf16 v[62:65], v[14:17], v[246:249], v[90:93]
	v_mfma_f32_16x16x32_bf16 v[80:83], v[24:27], v[250:253], v[62:65]
	v_mfma_f32_16x16x32_bf16 v[62:65], v[28:31], v[246:249], v[104:107]
	v_mfma_f32_16x16x32_bf16 v[64:67], v[210:213], v[250:253], v[62:65]
	v_mfma_f32_16x16x32_bf16 v[68:71], v[214:217], v[18:21], v[108:111]
	v_mfma_f32_16x16x32_bf16 v[18:21], v[222:225], v[18:21], v[34:37]
	v_mfma_f32_16x16x32_bf16 v[124:127], v[218:221], v[120:123], v[68:71]
	v_mfma_f32_16x16x32_bf16 v[120:123], v[226:229], v[120:123], v[18:21]
	v_mfma_f32_16x16x32_bf16 v[18:21], v[214:217], v[230:233], v[38:41]
	v_mfma_f32_16x16x32_bf16 v[108:111], v[218:221], v[234:237], v[18:21]
	v_mfma_f32_16x16x32_bf16 v[18:21], v[222:225], v[230:233], v[42:45]
	v_mfma_f32_16x16x32_bf16 v[104:107], v[226:229], v[234:237], v[18:21]
	v_mfma_f32_16x16x32_bf16 v[18:21], v[214:217], v[238:241], v[46:49]
	v_mfma_f32_16x16x32_bf16 v[92:95], v[218:221], v[242:245], v[18:21]
	v_mfma_f32_16x16x32_bf16 v[18:21], v[222:225], v[238:241], v[50:53]
	v_mfma_f32_16x16x32_bf16 v[88:91], v[226:229], v[242:245], v[18:21]
	v_mfma_f32_16x16x32_bf16 v[18:21], v[214:217], v[246:249], v[54:57]
	v_mfma_f32_16x16x32_bf16 v[72:75], v[218:221], v[250:253], v[18:21]
	v_mfma_f32_16x16x32_bf16 v[18:21], v[222:225], v[246:249], v[58:61]
	v_mfma_f32_16x16x32_bf16 v[68:71], v[226:229], v[250:253], v[18:21]
	s_barrier
	s_add_u32 s0, s50, 0x18000
	s_addc_u32 s1, s51, 0
	s_add_i32 s12, s12, s2
	s_nop 1
	v_lshl_add_u64 v[18:19], s[0:1], 0, v[134:135]
	s_mov_b32 m0, s12
	ds_read_b128 v[40:43], v155 offset:49152
	ds_read_b128 v[44:47], v155 offset:50176
	ds_read_b128 v[230:233], v155 offset:51200
	ds_read_b128 v[234:237], v155 offset:52224
	ds_read_b128 v[238:241], v155 offset:53248
	ds_read_b128 v[242:245], v155 offset:54272
	ds_read_b128 v[246:249], v155 offset:55296
	ds_read_b128 v[250:253], v155 offset:56320
	global_load_lds_dwordx4 v[18:19], off
	s_add_i32 m0, s12, 0x2000
	v_lshl_add_u64 v[18:19], s[0:1], 0, v[138:139]
	s_add_u32 s0, s50, 0x1c000
	s_addc_u32 s1, s51, 0
	s_add_i32 s12, s13, s2
	global_load_lds_dwordx4 v[18:19], off
	s_mov_b32 m0, s12
	v_lshl_add_u64 v[18:19], s[0:1], 0, v[134:135]
	global_load_lds_dwordx4 v[18:19], off
	s_add_i32 m0, s12, 0x2000
	v_lshl_add_u64 v[18:19], s[0:1], 0, v[138:139]
	global_load_lds_dwordx4 v[18:19], off
	s_mov_b32 m0, s33
	v_lshl_add_u64 v[18:19], v[148:149], 0, s[46:47]
	global_load_lds_dwordx4 v[18:19], off
	s_mov_b32 m0, s54
	v_lshl_add_u64 v[18:19], v[144:145], 0, s[46:47]
	global_load_lds_dwordx4 v[18:19], off
	s_waitcnt vmcnt(8) lgkmcnt(0)
	s_barrier
	v_mfma_f32_16x16x32_bf16 v[18:21], v[14:17], v[40:43], v[158:161]
	v_mfma_f32_16x16x32_bf16 v[76:79], v[24:27], v[44:47], v[18:21]
	v_mfma_f32_16x16x32_bf16 v[18:21], v[28:31], v[40:43], v[162:165]
	v_mfma_f32_16x16x32_bf16 v[52:55], v[210:213], v[44:47], v[18:21]
	v_mfma_f32_16x16x32_bf16 v[18:21], v[14:17], v[230:233], v[166:169]
	v_mfma_f32_16x16x32_bf16 v[48:51], v[24:27], v[234:237], v[18:21]
	v_mfma_f32_16x16x32_bf16 v[18:21], v[28:31], v[230:233], v[170:173]
	v_mfma_f32_16x16x32_bf16 v[36:39], v[210:213], v[234:237], v[18:21]
	v_mfma_f32_16x16x32_bf16 v[18:21], v[14:17], v[238:241], v[174:177]
	v_mfma_f32_16x16x32_bf16 v[32:35], v[24:27], v[242:245], v[18:21]
	v_mfma_f32_16x16x32_bf16 v[18:21], v[28:31], v[238:241], v[178:181]
	v_mfma_f32_16x16x32_bf16 v[2:5], v[14:17], v[246:249], v[2:5]
	v_mfma_f32_16x16x32_bf16 v[20:23], v[210:213], v[242:245], v[18:21]
	v_mfma_f32_16x16x32_bf16 v[16:19], v[24:27], v[250:253], v[2:5]
	v_mfma_f32_16x16x32_bf16 v[2:5], v[28:31], v[246:249], v[6:9]
	v_mfma_f32_16x16x32_bf16 v[4:7], v[210:213], v[250:253], v[2:5]
	v_mfma_f32_16x16x32_bf16 v[8:11], v[214:217], v[40:43], v[10:13]
	v_mfma_f32_16x16x32_bf16 v[60:63], v[218:221], v[44:47], v[8:11]
	v_mfma_f32_16x16x32_bf16 v[8:11], v[222:225], v[40:43], v[182:185]
	v_mfma_f32_16x16x32_bf16 v[56:59], v[226:229], v[44:47], v[8:11]
	v_mfma_f32_16x16x32_bf16 v[8:11], v[214:217], v[230:233], v[186:189]
	v_mfma_f32_16x16x32_bf16 v[44:47], v[218:221], v[234:237], v[8:11]
	v_mfma_f32_16x16x32_bf16 v[8:11], v[222:225], v[230:233], v[190:193]
	v_mfma_f32_16x16x32_bf16 v[40:43], v[226:229], v[234:237], v[8:11]
	v_mfma_f32_16x16x32_bf16 v[8:11], v[214:217], v[238:241], v[194:197]
	v_mfma_f32_16x16x32_bf16 v[28:31], v[218:221], v[242:245], v[8:11]
	v_mfma_f32_16x16x32_bf16 v[8:11], v[222:225], v[238:241], v[198:201]
	v_mfma_f32_16x16x32_bf16 v[24:27], v[226:229], v[242:245], v[8:11]
	v_mfma_f32_16x16x32_bf16 v[8:11], v[214:217], v[246:249], v[202:205]
	v_mfma_f32_16x16x32_bf16 v[12:15], v[218:221], v[250:253], v[8:11]
	v_mfma_f32_16x16x32_bf16 v[8:11], v[222:225], v[246:249], v[206:209]
	v_mfma_f32_16x16x32_bf16 v[8:11], v[226:229], v[250:253], v[8:11]
	s_barrier
	s_mov_b32 s22, 2
	s_branch .LBB0_761

.LBB0_762:
	ds_read_b128 v[158:161], v153
	ds_read_b128 v[162:165], v153 offset:1024
	ds_read_b128 v[166:169], v153 offset:2048
	ds_read_b128 v[170:173], v153 offset:3072
	ds_read_b128 v[174:177], v154
	ds_read_b128 v[178:181], v154 offset:1024
	ds_read_b128 v[182:185], v154 offset:2048
	ds_read_b128 v[186:189], v154 offset:3072
	s_add_u32 s12, s65, s30
	s_addc_u32 s13, s66, 0
	s_cmp_eq_u32 s30, s50
	s_cselect_b32 s23, s11, s13
	s_cselect_b32 s22, s10, s12
	s_cselect_b32 s53, s49, s64
	s_cselect_b32 s52, s48, s1
	s_add_i32 s68, s19, 0xc000
	v_lshl_add_u64 v[144:145], v[2:3], 0, s[30:31]
	s_mov_b32 m0, s68
	s_add_i32 s67, s19, 0xe000
	ds_read_b128 v[190:193], v155
	ds_read_b128 v[194:197], v155 offset:1024
	ds_read_b128 v[198:201], v155 offset:2048
	ds_read_b128 v[202:205], v155 offset:3072
	ds_read_b128 v[206:209], v155 offset:4096
	ds_read_b128 v[210:213], v155 offset:5120
	ds_read_b128 v[214:217], v155 offset:6144
	ds_read_b128 v[218:221], v155 offset:7168
	global_load_lds_dwordx4 v[144:145], off
	s_mov_b32 m0, s67
	v_lshl_add_u64 v[144:145], v[148:149], 0, s[30:31]
	global_load_lds_dwordx4 v[144:145], off
	s_waitcnt vmcnt(8) lgkmcnt(0)
	s_barrier
	v_mfma_f32_16x16x32_bf16 v[128:131], v[158:161], v[190:193], v[128:131]
	v_mfma_f32_16x16x32_bf16 v[128:131], v[162:165], v[194:197], v[128:131]
	v_mfma_f32_16x16x32_bf16 v[116:119], v[166:169], v[190:193], v[116:119]
	v_mfma_f32_16x16x32_bf16 v[116:119], v[170:173], v[194:197], v[116:119]
	v_mfma_f32_16x16x32_bf16 v[100:103], v[166:169], v[198:201], v[100:103]
	v_mfma_f32_16x16x32_bf16 v[100:103], v[170:173], v[202:205], v[100:103]
	v_mfma_f32_16x16x32_bf16 v[112:115], v[158:161], v[198:201], v[112:115]
	v_mfma_f32_16x16x32_bf16 v[112:115], v[162:165], v[202:205], v[112:115]
	v_mfma_f32_16x16x32_bf16 v[96:99], v[158:161], v[206:209], v[96:99]
	v_mfma_f32_16x16x32_bf16 v[96:99], v[162:165], v[210:213], v[96:99]
	v_mfma_f32_16x16x32_bf16 v[84:87], v[166:169], v[206:209], v[84:87]
	v_mfma_f32_16x16x32_bf16 v[84:87], v[170:173], v[210:213], v[84:87]
	v_mfma_f32_16x16x32_bf16 v[64:67], v[166:169], v[214:217], v[64:67]
	v_mfma_f32_16x16x32_bf16 v[64:67], v[170:173], v[218:221], v[64:67]
	v_mfma_f32_16x16x32_bf16 v[80:83], v[158:161], v[214:217], v[80:83]
	v_mfma_f32_16x16x32_bf16 v[80:83], v[162:165], v[218:221], v[80:83]
	v_mfma_f32_16x16x32_bf16 v[72:75], v[174:177], v[214:217], v[72:75]
	v_mfma_f32_16x16x32_bf16 v[72:75], v[178:181], v[218:221], v[72:75]
	v_mfma_f32_16x16x32_bf16 v[68:71], v[182:185], v[214:217], v[68:71]
	v_mfma_f32_16x16x32_bf16 v[68:71], v[186:189], v[218:221], v[68:71]
	v_mfma_f32_16x16x32_bf16 v[88:91], v[182:185], v[206:209], v[88:91]
	v_mfma_f32_16x16x32_bf16 v[88:91], v[186:189], v[210:213], v[88:91]
	v_mfma_f32_16x16x32_bf16 v[92:95], v[174:177], v[206:209], v[92:95]
	v_mfma_f32_16x16x32_bf16 v[92:95], v[178:181], v[210:213], v[92:95]
	v_mfma_f32_16x16x32_bf16 v[108:111], v[174:177], v[198:201], v[108:111]
	v_mfma_f32_16x16x32_bf16 v[108:111], v[178:181], v[202:205], v[108:111]
	v_mfma_f32_16x16x32_bf16 v[104:107], v[182:185], v[198:201], v[104:107]
	v_mfma_f32_16x16x32_bf16 v[104:107], v[186:189], v[202:205], v[104:107]
	v_mfma_f32_16x16x32_bf16 v[120:123], v[182:185], v[190:193], v[120:123]
	v_mfma_f32_16x16x32_bf16 v[120:123], v[186:189], v[194:197], v[120:123]
	v_mfma_f32_16x16x32_bf16 v[124:127], v[174:177], v[190:193], v[124:127]
	v_mfma_f32_16x16x32_bf16 v[124:127], v[178:181], v[194:197], v[124:127]
	s_barrier
	s_add_i32 s12, s57, s2
	v_lshl_add_u64 v[144:145], s[52:53], 0, v[134:135]
	s_mov_b32 m0, s12
	ds_read_b128 v[190:193], v155 offset:16384
	ds_read_b128 v[194:197], v155 offset:17408
	ds_read_b128 v[198:201], v155 offset:18432
	ds_read_b128 v[202:205], v155 offset:19456
	ds_read_b128 v[206:209], v155 offset:20480
	ds_read_b128 v[210:213], v155 offset:21504
	ds_read_b128 v[214:217], v155 offset:22528
	ds_read_b128 v[218:221], v155 offset:23552
	global_load_lds_dwordx4 v[144:145], off
	s_add_i32 m0, s12, 0x2000
	s_add_u32 s12, s52, 0x4000
	v_lshl_add_u64 v[144:145], s[52:53], 0, v[138:139]
	s_addc_u32 s13, s53, 0
	s_add_i32 s14, s58, s2
	global_load_lds_dwordx4 v[144:145], off
	v_lshl_add_u64 v[144:145], s[12:13], 0, v[134:135]
	s_mov_b32 m0, s14
	v_lshl_add_u64 v[222:223], s[22:23], 0, v[136:137]
	global_load_lds_dwordx4 v[144:145], off
	s_add_i32 m0, s14, 0x2000
	v_lshl_add_u64 v[144:145], s[12:13], 0, v[138:139]
	global_load_lds_dwordx4 v[144:145], off
	s_mov_b32 m0, s19
	v_lshl_add_u64 v[144:145], s[22:23], 0, v[132:133]
	global_load_lds_dwordx4 v[144:145], off
	s_mov_b32 m0, s20
	s_nop 0
	global_load_lds_dwordx4 v[222:223], off
	s_waitcnt vmcnt(8) lgkmcnt(0)
	s_barrier
	v_mfma_f32_16x16x32_bf16 v[76:79], v[158:161], v[190:193], v[76:79]
	v_mfma_f32_16x16x32_bf16 v[76:79], v[162:165], v[194:197], v[76:79]
	v_mfma_f32_16x16x32_bf16 v[52:55], v[166:169], v[190:193], v[52:55]
	v_mfma_f32_16x16x32_bf16 v[52:55], v[170:173], v[194:197], v[52:55]
	v_mfma_f32_16x16x32_bf16 v[36:39], v[166:169], v[198:201], v[36:39]
	v_mfma_f32_16x16x32_bf16 v[36:39], v[170:173], v[202:205], v[36:39]
	v_mfma_f32_16x16x32_bf16 v[48:51], v[158:161], v[198:201], v[48:51]
	v_mfma_f32_16x16x32_bf16 v[48:51], v[162:165], v[202:205], v[48:51]
	v_mfma_f32_16x16x32_bf16 v[32:35], v[158:161], v[206:209], v[32:35]
	v_mfma_f32_16x16x32_bf16 v[32:35], v[162:165], v[210:213], v[32:35]
	v_mfma_f32_16x16x32_bf16 v[20:23], v[166:169], v[206:209], v[20:23]
	v_mfma_f32_16x16x32_bf16 v[20:23], v[170:173], v[210:213], v[20:23]
	v_mfma_f32_16x16x32_bf16 v[4:7], v[166:169], v[214:217], v[4:7]
	v_mfma_f32_16x16x32_bf16 v[4:7], v[170:173], v[218:221], v[4:7]
	v_mfma_f32_16x16x32_bf16 v[16:19], v[158:161], v[214:217], v[16:19]
	v_mfma_f32_16x16x32_bf16 v[16:19], v[162:165], v[218:221], v[16:19]
	v_mfma_f32_16x16x32_bf16 v[12:15], v[174:177], v[214:217], v[12:15]
	v_mfma_f32_16x16x32_bf16 v[12:15], v[178:181], v[218:221], v[12:15]
	v_mfma_f32_16x16x32_bf16 v[8:11], v[182:185], v[214:217], v[8:11]
	v_mfma_f32_16x16x32_bf16 v[8:11], v[186:189], v[218:221], v[8:11]
	v_mfma_f32_16x16x32_bf16 v[24:27], v[182:185], v[206:209], v[24:27]
	v_mfma_f32_16x16x32_bf16 v[24:27], v[186:189], v[210:213], v[24:27]
	v_mfma_f32_16x16x32_bf16 v[28:31], v[174:177], v[206:209], v[28:31]
	v_mfma_f32_16x16x32_bf16 v[28:31], v[178:181], v[210:213], v[28:31]
	v_mfma_f32_16x16x32_bf16 v[44:47], v[174:177], v[198:201], v[44:47]
	v_mfma_f32_16x16x32_bf16 v[44:47], v[178:181], v[202:205], v[44:47]
	v_mfma_f32_16x16x32_bf16 v[40:43], v[182:185], v[198:201], v[40:43]
	v_mfma_f32_16x16x32_bf16 v[40:43], v[186:189], v[202:205], v[40:43]
	v_mfma_f32_16x16x32_bf16 v[56:59], v[182:185], v[190:193], v[56:59]
	v_mfma_f32_16x16x32_bf16 v[56:59], v[186:189], v[194:197], v[56:59]
	v_mfma_f32_16x16x32_bf16 v[60:63], v[174:177], v[190:193], v[60:63]
	v_mfma_f32_16x16x32_bf16 v[60:63], v[178:181], v[194:197], v[60:63]
	s_barrier
	s_add_i32 s14, 0, 0x18000
	v_add_u32_e32 v1, s14, v151
	s_add_i32 s69, 0, 0x1c000
	ds_read_b128 v[158:161], v1
	ds_read_b128 v[162:165], v1 offset:1024
	ds_read_b128 v[166:169], v1 offset:2048
	ds_read_b128 v[170:173], v1 offset:3072
	v_add_u32_e32 v1, s69, v151
	ds_read_b128 v[174:177], v1
	ds_read_b128 v[178:181], v1 offset:1024
	ds_read_b128 v[182:185], v1 offset:2048
	ds_read_b128 v[186:189], v1 offset:3072
	s_add_u32 s12, s22, 0x2b0000
	s_addc_u32 s13, s23, 0
	s_mov_b32 m0, s21
	v_lshl_add_u64 v[224:225], s[12:13], 0, v[132:133]
	ds_read_b128 v[190:193], v155 offset:32768
	ds_read_b128 v[194:197], v155 offset:33792
	ds_read_b128 v[198:201], v155 offset:34816
	ds_read_b128 v[202:205], v155 offset:35840
	ds_read_b128 v[206:209], v155 offset:36864
	ds_read_b128 v[210:213], v155 offset:37888
	ds_read_b128 v[214:217], v155 offset:38912
	ds_read_b128 v[218:221], v155 offset:39936
	global_load_lds_dwordx4 v[224:225], off
	s_mov_b32 m0, s24
	v_lshl_add_u64 v[224:225], s[12:13], 0, v[136:137]
	global_load_lds_dwordx4 v[224:225], off
	s_waitcnt vmcnt(8) lgkmcnt(0)
	s_barrier
	v_mfma_f32_16x16x32_bf16 v[128:131], v[158:161], v[190:193], v[128:131]
	v_mfma_f32_16x16x32_bf16 v[128:131], v[162:165], v[194:197], v[128:131]
	v_mfma_f32_16x16x32_bf16 v[116:119], v[166:169], v[190:193], v[116:119]
	v_mfma_f32_16x16x32_bf16 v[116:119], v[170:173], v[194:197], v[116:119]
	v_mfma_f32_16x16x32_bf16 v[100:103], v[166:169], v[198:201], v[100:103]
	v_mfma_f32_16x16x32_bf16 v[100:103], v[170:173], v[202:205], v[100:103]
	v_mfma_f32_16x16x32_bf16 v[112:115], v[158:161], v[198:201], v[112:115]
	v_mfma_f32_16x16x32_bf16 v[112:115], v[162:165], v[202:205], v[112:115]
	v_mfma_f32_16x16x32_bf16 v[96:99], v[158:161], v[206:209], v[96:99]
	v_mfma_f32_16x16x32_bf16 v[96:99], v[162:165], v[210:213], v[96:99]
	v_mfma_f32_16x16x32_bf16 v[84:87], v[166:169], v[206:209], v[84:87]
	v_mfma_f32_16x16x32_bf16 v[84:87], v[170:173], v[210:213], v[84:87]
	v_mfma_f32_16x16x32_bf16 v[64:67], v[166:169], v[214:217], v[64:67]
	v_mfma_f32_16x16x32_bf16 v[64:67], v[170:173], v[218:221], v[64:67]
	v_mfma_f32_16x16x32_bf16 v[80:83], v[158:161], v[214:217], v[80:83]
	v_mfma_f32_16x16x32_bf16 v[80:83], v[162:165], v[218:221], v[80:83]
	v_mfma_f32_16x16x32_bf16 v[72:75], v[174:177], v[214:217], v[72:75]
	v_mfma_f32_16x16x32_bf16 v[72:75], v[178:181], v[218:221], v[72:75]
	v_mfma_f32_16x16x32_bf16 v[68:71], v[182:185], v[214:217], v[68:71]
	v_mfma_f32_16x16x32_bf16 v[68:71], v[186:189], v[218:221], v[68:71]
	v_mfma_f32_16x16x32_bf16 v[88:91], v[182:185], v[206:209], v[88:91]
	v_mfma_f32_16x16x32_bf16 v[88:91], v[186:189], v[210:213], v[88:91]
	v_mfma_f32_16x16x32_bf16 v[92:95], v[174:177], v[206:209], v[92:95]
	v_mfma_f32_16x16x32_bf16 v[92:95], v[178:181], v[210:213], v[92:95]
	v_mfma_f32_16x16x32_bf16 v[108:111], v[174:177], v[198:201], v[108:111]
	v_mfma_f32_16x16x32_bf16 v[108:111], v[178:181], v[202:205], v[108:111]
	v_mfma_f32_16x16x32_bf16 v[104:107], v[182:185], v[198:201], v[104:107]
	v_mfma_f32_16x16x32_bf16 v[104:107], v[186:189], v[202:205], v[104:107]
	v_mfma_f32_16x16x32_bf16 v[120:123], v[182:185], v[190:193], v[120:123]
	v_mfma_f32_16x16x32_bf16 v[120:123], v[186:189], v[194:197], v[120:123]
	v_mfma_f32_16x16x32_bf16 v[124:127], v[174:177], v[190:193], v[124:127]
	v_mfma_f32_16x16x32_bf16 v[124:127], v[178:181], v[194:197], v[124:127]
	s_barrier
	s_add_u32 s12, s52, 0x8000
	s_addc_u32 s13, s53, 0
	s_add_i32 s14, s14, s2
	v_lshl_add_u64 v[224:225], s[12:13], 0, v[134:135]
	s_mov_b32 m0, s14
	ds_read_b128 v[190:193], v155 offset:49152
	ds_read_b128 v[194:197], v155 offset:50176
	ds_read_b128 v[198:201], v155 offset:51200
	ds_read_b128 v[202:205], v155 offset:52224
	ds_read_b128 v[206:209], v155 offset:53248
	ds_read_b128 v[210:213], v155 offset:54272
	ds_read_b128 v[214:217], v155 offset:55296
	ds_read_b128 v[218:221], v155 offset:56320
	global_load_lds_dwordx4 v[224:225], off
	s_add_i32 m0, s14, 0x2000
	v_lshl_add_u64 v[224:225], s[12:13], 0, v[138:139]
	s_add_u32 s12, s52, 0xc000
	s_addc_u32 s13, s53, 0
	s_add_i32 s14, s69, s2
	global_load_lds_dwordx4 v[224:225], off
	v_lshl_add_u64 v[224:225], s[12:13], 0, v[134:135]
	s_mov_b32 m0, s14
	v_lshl_add_u64 v[144:145], v[144:145], 0, s[40:41]
	global_load_lds_dwordx4 v[224:225], off
	s_add_i32 m0, s14, 0x2000
	v_lshl_add_u64 v[224:225], s[12:13], 0, v[138:139]
	global_load_lds_dwordx4 v[224:225], off
	s_mov_b32 m0, s33
	s_nop 0
	global_load_lds_dwordx4 v[144:145], off
	s_mov_b32 m0, s54
	v_lshl_add_u64 v[144:145], v[222:223], 0, s[40:41]
	global_load_lds_dwordx4 v[144:145], off
	s_waitcnt vmcnt(8) lgkmcnt(0)
	s_barrier
	v_mfma_f32_16x16x32_bf16 v[76:79], v[158:161], v[190:193], v[76:79]
	v_mfma_f32_16x16x32_bf16 v[76:79], v[162:165], v[194:197], v[76:79]
	v_mfma_f32_16x16x32_bf16 v[52:55], v[166:169], v[190:193], v[52:55]
	v_mfma_f32_16x16x32_bf16 v[52:55], v[170:173], v[194:197], v[52:55]
	v_mfma_f32_16x16x32_bf16 v[36:39], v[166:169], v[198:201], v[36:39]
	v_mfma_f32_16x16x32_bf16 v[36:39], v[170:173], v[202:205], v[36:39]
	v_mfma_f32_16x16x32_bf16 v[48:51], v[158:161], v[198:201], v[48:51]
	v_mfma_f32_16x16x32_bf16 v[48:51], v[162:165], v[202:205], v[48:51]
	v_mfma_f32_16x16x32_bf16 v[32:35], v[158:161], v[206:209], v[32:35]
	v_mfma_f32_16x16x32_bf16 v[32:35], v[162:165], v[210:213], v[32:35]
	v_mfma_f32_16x16x32_bf16 v[20:23], v[166:169], v[206:209], v[20:23]
	v_mfma_f32_16x16x32_bf16 v[20:23], v[170:173], v[210:213], v[20:23]
	v_mfma_f32_16x16x32_bf16 v[4:7], v[166:169], v[214:217], v[4:7]
	v_mfma_f32_16x16x32_bf16 v[4:7], v[170:173], v[218:221], v[4:7]
	v_mfma_f32_16x16x32_bf16 v[16:19], v[158:161], v[214:217], v[16:19]
	v_mfma_f32_16x16x32_bf16 v[16:19], v[162:165], v[218:221], v[16:19]
	v_mfma_f32_16x16x32_bf16 v[12:15], v[174:177], v[214:217], v[12:15]
	v_mfma_f32_16x16x32_bf16 v[12:15], v[178:181], v[218:221], v[12:15]
	v_mfma_f32_16x16x32_bf16 v[8:11], v[182:185], v[214:217], v[8:11]
	v_mfma_f32_16x16x32_bf16 v[8:11], v[186:189], v[218:221], v[8:11]
	v_mfma_f32_16x16x32_bf16 v[24:27], v[182:185], v[206:209], v[24:27]
	v_mfma_f32_16x16x32_bf16 v[24:27], v[186:189], v[210:213], v[24:27]
	v_mfma_f32_16x16x32_bf16 v[28:31], v[174:177], v[206:209], v[28:31]
	v_mfma_f32_16x16x32_bf16 v[28:31], v[178:181], v[210:213], v[28:31]
	v_mfma_f32_16x16x32_bf16 v[44:47], v[174:177], v[198:201], v[44:47]
	v_mfma_f32_16x16x32_bf16 v[44:47], v[178:181], v[202:205], v[44:47]
	v_mfma_f32_16x16x32_bf16 v[40:43], v[182:185], v[198:201], v[40:43]
	v_mfma_f32_16x16x32_bf16 v[40:43], v[186:189], v[202:205], v[40:43]
	v_mfma_f32_16x16x32_bf16 v[56:59], v[182:185], v[190:193], v[56:59]
	v_mfma_f32_16x16x32_bf16 v[56:59], v[186:189], v[194:197], v[56:59]
	v_mfma_f32_16x16x32_bf16 v[60:63], v[174:177], v[190:193], v[60:63]
	v_mfma_f32_16x16x32_bf16 v[60:63], v[178:181], v[194:197], v[60:63]
	s_barrier
	s_add_i32 s0, s0, 2
	s_add_u32 s1, s1, 0x10000
	s_addc_u32 s64, s64, 0
	s_add_u32 s65, s65, 0x100
	s_addc_u32 s66, s66, 0
	s_add_u32 s50, s50, 0xffffff00
	s_addc_u32 s51, s51, -1
	v_lshl_add_u64 v[2:3], v[2:3], 0, s[44:45]
	s_cmpk_gt_u32 s0, 0xa9
	v_lshl_add_u64 v[148:149], v[148:149], 0, s[44:45]
	s_cbranch_scc0 .LBB0_762
	s_and_b64 vcc, exec, s[42:43]
	s_cbranch_vccz .LBB0_765
	s_barrier

.LBB0_797:
	s_cmp_lg_u32 s67, 0
	s_mov_b32 s22, 0
	s_cbranch_scc0 .LBB0_799
	ds_read_b128 v[2:5], v155
	ds_read_b128 v[6:9], v155 offset:1024
	ds_read_b128 v[10:13], v155 offset:2048
	ds_read_b128 v[14:17], v155 offset:3072
	ds_read_b128 v[18:21], v156
	ds_read_b128 v[22:25], v156 offset:1024
	ds_read_b128 v[26:29], v156 offset:2048
	ds_read_b128 v[30:33], v156 offset:3072
	s_add_u32 s0, s56, 0x10000
	s_addc_u32 s1, s57, 0
	ds_read_b128 v[34:37], v157
	ds_read_b128 v[38:41], v157 offset:1024
	ds_read_b128 v[42:45], v157 offset:2048
	ds_read_b128 v[46:49], v157 offset:3072
	ds_read_b128 v[50:53], v157 offset:4096
	ds_read_b128 v[54:57], v157 offset:5120
	ds_read_b128 v[58:61], v157 offset:6144
	ds_read_b128 v[62:65], v157 offset:7168
	s_waitcnt vmcnt(16) lgkmcnt(0)
	s_barrier
	v_mfma_f32_16x16x32_bf16 v[86:89], v[10:13], v[50:53], 0
	v_mfma_f32_16x16x32_bf16 v[92:95], v[14:17], v[54:57], v[86:89]
	v_mfma_f32_16x16x32_bf16 v[86:89], v[2:5], v[58:61], 0
	v_mfma_f32_16x16x32_bf16 v[66:69], v[2:5], v[34:37], 0
	v_mfma_f32_16x16x32_bf16 v[70:73], v[10:13], v[34:37], 0
	v_mfma_f32_16x16x32_bf16 v[74:77], v[2:5], v[42:45], 0
	v_mfma_f32_16x16x32_bf16 v[78:81], v[10:13], v[42:45], 0
	v_mfma_f32_16x16x32_bf16 v[82:85], v[2:5], v[50:53], 0
	v_mfma_f32_16x16x32_bf16 v[96:99], v[6:9], v[62:65], v[86:89]
	v_mfma_f32_16x16x32_bf16 v[86:89], v[10:13], v[58:61], 0
	v_mfma_f32_16x16x32_bf16 v[66:69], v[6:9], v[38:41], v[66:69]
	v_mfma_f32_16x16x32_bf16 v[70:73], v[14:17], v[38:41], v[70:73]
	v_mfma_f32_16x16x32_bf16 v[74:77], v[6:9], v[46:49], v[74:77]
	v_mfma_f32_16x16x32_bf16 v[78:81], v[14:17], v[46:49], v[78:81]
	v_mfma_f32_16x16x32_bf16 v[82:85], v[6:9], v[54:57], v[82:85]
	v_mfma_f32_16x16x32_bf16 v[108:111], v[14:17], v[62:65], v[86:89]
	v_mfma_f32_16x16x32_bf16 v[86:89], v[18:21], v[34:37], 0
	v_mfma_f32_16x16x32_bf16 v[34:37], v[26:29], v[34:37], 0
	v_mfma_f32_16x16x32_bf16 v[112:115], v[22:25], v[38:41], v[86:89]
	v_mfma_f32_16x16x32_bf16 v[34:37], v[30:33], v[38:41], v[34:37]
	v_mfma_f32_16x16x32_bf16 v[38:41], v[18:21], v[42:45], 0
	v_mfma_f32_16x16x32_bf16 v[42:45], v[26:29], v[42:45], 0
	v_mfma_f32_16x16x32_bf16 v[38:41], v[22:25], v[46:49], v[38:41]
	v_mfma_f32_16x16x32_bf16 v[42:45], v[30:33], v[46:49], v[42:45]
	v_mfma_f32_16x16x32_bf16 v[46:49], v[18:21], v[50:53], 0
	v_mfma_f32_16x16x32_bf16 v[50:53], v[26:29], v[50:53], 0
	v_mfma_f32_16x16x32_bf16 v[46:49], v[22:25], v[54:57], v[46:49]
	v_mfma_f32_16x16x32_bf16 v[50:53], v[30:33], v[54:57], v[50:53]
	v_mfma_f32_16x16x32_bf16 v[54:57], v[18:21], v[58:61], 0
	v_mfma_f32_16x16x32_bf16 v[58:61], v[26:29], v[58:61], 0
	v_mfma_f32_16x16x32_bf16 v[54:57], v[22:25], v[62:65], v[54:57]
	v_mfma_f32_16x16x32_bf16 v[58:61], v[30:33], v[62:65], v[58:61]
	s_barrier
	s_add_i32 s12, s60, s2
	v_lshl_add_u64 v[90:91], s[0:1], 0, v[134:135]
	s_mov_b32 m0, s12
	ds_read_b128 v[62:65], v157 offset:16384
	ds_read_b128 v[86:89], v157 offset:17408
	ds_read_b128 v[100:103], v157 offset:18432
	ds_read_b128 v[104:107], v157 offset:19456
	ds_read_b128 v[116:119], v157 offset:20480
	ds_read_b128 v[120:123], v157 offset:21504
	ds_read_b128 v[124:127], v157 offset:22528
	ds_read_b128 v[128:131], v157 offset:23552
	global_load_lds_dwordx4 v[90:91], off
	s_add_i32 m0, s12, 0x2000
	v_lshl_add_u64 v[90:91], s[0:1], 0, v[138:139]
	s_add_u32 s0, s56, 0x14000
	s_addc_u32 s1, s57, 0
	s_add_i32 s12, s61, s2
	global_load_lds_dwordx4 v[90:91], off
	v_lshl_add_u64 v[90:91], s[0:1], 0, v[134:135]
	s_mov_b32 m0, s12
	v_lshl_add_u64 v[148:149], s[8:9], 0, v[132:133]
	global_load_lds_dwordx4 v[90:91], off
	v_lshl_add_u64 v[90:91], s[0:1], 0, v[138:139]
	s_add_i32 m0, s12, 0x2000
	v_lshl_add_u64 v[144:145], s[8:9], 0, v[136:137]
	global_load_lds_dwordx4 v[90:91], off
	s_mov_b32 m0, s33
	v_lshl_add_u64 v[90:91], v[148:149], 0, s[40:41]
	global_load_lds_dwordx4 v[90:91], off
	s_mov_b32 m0, s53
	v_lshl_add_u64 v[90:91], v[144:145], 0, s[40:41]
	global_load_lds_dwordx4 v[90:91], off
	s_waitcnt vmcnt(16) lgkmcnt(0)
	s_barrier
	v_mfma_f32_16x16x32_bf16 v[158:161], v[2:5], v[62:65], 0
	v_mfma_f32_16x16x32_bf16 v[166:169], v[2:5], v[100:103], 0
	v_mfma_f32_16x16x32_bf16 v[174:177], v[2:5], v[116:119], 0
	v_mfma_f32_16x16x32_bf16 v[2:5], v[2:5], v[124:127], 0
	v_mfma_f32_16x16x32_bf16 v[158:161], v[6:9], v[86:89], v[158:161]
	v_mfma_f32_16x16x32_bf16 v[162:165], v[10:13], v[62:65], 0
	v_mfma_f32_16x16x32_bf16 v[166:169], v[6:9], v[104:107], v[166:169]
	v_mfma_f32_16x16x32_bf16 v[170:173], v[10:13], v[100:103], 0
	v_mfma_f32_16x16x32_bf16 v[174:177], v[6:9], v[120:123], v[174:177]
	v_mfma_f32_16x16x32_bf16 v[178:181], v[10:13], v[116:119], 0
	v_mfma_f32_16x16x32_bf16 v[2:5], v[6:9], v[128:131], v[2:5]
	v_mfma_f32_16x16x32_bf16 v[6:9], v[10:13], v[124:127], 0
	v_mfma_f32_16x16x32_bf16 v[162:165], v[14:17], v[86:89], v[162:165]
	v_mfma_f32_16x16x32_bf16 v[170:173], v[14:17], v[104:107], v[170:173]
	v_mfma_f32_16x16x32_bf16 v[178:181], v[14:17], v[120:123], v[178:181]
	v_mfma_f32_16x16x32_bf16 v[12:15], v[14:17], v[128:131], v[6:9]
	v_mfma_f32_16x16x32_bf16 v[6:9], v[18:21], v[62:65], 0
	v_mfma_f32_16x16x32_bf16 v[182:185], v[22:25], v[86:89], v[6:9]
	v_mfma_f32_16x16x32_bf16 v[6:9], v[26:29], v[62:65], 0
	v_mfma_f32_16x16x32_bf16 v[186:189], v[30:33], v[86:89], v[6:9]
	v_mfma_f32_16x16x32_bf16 v[6:9], v[18:21], v[100:103], 0
	v_mfma_f32_16x16x32_bf16 v[190:193], v[22:25], v[104:107], v[6:9]
	v_mfma_f32_16x16x32_bf16 v[6:9], v[26:29], v[100:103], 0
	v_mfma_f32_16x16x32_bf16 v[194:197], v[30:33], v[104:107], v[6:9]
	v_mfma_f32_16x16x32_bf16 v[6:9], v[18:21], v[116:119], 0
	v_mfma_f32_16x16x32_bf16 v[198:201], v[22:25], v[120:123], v[6:9]
	v_mfma_f32_16x16x32_bf16 v[6:9], v[26:29], v[116:119], 0
	v_mfma_f32_16x16x32_bf16 v[202:205], v[30:33], v[120:123], v[6:9]
	v_mfma_f32_16x16x32_bf16 v[6:9], v[18:21], v[124:127], 0
	v_mfma_f32_16x16x32_bf16 v[16:19], v[22:25], v[128:131], v[6:9]
	v_mfma_f32_16x16x32_bf16 v[6:9], v[26:29], v[124:127], 0
	v_mfma_f32_16x16x32_bf16 v[206:209], v[30:33], v[128:131], v[6:9]
	s_barrier
	s_add_i32 s12, 0, 0x18000
	v_add_u32_e32 v1, s12, v152
	s_add_i32 s13, 0, 0x1c000
	s_nop 1
	ds_read_b128 v[6:9], v1
	ds_read_b128 v[28:31], v1 offset:1024
	ds_read_b128 v[62:65], v1 offset:2048
	ds_read_b128 v[210:213], v1 offset:3072
	v_add_u32_e32 v1, s13, v152
	ds_read_b128 v[214:217], v1
	ds_read_b128 v[218:221], v1 offset:1024
	ds_read_b128 v[222:225], v1 offset:2048
	ds_read_b128 v[226:229], v1 offset:3072
	s_add_u32 s0, s8, 0x100100
	s_addc_u32 s1, s9, 0
	s_mov_b32 m0, s55
	v_lshl_add_u64 v[10:11], s[0:1], 0, v[132:133]
	ds_read_b128 v[20:23], v157 offset:32768
	ds_read_b128 v[24:27], v157 offset:33792
	ds_read_b128 v[230:233], v157 offset:34816
	ds_read_b128 v[234:237], v157 offset:35840
	ds_read_b128 v[238:241], v157 offset:36864
	ds_read_b128 v[242:245], v157 offset:37888
	ds_read_b128 v[246:249], v157 offset:38912
	ds_read_b128 v[250:253], v157 offset:39936
	global_load_lds_dwordx4 v[10:11], off
	s_mov_b32 m0, s58
	v_lshl_add_u64 v[10:11], s[0:1], 0, v[136:137]
	global_load_lds_dwordx4 v[10:11], off
	s_waitcnt vmcnt(16) lgkmcnt(0)
	s_barrier
	v_mfma_f32_16x16x32_bf16 v[66:69], v[6:9], v[20:23], v[66:69]
	v_mfma_f32_16x16x32_bf16 v[120:123], v[28:31], v[24:27], v[66:69]
	v_mfma_f32_16x16x32_bf16 v[66:69], v[62:65], v[20:23], v[70:73]
	v_mfma_f32_16x16x32_bf16 v[116:119], v[210:213], v[24:27], v[66:69]
	v_mfma_f32_16x16x32_bf16 v[66:69], v[6:9], v[230:233], v[74:77]
	v_mfma_f32_16x16x32_bf16 v[104:107], v[28:31], v[234:237], v[66:69]
	v_mfma_f32_16x16x32_bf16 v[66:69], v[62:65], v[230:233], v[78:81]
	v_mfma_f32_16x16x32_bf16 v[100:103], v[210:213], v[234:237], v[66:69]
	v_mfma_f32_16x16x32_bf16 v[66:69], v[6:9], v[238:241], v[82:85]
	v_mfma_f32_16x16x32_bf16 v[88:91], v[28:31], v[242:245], v[66:69]
	v_mfma_f32_16x16x32_bf16 v[66:69], v[62:65], v[238:241], v[92:95]
	v_mfma_f32_16x16x32_bf16 v[84:87], v[210:213], v[242:245], v[66:69]
	v_mfma_f32_16x16x32_bf16 v[66:69], v[6:9], v[246:249], v[96:99]
	v_mfma_f32_16x16x32_bf16 v[72:75], v[28:31], v[250:253], v[66:69]
	v_mfma_f32_16x16x32_bf16 v[66:69], v[62:65], v[246:249], v[108:111]
	v_mfma_f32_16x16x32_bf16 v[68:71], v[210:213], v[250:253], v[66:69]
	v_mfma_f32_16x16x32_bf16 v[76:79], v[214:217], v[20:23], v[112:115]
	v_mfma_f32_16x16x32_bf16 v[20:23], v[222:225], v[20:23], v[34:37]
	v_mfma_f32_16x16x32_bf16 v[124:127], v[226:229], v[24:27], v[20:23]
	v_mfma_f32_16x16x32_bf16 v[20:23], v[214:217], v[230:233], v[38:41]
	v_mfma_f32_16x16x32_bf16 v[112:115], v[218:221], v[234:237], v[20:23]
	v_mfma_f32_16x16x32_bf16 v[20:23], v[222:225], v[230:233], v[42:45]
	v_mfma_f32_16x16x32_bf16 v[108:111], v[226:229], v[234:237], v[20:23]
	v_mfma_f32_16x16x32_bf16 v[20:23], v[214:217], v[238:241], v[46:49]
	v_mfma_f32_16x16x32_bf16 v[96:99], v[218:221], v[242:245], v[20:23]
	v_mfma_f32_16x16x32_bf16 v[20:23], v[222:225], v[238:241], v[50:53]
	v_mfma_f32_16x16x32_bf16 v[92:95], v[226:229], v[242:245], v[20:23]
	v_mfma_f32_16x16x32_bf16 v[20:23], v[214:217], v[246:249], v[54:57]
	v_mfma_f32_16x16x32_bf16 v[80:83], v[218:221], v[250:253], v[20:23]
	v_mfma_f32_16x16x32_bf16 v[20:23], v[222:225], v[246:249], v[58:61]
	v_mfma_f32_16x16x32_bf16 v[128:131], v[218:221], v[24:27], v[76:79]
	v_mfma_f32_16x16x32_bf16 v[76:79], v[226:229], v[250:253], v[20:23]
	s_barrier
	s_add_u32 s0, s56, 0x18000
	s_addc_u32 s1, s57, 0
	s_add_i32 s12, s12, s2
	v_lshl_add_u64 v[10:11], s[0:1], 0, v[134:135]
	s_mov_b32 m0, s12
	ds_read_b128 v[32:35], v157 offset:49152
	ds_read_b128 v[44:47], v157 offset:50176
	ds_read_b128 v[230:233], v157 offset:51200
	ds_read_b128 v[234:237], v157 offset:52224
	ds_read_b128 v[238:241], v157 offset:53248
	ds_read_b128 v[242:245], v157 offset:54272
	ds_read_b128 v[246:249], v157 offset:55296
	ds_read_b128 v[250:253], v157 offset:56320
	global_load_lds_dwordx4 v[10:11], off
	s_add_i32 m0, s12, 0x2000
	v_lshl_add_u64 v[10:11], s[0:1], 0, v[138:139]
	s_add_u32 s0, s56, 0x1c000
	s_addc_u32 s1, s57, 0
	s_add_i32 s12, s13, s2
	global_load_lds_dwordx4 v[10:11], off
	s_mov_b32 m0, s12
	v_lshl_add_u64 v[10:11], s[0:1], 0, v[134:135]
	global_load_lds_dwordx4 v[10:11], off
	s_add_i32 m0, s12, 0x2000
	v_lshl_add_u64 v[10:11], s[0:1], 0, v[138:139]
	global_load_lds_dwordx4 v[10:11], off
	s_mov_b32 m0, s16
	v_lshl_add_u64 v[10:11], v[148:149], 0, s[42:43]
	global_load_lds_dwordx4 v[10:11], off
	s_mov_b32 m0, s59
	v_lshl_add_u64 v[10:11], v[144:145], 0, s[42:43]
	global_load_lds_dwordx4 v[10:11], off
	s_waitcnt vmcnt(8) lgkmcnt(0)
	s_barrier
	v_mfma_f32_16x16x32_bf16 v[20:23], v[6:9], v[32:35], v[158:161]
	v_mfma_f32_16x16x32_bf16 v[56:59], v[28:31], v[44:47], v[20:23]
	v_mfma_f32_16x16x32_bf16 v[20:23], v[62:65], v[32:35], v[162:165]
	v_mfma_f32_16x16x32_bf16 v[52:55], v[210:213], v[44:47], v[20:23]
	v_mfma_f32_16x16x32_bf16 v[20:23], v[6:9], v[230:233], v[166:169]
	v_mfma_f32_16x16x32_bf16 v[40:43], v[28:31], v[234:237], v[20:23]
	v_mfma_f32_16x16x32_bf16 v[20:23], v[62:65], v[230:233], v[170:173]
	v_mfma_f32_16x16x32_bf16 v[36:39], v[210:213], v[234:237], v[20:23]
	v_mfma_f32_16x16x32_bf16 v[20:23], v[6:9], v[238:241], v[174:177]
	v_mfma_f32_16x16x32_bf16 v[2:5], v[6:9], v[246:249], v[2:5]
	v_mfma_f32_16x16x32_bf16 v[24:27], v[28:31], v[242:245], v[20:23]
	v_mfma_f32_16x16x32_bf16 v[20:23], v[62:65], v[238:241], v[178:181]
	v_mfma_f32_16x16x32_bf16 v[8:11], v[28:31], v[250:253], v[2:5]
	v_mfma_f32_16x16x32_bf16 v[2:5], v[62:65], v[246:249], v[12:15]
	v_mfma_f32_16x16x32_bf16 v[20:23], v[210:213], v[242:245], v[20:23]
	v_mfma_f32_16x16x32_bf16 v[4:7], v[210:213], v[250:253], v[2:5]
	v_mfma_f32_16x16x32_bf16 v[12:15], v[214:217], v[32:35], v[182:185]
	v_mfma_f32_16x16x32_bf16 v[64:67], v[218:221], v[44:47], v[12:15]
	v_mfma_f32_16x16x32_bf16 v[12:15], v[222:225], v[32:35], v[186:189]
	v_mfma_f32_16x16x32_bf16 v[60:63], v[226:229], v[44:47], v[12:15]
	v_mfma_f32_16x16x32_bf16 v[12:15], v[214:217], v[230:233], v[190:193]
	v_mfma_f32_16x16x32_bf16 v[48:51], v[218:221], v[234:237], v[12:15]
	v_mfma_f32_16x16x32_bf16 v[12:15], v[222:225], v[230:233], v[194:197]
	v_mfma_f32_16x16x32_bf16 v[44:47], v[226:229], v[234:237], v[12:15]
	v_mfma_f32_16x16x32_bf16 v[12:15], v[214:217], v[238:241], v[198:201]
	v_mfma_f32_16x16x32_bf16 v[32:35], v[218:221], v[242:245], v[12:15]
	v_mfma_f32_16x16x32_bf16 v[12:15], v[222:225], v[238:241], v[202:205]
	v_mfma_f32_16x16x32_bf16 v[28:31], v[226:229], v[242:245], v[12:15]
	v_mfma_f32_16x16x32_bf16 v[12:15], v[214:217], v[246:249], v[16:19]
	v_mfma_f32_16x16x32_bf16 v[16:19], v[218:221], v[250:253], v[12:15]
	v_mfma_f32_16x16x32_bf16 v[12:15], v[222:225], v[246:249], v[206:209]
	v_mfma_f32_16x16x32_bf16 v[12:15], v[226:229], v[250:253], v[12:15]
	s_barrier
	s_mov_b32 s22, 2
	s_branch .LBB0_800

.LBB0_801:
	ds_read_b128 v[158:161], v155
	ds_read_b128 v[162:165], v155 offset:1024
	ds_read_b128 v[166:169], v155 offset:2048
	ds_read_b128 v[170:173], v155 offset:3072
	ds_read_b128 v[174:177], v156
	ds_read_b128 v[178:181], v156 offset:1024
	ds_read_b128 v[182:185], v156 offset:2048
	ds_read_b128 v[186:189], v156 offset:3072
	s_add_u32 s12, s72, s36
	s_addc_u32 s13, s73, 0
	s_cmp_eq_u32 s36, s8
	s_cselect_b32 s23, s0, s13
	s_cselect_b32 s22, s1, s12
	s_cselect_b32 s57, s45, s71
	s_cselect_b32 s56, s68, s70
	s_add_i32 s75, s33, 0xc000
	v_lshl_add_u64 v[144:145], v[2:3], 0, s[36:37]
	s_mov_b32 m0, s75
	s_add_i32 s74, s33, 0xe000
	ds_read_b128 v[190:193], v157
	ds_read_b128 v[194:197], v157 offset:1024
	ds_read_b128 v[198:201], v157 offset:2048
	ds_read_b128 v[202:205], v157 offset:3072
	ds_read_b128 v[206:209], v157 offset:4096
	ds_read_b128 v[210:213], v157 offset:5120
	ds_read_b128 v[214:217], v157 offset:6144
	ds_read_b128 v[218:221], v157 offset:7168
	global_load_lds_dwordx4 v[144:145], off
	s_mov_b32 m0, s74
	v_lshl_add_u64 v[144:145], v[148:149], 0, s[36:37]
	global_load_lds_dwordx4 v[144:145], off
	s_waitcnt vmcnt(8) lgkmcnt(0)
	s_barrier
	v_mfma_f32_16x16x32_bf16 v[120:123], v[158:161], v[190:193], v[120:123]
	v_mfma_f32_16x16x32_bf16 v[120:123], v[162:165], v[194:197], v[120:123]
	v_mfma_f32_16x16x32_bf16 v[116:119], v[166:169], v[190:193], v[116:119]
	v_mfma_f32_16x16x32_bf16 v[116:119], v[170:173], v[194:197], v[116:119]
	v_mfma_f32_16x16x32_bf16 v[100:103], v[166:169], v[198:201], v[100:103]
	v_mfma_f32_16x16x32_bf16 v[100:103], v[170:173], v[202:205], v[100:103]
	v_mfma_f32_16x16x32_bf16 v[104:107], v[158:161], v[198:201], v[104:107]
	v_mfma_f32_16x16x32_bf16 v[104:107], v[162:165], v[202:205], v[104:107]
	v_mfma_f32_16x16x32_bf16 v[88:91], v[158:161], v[206:209], v[88:91]
	v_mfma_f32_16x16x32_bf16 v[88:91], v[162:165], v[210:213], v[88:91]
	v_mfma_f32_16x16x32_bf16 v[84:87], v[166:169], v[206:209], v[84:87]
	v_mfma_f32_16x16x32_bf16 v[84:87], v[170:173], v[210:213], v[84:87]
	v_mfma_f32_16x16x32_bf16 v[68:71], v[166:169], v[214:217], v[68:71]
	v_mfma_f32_16x16x32_bf16 v[68:71], v[170:173], v[218:221], v[68:71]
	v_mfma_f32_16x16x32_bf16 v[72:75], v[158:161], v[214:217], v[72:75]
	v_mfma_f32_16x16x32_bf16 v[72:75], v[162:165], v[218:221], v[72:75]
	v_mfma_f32_16x16x32_bf16 v[80:83], v[174:177], v[214:217], v[80:83]
	v_mfma_f32_16x16x32_bf16 v[80:83], v[178:181], v[218:221], v[80:83]
	v_mfma_f32_16x16x32_bf16 v[76:79], v[182:185], v[214:217], v[76:79]
	v_mfma_f32_16x16x32_bf16 v[76:79], v[186:189], v[218:221], v[76:79]
	v_mfma_f32_16x16x32_bf16 v[92:95], v[182:185], v[206:209], v[92:95]
	v_mfma_f32_16x16x32_bf16 v[92:95], v[186:189], v[210:213], v[92:95]
	v_mfma_f32_16x16x32_bf16 v[96:99], v[174:177], v[206:209], v[96:99]
	v_mfma_f32_16x16x32_bf16 v[96:99], v[178:181], v[210:213], v[96:99]
	v_mfma_f32_16x16x32_bf16 v[112:115], v[174:177], v[198:201], v[112:115]
	v_mfma_f32_16x16x32_bf16 v[112:115], v[178:181], v[202:205], v[112:115]
	v_mfma_f32_16x16x32_bf16 v[108:111], v[182:185], v[198:201], v[108:111]
	v_mfma_f32_16x16x32_bf16 v[108:111], v[186:189], v[202:205], v[108:111]
	v_mfma_f32_16x16x32_bf16 v[124:127], v[182:185], v[190:193], v[124:127]
	v_mfma_f32_16x16x32_bf16 v[124:127], v[186:189], v[194:197], v[124:127]
	v_mfma_f32_16x16x32_bf16 v[128:131], v[174:177], v[190:193], v[128:131]
	v_mfma_f32_16x16x32_bf16 v[128:131], v[178:181], v[194:197], v[128:131]
	s_barrier
	s_add_i32 s12, s60, s2
	v_lshl_add_u64 v[144:145], s[56:57], 0, v[134:135]
	s_mov_b32 m0, s12
	ds_read_b128 v[190:193], v157 offset:16384
	ds_read_b128 v[194:197], v157 offset:17408
	ds_read_b128 v[198:201], v157 offset:18432
	ds_read_b128 v[202:205], v157 offset:19456
	ds_read_b128 v[206:209], v157 offset:20480
	ds_read_b128 v[210:213], v157 offset:21504
	ds_read_b128 v[214:217], v157 offset:22528
	ds_read_b128 v[218:221], v157 offset:23552
	global_load_lds_dwordx4 v[144:145], off
	s_add_i32 m0, s12, 0x2000
	s_add_u32 s12, s56, 0x4000
	v_lshl_add_u64 v[144:145], s[56:57], 0, v[138:139]
	s_addc_u32 s13, s57, 0
	s_add_i32 s14, s61, s2
	global_load_lds_dwordx4 v[144:145], off
	v_lshl_add_u64 v[144:145], s[12:13], 0, v[134:135]
	s_mov_b32 m0, s14
	v_lshl_add_u64 v[222:223], s[22:23], 0, v[136:137]
	global_load_lds_dwordx4 v[144:145], off
	s_add_i32 m0, s14, 0x2000
	v_lshl_add_u64 v[144:145], s[12:13], 0, v[138:139]
	global_load_lds_dwordx4 v[144:145], off
	s_mov_b32 m0, s33
	v_lshl_add_u64 v[144:145], s[22:23], 0, v[132:133]
	global_load_lds_dwordx4 v[144:145], off
	s_mov_b32 m0, s53
	s_nop 0
	global_load_lds_dwordx4 v[222:223], off
	s_waitcnt vmcnt(8) lgkmcnt(0)
	s_barrier
	v_mfma_f32_16x16x32_bf16 v[56:59], v[158:161], v[190:193], v[56:59]
	v_mfma_f32_16x16x32_bf16 v[56:59], v[162:165], v[194:197], v[56:59]
	v_mfma_f32_16x16x32_bf16 v[52:55], v[166:169], v[190:193], v[52:55]
	v_mfma_f32_16x16x32_bf16 v[52:55], v[170:173], v[194:197], v[52:55]
	v_mfma_f32_16x16x32_bf16 v[36:39], v[166:169], v[198:201], v[36:39]
	v_mfma_f32_16x16x32_bf16 v[36:39], v[170:173], v[202:205], v[36:39]
	v_mfma_f32_16x16x32_bf16 v[40:43], v[158:161], v[198:201], v[40:43]
	v_mfma_f32_16x16x32_bf16 v[40:43], v[162:165], v[202:205], v[40:43]
	v_mfma_f32_16x16x32_bf16 v[24:27], v[158:161], v[206:209], v[24:27]
	v_mfma_f32_16x16x32_bf16 v[24:27], v[162:165], v[210:213], v[24:27]
	v_mfma_f32_16x16x32_bf16 v[20:23], v[166:169], v[206:209], v[20:23]
	v_mfma_f32_16x16x32_bf16 v[20:23], v[170:173], v[210:213], v[20:23]
	v_mfma_f32_16x16x32_bf16 v[4:7], v[166:169], v[214:217], v[4:7]
	v_mfma_f32_16x16x32_bf16 v[4:7], v[170:173], v[218:221], v[4:7]
	v_mfma_f32_16x16x32_bf16 v[8:11], v[158:161], v[214:217], v[8:11]
	v_mfma_f32_16x16x32_bf16 v[8:11], v[162:165], v[218:221], v[8:11]
	v_mfma_f32_16x16x32_bf16 v[16:19], v[174:177], v[214:217], v[16:19]
	v_mfma_f32_16x16x32_bf16 v[16:19], v[178:181], v[218:221], v[16:19]
	v_mfma_f32_16x16x32_bf16 v[12:15], v[182:185], v[214:217], v[12:15]
	v_mfma_f32_16x16x32_bf16 v[12:15], v[186:189], v[218:221], v[12:15]
	v_mfma_f32_16x16x32_bf16 v[28:31], v[182:185], v[206:209], v[28:31]
	v_mfma_f32_16x16x32_bf16 v[28:31], v[186:189], v[210:213], v[28:31]
	v_mfma_f32_16x16x32_bf16 v[32:35], v[174:177], v[206:209], v[32:35]
	v_mfma_f32_16x16x32_bf16 v[32:35], v[178:181], v[210:213], v[32:35]
	v_mfma_f32_16x16x32_bf16 v[48:51], v[174:177], v[198:201], v[48:51]
	v_mfma_f32_16x16x32_bf16 v[48:51], v[178:181], v[202:205], v[48:51]
	v_mfma_f32_16x16x32_bf16 v[44:47], v[182:185], v[198:201], v[44:47]
	v_mfma_f32_16x16x32_bf16 v[44:47], v[186:189], v[202:205], v[44:47]
	v_mfma_f32_16x16x32_bf16 v[60:63], v[182:185], v[190:193], v[60:63]
	v_mfma_f32_16x16x32_bf16 v[60:63], v[186:189], v[194:197], v[60:63]
	v_mfma_f32_16x16x32_bf16 v[64:67], v[174:177], v[190:193], v[64:67]
	v_mfma_f32_16x16x32_bf16 v[64:67], v[178:181], v[194:197], v[64:67]
	s_barrier
	s_add_i32 s14, 0, 0x18000
	v_add_u32_e32 v1, s14, v152
	s_add_i32 s76, 0, 0x1c000
	ds_read_b128 v[158:161], v1
	ds_read_b128 v[162:165], v1 offset:1024
	ds_read_b128 v[166:169], v1 offset:2048
	ds_read_b128 v[170:173], v1 offset:3072
	v_add_u32_e32 v1, s76, v152
	ds_read_b128 v[174:177], v1
	ds_read_b128 v[178:181], v1 offset:1024
	ds_read_b128 v[182:185], v1 offset:2048
	ds_read_b128 v[186:189], v1 offset:3072
	s_add_u32 s12, s22, 0x100000
	s_addc_u32 s13, s23, 0
	s_mov_b32 m0, s55
	v_lshl_add_u64 v[224:225], s[12:13], 0, v[132:133]
	ds_read_b128 v[190:193], v157 offset:32768
	ds_read_b128 v[194:197], v157 offset:33792
	ds_read_b128 v[198:201], v157 offset:34816
	ds_read_b128 v[202:205], v157 offset:35840
	ds_read_b128 v[206:209], v157 offset:36864
	ds_read_b128 v[210:213], v157 offset:37888
	ds_read_b128 v[214:217], v157 offset:38912
	ds_read_b128 v[218:221], v157 offset:39936
	global_load_lds_dwordx4 v[224:225], off
	s_mov_b32 m0, s58
	v_lshl_add_u64 v[224:225], s[12:13], 0, v[136:137]
	global_load_lds_dwordx4 v[224:225], off
	s_waitcnt vmcnt(8) lgkmcnt(0)
	s_barrier
	v_mfma_f32_16x16x32_bf16 v[120:123], v[158:161], v[190:193], v[120:123]
	v_mfma_f32_16x16x32_bf16 v[120:123], v[162:165], v[194:197], v[120:123]
	v_mfma_f32_16x16x32_bf16 v[116:119], v[166:169], v[190:193], v[116:119]
	v_mfma_f32_16x16x32_bf16 v[116:119], v[170:173], v[194:197], v[116:119]
	v_mfma_f32_16x16x32_bf16 v[100:103], v[166:169], v[198:201], v[100:103]
	v_mfma_f32_16x16x32_bf16 v[100:103], v[170:173], v[202:205], v[100:103]
	v_mfma_f32_16x16x32_bf16 v[104:107], v[158:161], v[198:201], v[104:107]
	v_mfma_f32_16x16x32_bf16 v[104:107], v[162:165], v[202:205], v[104:107]
	v_mfma_f32_16x16x32_bf16 v[88:91], v[158:161], v[206:209], v[88:91]
	v_mfma_f32_16x16x32_bf16 v[88:91], v[162:165], v[210:213], v[88:91]
	v_mfma_f32_16x16x32_bf16 v[84:87], v[166:169], v[206:209], v[84:87]
	v_mfma_f32_16x16x32_bf16 v[84:87], v[170:173], v[210:213], v[84:87]
	v_mfma_f32_16x16x32_bf16 v[68:71], v[166:169], v[214:217], v[68:71]
	v_mfma_f32_16x16x32_bf16 v[68:71], v[170:173], v[218:221], v[68:71]
	v_mfma_f32_16x16x32_bf16 v[72:75], v[158:161], v[214:217], v[72:75]
	v_mfma_f32_16x16x32_bf16 v[72:75], v[162:165], v[218:221], v[72:75]
	v_mfma_f32_16x16x32_bf16 v[80:83], v[174:177], v[214:217], v[80:83]
	v_mfma_f32_16x16x32_bf16 v[80:83], v[178:181], v[218:221], v[80:83]
	v_mfma_f32_16x16x32_bf16 v[76:79], v[182:185], v[214:217], v[76:79]
	v_mfma_f32_16x16x32_bf16 v[76:79], v[186:189], v[218:221], v[76:79]
	v_mfma_f32_16x16x32_bf16 v[92:95], v[182:185], v[206:209], v[92:95]
	v_mfma_f32_16x16x32_bf16 v[92:95], v[186:189], v[210:213], v[92:95]
	v_mfma_f32_16x16x32_bf16 v[96:99], v[174:177], v[206:209], v[96:99]
	v_mfma_f32_16x16x32_bf16 v[96:99], v[178:181], v[210:213], v[96:99]
	v_mfma_f32_16x16x32_bf16 v[112:115], v[174:177], v[198:201], v[112:115]
	v_mfma_f32_16x16x32_bf16 v[112:115], v[178:181], v[202:205], v[112:115]
	v_mfma_f32_16x16x32_bf16 v[108:111], v[182:185], v[198:201], v[108:111]
	v_mfma_f32_16x16x32_bf16 v[108:111], v[186:189], v[202:205], v[108:111]
	v_mfma_f32_16x16x32_bf16 v[124:127], v[182:185], v[190:193], v[124:127]
	v_mfma_f32_16x16x32_bf16 v[124:127], v[186:189], v[194:197], v[124:127]
	v_mfma_f32_16x16x32_bf16 v[128:131], v[174:177], v[190:193], v[128:131]
	v_mfma_f32_16x16x32_bf16 v[128:131], v[178:181], v[194:197], v[128:131]
	s_barrier
	s_add_u32 s12, s56, 0x8000
	s_addc_u32 s13, s57, 0
	s_add_i32 s14, s14, s2
	v_lshl_add_u64 v[224:225], s[12:13], 0, v[134:135]
	s_mov_b32 m0, s14
	ds_read_b128 v[190:193], v157 offset:49152
	ds_read_b128 v[194:197], v157 offset:50176
	ds_read_b128 v[198:201], v157 offset:51200
	ds_read_b128 v[202:205], v157 offset:52224
	ds_read_b128 v[206:209], v157 offset:53248
	ds_read_b128 v[210:213], v157 offset:54272
	ds_read_b128 v[214:217], v157 offset:55296
	ds_read_b128 v[218:221], v157 offset:56320
	global_load_lds_dwordx4 v[224:225], off
	s_add_i32 m0, s14, 0x2000
	v_lshl_add_u64 v[224:225], s[12:13], 0, v[138:139]
	s_add_u32 s12, s56, 0xc000
	s_addc_u32 s13, s57, 0
	s_add_i32 s14, s76, s2
	global_load_lds_dwordx4 v[224:225], off
	v_lshl_add_u64 v[224:225], s[12:13], 0, v[134:135]
	s_mov_b32 m0, s14
	v_lshl_add_u64 v[144:145], v[144:145], 0, s[34:35]
	global_load_lds_dwordx4 v[224:225], off
	s_add_i32 m0, s14, 0x2000
	v_lshl_add_u64 v[224:225], s[12:13], 0, v[138:139]
	global_load_lds_dwordx4 v[224:225], off
	s_mov_b32 m0, s16
	s_nop 0
	global_load_lds_dwordx4 v[144:145], off
	s_mov_b32 m0, s59
	v_lshl_add_u64 v[144:145], v[222:223], 0, s[34:35]
	global_load_lds_dwordx4 v[144:145], off
	s_waitcnt vmcnt(8) lgkmcnt(0)
	s_barrier
	v_mfma_f32_16x16x32_bf16 v[56:59], v[158:161], v[190:193], v[56:59]
	v_mfma_f32_16x16x32_bf16 v[56:59], v[162:165], v[194:197], v[56:59]
	v_mfma_f32_16x16x32_bf16 v[52:55], v[166:169], v[190:193], v[52:55]
	v_mfma_f32_16x16x32_bf16 v[52:55], v[170:173], v[194:197], v[52:55]
	v_mfma_f32_16x16x32_bf16 v[36:39], v[166:169], v[198:201], v[36:39]
	v_mfma_f32_16x16x32_bf16 v[36:39], v[170:173], v[202:205], v[36:39]
	v_mfma_f32_16x16x32_bf16 v[40:43], v[158:161], v[198:201], v[40:43]
	v_mfma_f32_16x16x32_bf16 v[40:43], v[162:165], v[202:205], v[40:43]
	v_mfma_f32_16x16x32_bf16 v[24:27], v[158:161], v[206:209], v[24:27]
	v_mfma_f32_16x16x32_bf16 v[24:27], v[162:165], v[210:213], v[24:27]
	v_mfma_f32_16x16x32_bf16 v[20:23], v[166:169], v[206:209], v[20:23]
	v_mfma_f32_16x16x32_bf16 v[20:23], v[170:173], v[210:213], v[20:23]
	v_mfma_f32_16x16x32_bf16 v[4:7], v[166:169], v[214:217], v[4:7]
	v_mfma_f32_16x16x32_bf16 v[4:7], v[170:173], v[218:221], v[4:7]
	v_mfma_f32_16x16x32_bf16 v[8:11], v[158:161], v[214:217], v[8:11]
	v_mfma_f32_16x16x32_bf16 v[8:11], v[162:165], v[218:221], v[8:11]
	v_mfma_f32_16x16x32_bf16 v[16:19], v[174:177], v[214:217], v[16:19]
	v_mfma_f32_16x16x32_bf16 v[16:19], v[178:181], v[218:221], v[16:19]
	v_mfma_f32_16x16x32_bf16 v[12:15], v[182:185], v[214:217], v[12:15]
	v_mfma_f32_16x16x32_bf16 v[12:15], v[186:189], v[218:221], v[12:15]
	v_mfma_f32_16x16x32_bf16 v[28:31], v[182:185], v[206:209], v[28:31]
	v_mfma_f32_16x16x32_bf16 v[28:31], v[186:189], v[210:213], v[28:31]
	v_mfma_f32_16x16x32_bf16 v[32:35], v[174:177], v[206:209], v[32:35]
	v_mfma_f32_16x16x32_bf16 v[32:35], v[178:181], v[210:213], v[32:35]
	v_mfma_f32_16x16x32_bf16 v[48:51], v[174:177], v[198:201], v[48:51]
	v_mfma_f32_16x16x32_bf16 v[48:51], v[178:181], v[202:205], v[48:51]
	v_mfma_f32_16x16x32_bf16 v[44:47], v[182:185], v[198:201], v[44:47]
	v_mfma_f32_16x16x32_bf16 v[44:47], v[186:189], v[202:205], v[44:47]
	v_mfma_f32_16x16x32_bf16 v[60:63], v[182:185], v[190:193], v[60:63]
	v_mfma_f32_16x16x32_bf16 v[60:63], v[186:189], v[194:197], v[60:63]
	v_mfma_f32_16x16x32_bf16 v[64:67], v[174:177], v[190:193], v[64:67]
	v_mfma_f32_16x16x32_bf16 v[64:67], v[178:181], v[194:197], v[64:67]
	s_barrier
	s_add_i32 s69, s69, 2
	s_add_u32 s70, s70, 0x10000
	s_addc_u32 s71, s71, 0
	s_add_u32 s72, s72, 0x100
	s_addc_u32 s73, s73, 0
	s_add_u32 s8, s8, 0xffffff00
	s_addc_u32 s9, s9, -1
	v_lshl_add_u64 v[2:3], v[2:3], 0, s[40:41]
	s_cmp_gt_u32 s69, 61
	v_lshl_add_u64 v[148:149], v[148:149], 0, s[40:41]
	s_cbranch_scc0 .LBB0_801
	s_and_b64 vcc, exec, s[38:39]
	s_cbranch_vccnz .LBB0_809
	s_and_b64 s[0:1], s[10:11], s[6:7]
	s_andn2_b64 vcc, exec, s[0:1]
	s_cbranch_vccz .LBB0_810

.LBB0_891:
	ds_read_b128 v[2:5], v153
	ds_read_b128 v[6:9], v153 offset:1024
	ds_read_b128 v[10:13], v153 offset:2048
	ds_read_b128 v[14:17], v153 offset:3072
	ds_read_b128 v[18:21], v154
	ds_read_b128 v[22:25], v154 offset:1024
	ds_read_b128 v[26:29], v154 offset:2048
	ds_read_b128 v[30:33], v154 offset:3072
	s_add_u32 s0, s46, 0x10000
	s_addc_u32 s1, s47, 0
	ds_read_b128 v[34:37], v155
	ds_read_b128 v[38:41], v155 offset:1024
	ds_read_b128 v[42:45], v155 offset:2048
	ds_read_b128 v[46:49], v155 offset:3072
	ds_read_b128 v[50:53], v155 offset:4096
	ds_read_b128 v[54:57], v155 offset:5120
	ds_read_b128 v[58:61], v155 offset:6144
	ds_read_b128 v[62:65], v155 offset:7168
	s_waitcnt vmcnt(24) lgkmcnt(0)
	s_barrier
	v_mfma_f32_16x16x32_bf16 v[66:69], v[2:5], v[34:37], 0
	v_mfma_f32_16x16x32_bf16 v[70:73], v[10:13], v[34:37], 0
	v_mfma_f32_16x16x32_bf16 v[74:77], v[2:5], v[42:45], 0
	v_mfma_f32_16x16x32_bf16 v[78:81], v[10:13], v[42:45], 0
	v_mfma_f32_16x16x32_bf16 v[82:85], v[2:5], v[50:53], 0
	v_mfma_f32_16x16x32_bf16 v[86:89], v[10:13], v[50:53], 0
	v_mfma_f32_16x16x32_bf16 v[90:93], v[2:5], v[58:61], 0
	v_mfma_f32_16x16x32_bf16 v[94:97], v[10:13], v[58:61], 0
	v_mfma_f32_16x16x32_bf16 v[66:69], v[6:9], v[38:41], v[66:69]
	v_mfma_f32_16x16x32_bf16 v[70:73], v[14:17], v[38:41], v[70:73]
	v_mfma_f32_16x16x32_bf16 v[74:77], v[6:9], v[46:49], v[74:77]
	v_mfma_f32_16x16x32_bf16 v[78:81], v[14:17], v[46:49], v[78:81]
	v_mfma_f32_16x16x32_bf16 v[82:85], v[6:9], v[54:57], v[82:85]
	v_mfma_f32_16x16x32_bf16 v[86:89], v[14:17], v[54:57], v[86:89]
	v_mfma_f32_16x16x32_bf16 v[90:93], v[6:9], v[62:65], v[90:93]
	v_mfma_f32_16x16x32_bf16 v[104:107], v[14:17], v[62:65], v[94:97]
	v_mfma_f32_16x16x32_bf16 v[94:97], v[18:21], v[34:37], 0
	v_mfma_f32_16x16x32_bf16 v[34:37], v[26:29], v[34:37], 0
	v_mfma_f32_16x16x32_bf16 v[108:111], v[22:25], v[38:41], v[94:97]
	v_mfma_f32_16x16x32_bf16 v[34:37], v[30:33], v[38:41], v[34:37]
	v_mfma_f32_16x16x32_bf16 v[38:41], v[18:21], v[42:45], 0
	v_mfma_f32_16x16x32_bf16 v[42:45], v[26:29], v[42:45], 0
	v_mfma_f32_16x16x32_bf16 v[38:41], v[22:25], v[46:49], v[38:41]
	v_mfma_f32_16x16x32_bf16 v[42:45], v[30:33], v[46:49], v[42:45]
	v_mfma_f32_16x16x32_bf16 v[46:49], v[18:21], v[50:53], 0
	v_mfma_f32_16x16x32_bf16 v[50:53], v[26:29], v[50:53], 0
	v_mfma_f32_16x16x32_bf16 v[46:49], v[22:25], v[54:57], v[46:49]
	v_mfma_f32_16x16x32_bf16 v[50:53], v[30:33], v[54:57], v[50:53]
	v_mfma_f32_16x16x32_bf16 v[54:57], v[18:21], v[58:61], 0
	v_mfma_f32_16x16x32_bf16 v[58:61], v[26:29], v[58:61], 0
	v_mfma_f32_16x16x32_bf16 v[54:57], v[22:25], v[62:65], v[54:57]
	v_mfma_f32_16x16x32_bf16 v[58:61], v[30:33], v[62:65], v[58:61]
	s_barrier
	s_add_i32 s12, s52, s17
	v_lshl_add_u64 v[102:103], s[0:1], 0, v[134:135]
	s_mov_b32 m0, s12
	ds_read_b128 v[62:65], v155 offset:16384
	ds_read_b128 v[94:97], v155 offset:17408
	ds_read_b128 v[98:101], v155 offset:18432
	ds_read_b128 v[112:115], v155 offset:19456
	ds_read_b128 v[116:119], v155 offset:20480
	ds_read_b128 v[120:123], v155 offset:21504
	ds_read_b128 v[124:127], v155 offset:22528
	ds_read_b128 v[128:131], v155 offset:23552
	global_load_lds_dwordx4 v[102:103], off
	s_add_i32 m0, s12, 0x2000
	v_lshl_add_u64 v[102:103], s[0:1], 0, v[138:139]
	s_add_u32 s0, s46, 0x14000
	s_addc_u32 s1, s47, 0
	s_add_i32 s12, s53, s17
	global_load_lds_dwordx4 v[102:103], off
	v_lshl_add_u64 v[102:103], s[0:1], 0, v[134:135]
	s_mov_b32 m0, s12
	v_lshl_add_u64 v[148:149], s[48:49], 0, v[132:133]
	global_load_lds_dwordx4 v[102:103], off
	v_lshl_add_u64 v[102:103], s[0:1], 0, v[138:139]
	s_add_i32 m0, s12, 0x2000
	v_lshl_add_u64 v[144:145], s[48:49], 0, v[136:137]
	global_load_lds_dwordx4 v[102:103], off
	s_mov_b32 m0, s18
	v_lshl_add_u64 v[102:103], v[148:149], 0, s[40:41]
	global_load_lds_dwordx4 v[102:103], off
	s_mov_b32 m0, s19
	v_lshl_add_u64 v[102:103], v[144:145], 0, s[40:41]
	global_load_lds_dwordx4 v[102:103], off
	s_waitcnt vmcnt(24) lgkmcnt(0)
	s_barrier
	v_mfma_f32_16x16x32_bf16 v[158:161], v[2:5], v[62:65], 0
	v_mfma_f32_16x16x32_bf16 v[166:169], v[2:5], v[98:101], 0
	v_mfma_f32_16x16x32_bf16 v[174:177], v[2:5], v[116:119], 0
	v_mfma_f32_16x16x32_bf16 v[2:5], v[2:5], v[124:127], 0
	v_mfma_f32_16x16x32_bf16 v[158:161], v[6:9], v[94:97], v[158:161]
	v_mfma_f32_16x16x32_bf16 v[166:169], v[6:9], v[112:115], v[166:169]
	v_mfma_f32_16x16x32_bf16 v[174:177], v[6:9], v[120:123], v[174:177]
	v_mfma_f32_16x16x32_bf16 v[2:5], v[6:9], v[128:131], v[2:5]
	v_mfma_f32_16x16x32_bf16 v[6:9], v[10:13], v[124:127], 0
	v_mfma_f32_16x16x32_bf16 v[162:165], v[10:13], v[62:65], 0
	v_mfma_f32_16x16x32_bf16 v[170:173], v[10:13], v[98:101], 0
	v_mfma_f32_16x16x32_bf16 v[178:181], v[10:13], v[116:119], 0
	v_mfma_f32_16x16x32_bf16 v[6:9], v[14:17], v[128:131], v[6:9]
	v_mfma_f32_16x16x32_bf16 v[162:165], v[14:17], v[94:97], v[162:165]
	v_mfma_f32_16x16x32_bf16 v[170:173], v[14:17], v[112:115], v[170:173]
	v_mfma_f32_16x16x32_bf16 v[178:181], v[14:17], v[120:123], v[178:181]
	v_mfma_f32_16x16x32_bf16 v[14:17], v[26:29], v[62:65], 0
	v_mfma_f32_16x16x32_bf16 v[182:185], v[30:33], v[94:97], v[14:17]
	v_mfma_f32_16x16x32_bf16 v[14:17], v[18:21], v[98:101], 0
	v_mfma_f32_16x16x32_bf16 v[186:189], v[22:25], v[112:115], v[14:17]
	v_mfma_f32_16x16x32_bf16 v[14:17], v[26:29], v[98:101], 0
	v_mfma_f32_16x16x32_bf16 v[190:193], v[30:33], v[112:115], v[14:17]
	v_mfma_f32_16x16x32_bf16 v[14:17], v[18:21], v[116:119], 0
	v_mfma_f32_16x16x32_bf16 v[194:197], v[22:25], v[120:123], v[14:17]
	v_mfma_f32_16x16x32_bf16 v[14:17], v[26:29], v[116:119], 0
	v_mfma_f32_16x16x32_bf16 v[10:13], v[18:21], v[62:65], 0
	v_mfma_f32_16x16x32_bf16 v[198:201], v[30:33], v[120:123], v[14:17]
	v_mfma_f32_16x16x32_bf16 v[14:17], v[18:21], v[124:127], 0
	v_mfma_f32_16x16x32_bf16 v[10:13], v[22:25], v[94:97], v[10:13]
	v_mfma_f32_16x16x32_bf16 v[202:205], v[22:25], v[128:131], v[14:17]
	v_mfma_f32_16x16x32_bf16 v[14:17], v[26:29], v[124:127], 0
	v_mfma_f32_16x16x32_bf16 v[206:209], v[30:33], v[128:131], v[14:17]
	s_barrier
	s_add_i32 s12, 0, 0x18000
	v_add_u32_e32 v1, s12, v151
	s_add_i32 s13, 0, 0x1c000
	s_nop 1
	ds_read_b128 v[14:17], v1
	ds_read_b128 v[24:27], v1 offset:1024
	ds_read_b128 v[28:31], v1 offset:2048
	ds_read_b128 v[210:213], v1 offset:3072
	v_add_u32_e32 v1, s13, v151
	ds_read_b128 v[214:217], v1
	ds_read_b128 v[218:221], v1 offset:1024
	ds_read_b128 v[222:225], v1 offset:2048
	ds_read_b128 v[226:229], v1 offset:3072
	s_add_u32 s0, s48, 0x2b0100
	s_addc_u32 s1, s49, 0
	s_mov_b32 m0, s20
	v_lshl_add_u64 v[22:23], s[0:1], 0, v[132:133]
	ds_read_b128 v[18:21], v155 offset:32768
	ds_read_b128 v[120:123], v155 offset:33792
	ds_read_b128 v[230:233], v155 offset:34816
	ds_read_b128 v[234:237], v155 offset:35840
	ds_read_b128 v[238:241], v155 offset:36864
	ds_read_b128 v[242:245], v155 offset:37888
	ds_read_b128 v[246:249], v155 offset:38912
	ds_read_b128 v[250:253], v155 offset:39936
	global_load_lds_dwordx4 v[22:23], off
	s_mov_b32 m0, s21
	v_lshl_add_u64 v[22:23], s[0:1], 0, v[136:137]
	global_load_lds_dwordx4 v[22:23], off
	s_waitcnt vmcnt(24) lgkmcnt(0)
	s_barrier
	v_mfma_f32_16x16x32_bf16 v[62:65], v[14:17], v[18:21], v[66:69]
	v_mfma_f32_16x16x32_bf16 v[128:131], v[24:27], v[120:123], v[62:65]
	v_mfma_f32_16x16x32_bf16 v[62:65], v[28:31], v[18:21], v[70:73]
	v_mfma_f32_16x16x32_bf16 v[116:119], v[210:213], v[120:123], v[62:65]
	v_mfma_f32_16x16x32_bf16 v[62:65], v[14:17], v[230:233], v[74:77]
	v_mfma_f32_16x16x32_bf16 v[112:115], v[24:27], v[234:237], v[62:65]
	v_mfma_f32_16x16x32_bf16 v[62:65], v[28:31], v[230:233], v[78:81]
	v_mfma_f32_16x16x32_bf16 v[100:103], v[210:213], v[234:237], v[62:65]
	v_mfma_f32_16x16x32_bf16 v[62:65], v[14:17], v[238:241], v[82:85]
	v_mfma_f32_16x16x32_bf16 v[96:99], v[24:27], v[242:245], v[62:65]
	v_mfma_f32_16x16x32_bf16 v[62:65], v[28:31], v[238:241], v[86:89]
	v_mfma_f32_16x16x32_bf16 v[84:87], v[210:213], v[242:245], v[62:65]
	v_mfma_f32_16x16x32_bf16 v[62:65], v[14:17], v[246:249], v[90:93]
	v_mfma_f32_16x16x32_bf16 v[80:83], v[24:27], v[250:253], v[62:65]
	v_mfma_f32_16x16x32_bf16 v[62:65], v[28:31], v[246:249], v[104:107]
	v_mfma_f32_16x16x32_bf16 v[64:67], v[210:213], v[250:253], v[62:65]
	v_mfma_f32_16x16x32_bf16 v[68:71], v[214:217], v[18:21], v[108:111]
	v_mfma_f32_16x16x32_bf16 v[18:21], v[222:225], v[18:21], v[34:37]
	v_mfma_f32_16x16x32_bf16 v[124:127], v[218:221], v[120:123], v[68:71]
	v_mfma_f32_16x16x32_bf16 v[120:123], v[226:229], v[120:123], v[18:21]
	v_mfma_f32_16x16x32_bf16 v[18:21], v[214:217], v[230:233], v[38:41]
	v_mfma_f32_16x16x32_bf16 v[108:111], v[218:221], v[234:237], v[18:21]
	v_mfma_f32_16x16x32_bf16 v[18:21], v[222:225], v[230:233], v[42:45]
	v_mfma_f32_16x16x32_bf16 v[104:107], v[226:229], v[234:237], v[18:21]
	v_mfma_f32_16x16x32_bf16 v[18:21], v[214:217], v[238:241], v[46:49]
	v_mfma_f32_16x16x32_bf16 v[92:95], v[218:221], v[242:245], v[18:21]
	v_mfma_f32_16x16x32_bf16 v[18:21], v[222:225], v[238:241], v[50:53]
	v_mfma_f32_16x16x32_bf16 v[88:91], v[226:229], v[242:245], v[18:21]
	v_mfma_f32_16x16x32_bf16 v[18:21], v[214:217], v[246:249], v[54:57]
	v_mfma_f32_16x16x32_bf16 v[72:75], v[218:221], v[250:253], v[18:21]
	v_mfma_f32_16x16x32_bf16 v[18:21], v[222:225], v[246:249], v[58:61]
	v_mfma_f32_16x16x32_bf16 v[68:71], v[226:229], v[250:253], v[18:21]
	s_barrier
	s_add_u32 s0, s46, 0x18000
	s_addc_u32 s1, s47, 0
	s_add_i32 s12, s12, s17
	s_nop 1
	v_lshl_add_u64 v[18:19], s[0:1], 0, v[134:135]
	s_mov_b32 m0, s12
	ds_read_b128 v[40:43], v155 offset:49152
	ds_read_b128 v[44:47], v155 offset:50176
	ds_read_b128 v[230:233], v155 offset:51200
	ds_read_b128 v[234:237], v155 offset:52224
	ds_read_b128 v[238:241], v155 offset:53248
	ds_read_b128 v[242:245], v155 offset:54272
	ds_read_b128 v[246:249], v155 offset:55296
	ds_read_b128 v[250:253], v155 offset:56320
	global_load_lds_dwordx4 v[18:19], off
	s_add_i32 m0, s12, 0x2000
	v_lshl_add_u64 v[18:19], s[0:1], 0, v[138:139]
	s_add_u32 s0, s46, 0x1c000
	s_addc_u32 s1, s47, 0
	s_add_i32 s12, s13, s17
	global_load_lds_dwordx4 v[18:19], off
	s_mov_b32 m0, s12
	v_lshl_add_u64 v[18:19], s[0:1], 0, v[134:135]
	global_load_lds_dwordx4 v[18:19], off
	s_add_i32 m0, s12, 0x2000
	v_lshl_add_u64 v[18:19], s[0:1], 0, v[138:139]
	global_load_lds_dwordx4 v[18:19], off
	s_mov_b32 m0, s25
	v_lshl_add_u64 v[18:19], v[148:149], 0, s[42:43]
	global_load_lds_dwordx4 v[18:19], off
	s_mov_b32 m0, s33
	v_lshl_add_u64 v[18:19], v[144:145], 0, s[42:43]
	global_load_lds_dwordx4 v[18:19], off
	s_waitcnt vmcnt(8) lgkmcnt(0)
	s_barrier
	v_mfma_f32_16x16x32_bf16 v[18:21], v[14:17], v[40:43], v[158:161]
	v_mfma_f32_16x16x32_bf16 v[76:79], v[24:27], v[44:47], v[18:21]
	v_mfma_f32_16x16x32_bf16 v[18:21], v[28:31], v[40:43], v[162:165]
	v_mfma_f32_16x16x32_bf16 v[52:55], v[210:213], v[44:47], v[18:21]
	v_mfma_f32_16x16x32_bf16 v[18:21], v[14:17], v[230:233], v[166:169]
	v_mfma_f32_16x16x32_bf16 v[48:51], v[24:27], v[234:237], v[18:21]
	v_mfma_f32_16x16x32_bf16 v[18:21], v[28:31], v[230:233], v[170:173]
	v_mfma_f32_16x16x32_bf16 v[36:39], v[210:213], v[234:237], v[18:21]
	v_mfma_f32_16x16x32_bf16 v[18:21], v[14:17], v[238:241], v[174:177]
	v_mfma_f32_16x16x32_bf16 v[32:35], v[24:27], v[242:245], v[18:21]
	v_mfma_f32_16x16x32_bf16 v[18:21], v[28:31], v[238:241], v[178:181]
	v_mfma_f32_16x16x32_bf16 v[2:5], v[14:17], v[246:249], v[2:5]
	v_mfma_f32_16x16x32_bf16 v[20:23], v[210:213], v[242:245], v[18:21]
	v_mfma_f32_16x16x32_bf16 v[16:19], v[24:27], v[250:253], v[2:5]
	v_mfma_f32_16x16x32_bf16 v[2:5], v[28:31], v[246:249], v[6:9]
	v_mfma_f32_16x16x32_bf16 v[4:7], v[210:213], v[250:253], v[2:5]
	v_mfma_f32_16x16x32_bf16 v[8:11], v[214:217], v[40:43], v[10:13]
	v_mfma_f32_16x16x32_bf16 v[60:63], v[218:221], v[44:47], v[8:11]
	v_mfma_f32_16x16x32_bf16 v[8:11], v[222:225], v[40:43], v[182:185]
	v_mfma_f32_16x16x32_bf16 v[56:59], v[226:229], v[44:47], v[8:11]
	v_mfma_f32_16x16x32_bf16 v[8:11], v[214:217], v[230:233], v[186:189]
	v_mfma_f32_16x16x32_bf16 v[44:47], v[218:221], v[234:237], v[8:11]
	v_mfma_f32_16x16x32_bf16 v[8:11], v[222:225], v[230:233], v[190:193]
	v_mfma_f32_16x16x32_bf16 v[40:43], v[226:229], v[234:237], v[8:11]
	v_mfma_f32_16x16x32_bf16 v[8:11], v[214:217], v[238:241], v[194:197]
	v_mfma_f32_16x16x32_bf16 v[28:31], v[218:221], v[242:245], v[8:11]
	v_mfma_f32_16x16x32_bf16 v[8:11], v[222:225], v[238:241], v[198:201]
	v_mfma_f32_16x16x32_bf16 v[24:27], v[226:229], v[242:245], v[8:11]
	v_mfma_f32_16x16x32_bf16 v[8:11], v[214:217], v[246:249], v[202:205]
	v_mfma_f32_16x16x32_bf16 v[12:15], v[218:221], v[250:253], v[8:11]
	v_mfma_f32_16x16x32_bf16 v[8:11], v[222:225], v[246:249], v[206:209]
	v_mfma_f32_16x16x32_bf16 v[8:11], v[226:229], v[250:253], v[8:11]
	s_barrier
	s_mov_b32 s22, 2
	s_branch .LBB0_895

.LBB0_896:
	ds_read_b128 v[158:161], v153
	ds_read_b128 v[162:165], v153 offset:1024
	ds_read_b128 v[166:169], v153 offset:2048
	ds_read_b128 v[170:173], v153 offset:3072
	ds_read_b128 v[174:177], v154
	ds_read_b128 v[178:181], v154 offset:1024
	ds_read_b128 v[182:185], v154 offset:2048
	ds_read_b128 v[186:189], v154 offset:3072
	s_add_u32 s12, s60, s26
	s_addc_u32 s13, s61, 0
	s_cmp_eq_u32 s26, s46
	s_cselect_b32 s23, s9, s13
	s_cselect_b32 s22, s8, s12
	s_cselect_b32 s49, s45, s59
	s_cselect_b32 s48, s44, s1
	s_add_i32 s63, s18, 0xc000
	v_lshl_add_u64 v[144:145], v[2:3], 0, s[26:27]
	s_mov_b32 m0, s63
	s_add_i32 s62, s18, 0xe000
	ds_read_b128 v[190:193], v155
	ds_read_b128 v[194:197], v155 offset:1024
	ds_read_b128 v[198:201], v155 offset:2048
	ds_read_b128 v[202:205], v155 offset:3072
	ds_read_b128 v[206:209], v155 offset:4096
	ds_read_b128 v[210:213], v155 offset:5120
	ds_read_b128 v[214:217], v155 offset:6144
	ds_read_b128 v[218:221], v155 offset:7168
	global_load_lds_dwordx4 v[144:145], off
	s_mov_b32 m0, s62
	v_lshl_add_u64 v[144:145], v[148:149], 0, s[26:27]
	global_load_lds_dwordx4 v[144:145], off
	s_waitcnt vmcnt(8) lgkmcnt(0)
	s_barrier
	v_mfma_f32_16x16x32_bf16 v[128:131], v[158:161], v[190:193], v[128:131]
	v_mfma_f32_16x16x32_bf16 v[128:131], v[162:165], v[194:197], v[128:131]
	v_mfma_f32_16x16x32_bf16 v[116:119], v[166:169], v[190:193], v[116:119]
	v_mfma_f32_16x16x32_bf16 v[116:119], v[170:173], v[194:197], v[116:119]
	v_mfma_f32_16x16x32_bf16 v[100:103], v[166:169], v[198:201], v[100:103]
	v_mfma_f32_16x16x32_bf16 v[100:103], v[170:173], v[202:205], v[100:103]
	v_mfma_f32_16x16x32_bf16 v[112:115], v[158:161], v[198:201], v[112:115]
	v_mfma_f32_16x16x32_bf16 v[112:115], v[162:165], v[202:205], v[112:115]
	v_mfma_f32_16x16x32_bf16 v[96:99], v[158:161], v[206:209], v[96:99]
	v_mfma_f32_16x16x32_bf16 v[96:99], v[162:165], v[210:213], v[96:99]
	v_mfma_f32_16x16x32_bf16 v[84:87], v[166:169], v[206:209], v[84:87]
	v_mfma_f32_16x16x32_bf16 v[84:87], v[170:173], v[210:213], v[84:87]
	v_mfma_f32_16x16x32_bf16 v[64:67], v[166:169], v[214:217], v[64:67]
	v_mfma_f32_16x16x32_bf16 v[64:67], v[170:173], v[218:221], v[64:67]
	v_mfma_f32_16x16x32_bf16 v[80:83], v[158:161], v[214:217], v[80:83]
	v_mfma_f32_16x16x32_bf16 v[80:83], v[162:165], v[218:221], v[80:83]
	v_mfma_f32_16x16x32_bf16 v[72:75], v[174:177], v[214:217], v[72:75]
	v_mfma_f32_16x16x32_bf16 v[72:75], v[178:181], v[218:221], v[72:75]
	v_mfma_f32_16x16x32_bf16 v[68:71], v[182:185], v[214:217], v[68:71]
	v_mfma_f32_16x16x32_bf16 v[68:71], v[186:189], v[218:221], v[68:71]
	v_mfma_f32_16x16x32_bf16 v[88:91], v[182:185], v[206:209], v[88:91]
	v_mfma_f32_16x16x32_bf16 v[88:91], v[186:189], v[210:213], v[88:91]
	v_mfma_f32_16x16x32_bf16 v[92:95], v[174:177], v[206:209], v[92:95]
	v_mfma_f32_16x16x32_bf16 v[92:95], v[178:181], v[210:213], v[92:95]
	v_mfma_f32_16x16x32_bf16 v[108:111], v[174:177], v[198:201], v[108:111]
	v_mfma_f32_16x16x32_bf16 v[108:111], v[178:181], v[202:205], v[108:111]
	v_mfma_f32_16x16x32_bf16 v[104:107], v[182:185], v[198:201], v[104:107]
	v_mfma_f32_16x16x32_bf16 v[104:107], v[186:189], v[202:205], v[104:107]
	v_mfma_f32_16x16x32_bf16 v[120:123], v[182:185], v[190:193], v[120:123]
	v_mfma_f32_16x16x32_bf16 v[120:123], v[186:189], v[194:197], v[120:123]
	v_mfma_f32_16x16x32_bf16 v[124:127], v[174:177], v[190:193], v[124:127]
	v_mfma_f32_16x16x32_bf16 v[124:127], v[178:181], v[194:197], v[124:127]
	s_barrier
	s_add_i32 s12, s52, s17
	v_lshl_add_u64 v[144:145], s[48:49], 0, v[134:135]
	s_mov_b32 m0, s12
	ds_read_b128 v[190:193], v155 offset:16384
	ds_read_b128 v[194:197], v155 offset:17408
	ds_read_b128 v[198:201], v155 offset:18432
	ds_read_b128 v[202:205], v155 offset:19456
	ds_read_b128 v[206:209], v155 offset:20480
	ds_read_b128 v[210:213], v155 offset:21504
	ds_read_b128 v[214:217], v155 offset:22528
	ds_read_b128 v[218:221], v155 offset:23552
	global_load_lds_dwordx4 v[144:145], off
	s_add_i32 m0, s12, 0x2000
	s_add_u32 s12, s48, 0x4000
	v_lshl_add_u64 v[144:145], s[48:49], 0, v[138:139]
	s_addc_u32 s13, s49, 0
	s_add_i32 s14, s53, s17
	global_load_lds_dwordx4 v[144:145], off
	v_lshl_add_u64 v[144:145], s[12:13], 0, v[134:135]
	s_mov_b32 m0, s14
	v_lshl_add_u64 v[222:223], s[22:23], 0, v[136:137]
	global_load_lds_dwordx4 v[144:145], off
	s_add_i32 m0, s14, 0x2000
	v_lshl_add_u64 v[144:145], s[12:13], 0, v[138:139]
	global_load_lds_dwordx4 v[144:145], off
	s_mov_b32 m0, s18
	v_lshl_add_u64 v[144:145], s[22:23], 0, v[132:133]
	global_load_lds_dwordx4 v[144:145], off
	s_mov_b32 m0, s19
	s_nop 0
	global_load_lds_dwordx4 v[222:223], off
	s_waitcnt vmcnt(8) lgkmcnt(0)
	s_barrier
	v_mfma_f32_16x16x32_bf16 v[76:79], v[158:161], v[190:193], v[76:79]
	v_mfma_f32_16x16x32_bf16 v[76:79], v[162:165], v[194:197], v[76:79]
	v_mfma_f32_16x16x32_bf16 v[52:55], v[166:169], v[190:193], v[52:55]
	v_mfma_f32_16x16x32_bf16 v[52:55], v[170:173], v[194:197], v[52:55]
	v_mfma_f32_16x16x32_bf16 v[36:39], v[166:169], v[198:201], v[36:39]
	v_mfma_f32_16x16x32_bf16 v[36:39], v[170:173], v[202:205], v[36:39]
	v_mfma_f32_16x16x32_bf16 v[48:51], v[158:161], v[198:201], v[48:51]
	v_mfma_f32_16x16x32_bf16 v[48:51], v[162:165], v[202:205], v[48:51]
	v_mfma_f32_16x16x32_bf16 v[32:35], v[158:161], v[206:209], v[32:35]
	v_mfma_f32_16x16x32_bf16 v[32:35], v[162:165], v[210:213], v[32:35]
	v_mfma_f32_16x16x32_bf16 v[20:23], v[166:169], v[206:209], v[20:23]
	v_mfma_f32_16x16x32_bf16 v[20:23], v[170:173], v[210:213], v[20:23]
	v_mfma_f32_16x16x32_bf16 v[4:7], v[166:169], v[214:217], v[4:7]
	v_mfma_f32_16x16x32_bf16 v[4:7], v[170:173], v[218:221], v[4:7]
	v_mfma_f32_16x16x32_bf16 v[16:19], v[158:161], v[214:217], v[16:19]
	v_mfma_f32_16x16x32_bf16 v[16:19], v[162:165], v[218:221], v[16:19]
	v_mfma_f32_16x16x32_bf16 v[12:15], v[174:177], v[214:217], v[12:15]
	v_mfma_f32_16x16x32_bf16 v[12:15], v[178:181], v[218:221], v[12:15]
	v_mfma_f32_16x16x32_bf16 v[8:11], v[182:185], v[214:217], v[8:11]
	v_mfma_f32_16x16x32_bf16 v[8:11], v[186:189], v[218:221], v[8:11]
	v_mfma_f32_16x16x32_bf16 v[24:27], v[182:185], v[206:209], v[24:27]
	v_mfma_f32_16x16x32_bf16 v[24:27], v[186:189], v[210:213], v[24:27]
	v_mfma_f32_16x16x32_bf16 v[28:31], v[174:177], v[206:209], v[28:31]
	v_mfma_f32_16x16x32_bf16 v[28:31], v[178:181], v[210:213], v[28:31]
	v_mfma_f32_16x16x32_bf16 v[44:47], v[174:177], v[198:201], v[44:47]
	v_mfma_f32_16x16x32_bf16 v[44:47], v[178:181], v[202:205], v[44:47]
	v_mfma_f32_16x16x32_bf16 v[40:43], v[182:185], v[198:201], v[40:43]
	v_mfma_f32_16x16x32_bf16 v[40:43], v[186:189], v[202:205], v[40:43]
	v_mfma_f32_16x16x32_bf16 v[56:59], v[182:185], v[190:193], v[56:59]
	v_mfma_f32_16x16x32_bf16 v[56:59], v[186:189], v[194:197], v[56:59]
	v_mfma_f32_16x16x32_bf16 v[60:63], v[174:177], v[190:193], v[60:63]
	v_mfma_f32_16x16x32_bf16 v[60:63], v[178:181], v[194:197], v[60:63]
	s_barrier
	s_add_i32 s14, 0, 0x18000
	v_add_u32_e32 v1, s14, v151
	s_add_i32 s64, 0, 0x1c000
	ds_read_b128 v[158:161], v1
	ds_read_b128 v[162:165], v1 offset:1024
	ds_read_b128 v[166:169], v1 offset:2048
	ds_read_b128 v[170:173], v1 offset:3072
	v_add_u32_e32 v1, s64, v151
	ds_read_b128 v[174:177], v1
	ds_read_b128 v[178:181], v1 offset:1024
	ds_read_b128 v[182:185], v1 offset:2048
	ds_read_b128 v[186:189], v1 offset:3072
	s_add_u32 s12, s22, 0x2b0000
	s_addc_u32 s13, s23, 0
	s_mov_b32 m0, s20
	v_lshl_add_u64 v[224:225], s[12:13], 0, v[132:133]
	ds_read_b128 v[190:193], v155 offset:32768
	ds_read_b128 v[194:197], v155 offset:33792
	ds_read_b128 v[198:201], v155 offset:34816
	ds_read_b128 v[202:205], v155 offset:35840
	ds_read_b128 v[206:209], v155 offset:36864
	ds_read_b128 v[210:213], v155 offset:37888
	ds_read_b128 v[214:217], v155 offset:38912
	ds_read_b128 v[218:221], v155 offset:39936
	global_load_lds_dwordx4 v[224:225], off
	s_mov_b32 m0, s21
	v_lshl_add_u64 v[224:225], s[12:13], 0, v[136:137]
	global_load_lds_dwordx4 v[224:225], off
	s_waitcnt vmcnt(8) lgkmcnt(0)
	s_barrier
	v_mfma_f32_16x16x32_bf16 v[128:131], v[158:161], v[190:193], v[128:131]
	v_mfma_f32_16x16x32_bf16 v[128:131], v[162:165], v[194:197], v[128:131]
	v_mfma_f32_16x16x32_bf16 v[116:119], v[166:169], v[190:193], v[116:119]
	v_mfma_f32_16x16x32_bf16 v[116:119], v[170:173], v[194:197], v[116:119]
	v_mfma_f32_16x16x32_bf16 v[100:103], v[166:169], v[198:201], v[100:103]
	v_mfma_f32_16x16x32_bf16 v[100:103], v[170:173], v[202:205], v[100:103]
	v_mfma_f32_16x16x32_bf16 v[112:115], v[158:161], v[198:201], v[112:115]
	v_mfma_f32_16x16x32_bf16 v[112:115], v[162:165], v[202:205], v[112:115]
	v_mfma_f32_16x16x32_bf16 v[96:99], v[158:161], v[206:209], v[96:99]
	v_mfma_f32_16x16x32_bf16 v[96:99], v[162:165], v[210:213], v[96:99]
	v_mfma_f32_16x16x32_bf16 v[84:87], v[166:169], v[206:209], v[84:87]
	v_mfma_f32_16x16x32_bf16 v[84:87], v[170:173], v[210:213], v[84:87]
	v_mfma_f32_16x16x32_bf16 v[64:67], v[166:169], v[214:217], v[64:67]
	v_mfma_f32_16x16x32_bf16 v[64:67], v[170:173], v[218:221], v[64:67]
	v_mfma_f32_16x16x32_bf16 v[80:83], v[158:161], v[214:217], v[80:83]
	v_mfma_f32_16x16x32_bf16 v[80:83], v[162:165], v[218:221], v[80:83]
	v_mfma_f32_16x16x32_bf16 v[72:75], v[174:177], v[214:217], v[72:75]
	v_mfma_f32_16x16x32_bf16 v[72:75], v[178:181], v[218:221], v[72:75]
	v_mfma_f32_16x16x32_bf16 v[68:71], v[182:185], v[214:217], v[68:71]
	v_mfma_f32_16x16x32_bf16 v[68:71], v[186:189], v[218:221], v[68:71]
	v_mfma_f32_16x16x32_bf16 v[88:91], v[182:185], v[206:209], v[88:91]
	v_mfma_f32_16x16x32_bf16 v[88:91], v[186:189], v[210:213], v[88:91]
	v_mfma_f32_16x16x32_bf16 v[92:95], v[174:177], v[206:209], v[92:95]
	v_mfma_f32_16x16x32_bf16 v[92:95], v[178:181], v[210:213], v[92:95]
	v_mfma_f32_16x16x32_bf16 v[108:111], v[174:177], v[198:201], v[108:111]
	v_mfma_f32_16x16x32_bf16 v[108:111], v[178:181], v[202:205], v[108:111]
	v_mfma_f32_16x16x32_bf16 v[104:107], v[182:185], v[198:201], v[104:107]
	v_mfma_f32_16x16x32_bf16 v[104:107], v[186:189], v[202:205], v[104:107]
	v_mfma_f32_16x16x32_bf16 v[120:123], v[182:185], v[190:193], v[120:123]
	v_mfma_f32_16x16x32_bf16 v[120:123], v[186:189], v[194:197], v[120:123]
	v_mfma_f32_16x16x32_bf16 v[124:127], v[174:177], v[190:193], v[124:127]
	v_mfma_f32_16x16x32_bf16 v[124:127], v[178:181], v[194:197], v[124:127]
	s_barrier
	s_add_u32 s12, s48, 0x8000
	s_addc_u32 s13, s49, 0
	s_add_i32 s14, s14, s17
	v_lshl_add_u64 v[224:225], s[12:13], 0, v[134:135]
	s_mov_b32 m0, s14
	ds_read_b128 v[190:193], v155 offset:49152
	ds_read_b128 v[194:197], v155 offset:50176
	ds_read_b128 v[198:201], v155 offset:51200
	ds_read_b128 v[202:205], v155 offset:52224
	ds_read_b128 v[206:209], v155 offset:53248
	ds_read_b128 v[210:213], v155 offset:54272
	ds_read_b128 v[214:217], v155 offset:55296
	ds_read_b128 v[218:221], v155 offset:56320
	global_load_lds_dwordx4 v[224:225], off
	s_add_i32 m0, s14, 0x2000
	v_lshl_add_u64 v[224:225], s[12:13], 0, v[138:139]
	s_add_u32 s12, s48, 0xc000
	s_addc_u32 s13, s49, 0
	s_add_i32 s14, s64, s17
	global_load_lds_dwordx4 v[224:225], off
	v_lshl_add_u64 v[224:225], s[12:13], 0, v[134:135]
	s_mov_b32 m0, s14
	v_lshl_add_u64 v[144:145], v[144:145], 0, s[36:37]
	global_load_lds_dwordx4 v[224:225], off
	s_add_i32 m0, s14, 0x2000
	v_lshl_add_u64 v[224:225], s[12:13], 0, v[138:139]
	global_load_lds_dwordx4 v[224:225], off
	s_mov_b32 m0, s25
	s_nop 0
	global_load_lds_dwordx4 v[144:145], off
	s_mov_b32 m0, s33
	v_lshl_add_u64 v[144:145], v[222:223], 0, s[36:37]
	global_load_lds_dwordx4 v[144:145], off
	s_waitcnt vmcnt(8) lgkmcnt(0)
	s_barrier
	v_mfma_f32_16x16x32_bf16 v[76:79], v[158:161], v[190:193], v[76:79]
	v_mfma_f32_16x16x32_bf16 v[76:79], v[162:165], v[194:197], v[76:79]
	v_mfma_f32_16x16x32_bf16 v[52:55], v[166:169], v[190:193], v[52:55]
	v_mfma_f32_16x16x32_bf16 v[52:55], v[170:173], v[194:197], v[52:55]
	v_mfma_f32_16x16x32_bf16 v[36:39], v[166:169], v[198:201], v[36:39]
	v_mfma_f32_16x16x32_bf16 v[36:39], v[170:173], v[202:205], v[36:39]
	v_mfma_f32_16x16x32_bf16 v[48:51], v[158:161], v[198:201], v[48:51]
	v_mfma_f32_16x16x32_bf16 v[48:51], v[162:165], v[202:205], v[48:51]
	v_mfma_f32_16x16x32_bf16 v[32:35], v[158:161], v[206:209], v[32:35]
	v_mfma_f32_16x16x32_bf16 v[32:35], v[162:165], v[210:213], v[32:35]
	v_mfma_f32_16x16x32_bf16 v[20:23], v[166:169], v[206:209], v[20:23]
	v_mfma_f32_16x16x32_bf16 v[20:23], v[170:173], v[210:213], v[20:23]
	v_mfma_f32_16x16x32_bf16 v[4:7], v[166:169], v[214:217], v[4:7]
	v_mfma_f32_16x16x32_bf16 v[4:7], v[170:173], v[218:221], v[4:7]
	v_mfma_f32_16x16x32_bf16 v[16:19], v[158:161], v[214:217], v[16:19]
	v_mfma_f32_16x16x32_bf16 v[16:19], v[162:165], v[218:221], v[16:19]
	v_mfma_f32_16x16x32_bf16 v[12:15], v[174:177], v[214:217], v[12:15]
	v_mfma_f32_16x16x32_bf16 v[12:15], v[178:181], v[218:221], v[12:15]
	v_mfma_f32_16x16x32_bf16 v[8:11], v[182:185], v[214:217], v[8:11]
	v_mfma_f32_16x16x32_bf16 v[8:11], v[186:189], v[218:221], v[8:11]
	v_mfma_f32_16x16x32_bf16 v[24:27], v[182:185], v[206:209], v[24:27]
	v_mfma_f32_16x16x32_bf16 v[24:27], v[186:189], v[210:213], v[24:27]
	v_mfma_f32_16x16x32_bf16 v[28:31], v[174:177], v[206:209], v[28:31]
	v_mfma_f32_16x16x32_bf16 v[28:31], v[178:181], v[210:213], v[28:31]
	v_mfma_f32_16x16x32_bf16 v[44:47], v[174:177], v[198:201], v[44:47]
	v_mfma_f32_16x16x32_bf16 v[44:47], v[178:181], v[202:205], v[44:47]
	v_mfma_f32_16x16x32_bf16 v[40:43], v[182:185], v[198:201], v[40:43]
	v_mfma_f32_16x16x32_bf16 v[40:43], v[186:189], v[202:205], v[40:43]
	v_mfma_f32_16x16x32_bf16 v[56:59], v[182:185], v[190:193], v[56:59]
	v_mfma_f32_16x16x32_bf16 v[56:59], v[186:189], v[194:197], v[56:59]
	v_mfma_f32_16x16x32_bf16 v[60:63], v[174:177], v[190:193], v[60:63]
	v_mfma_f32_16x16x32_bf16 v[60:63], v[178:181], v[194:197], v[60:63]
	s_barrier
	s_add_i32 s0, s0, 2
	s_add_u32 s1, s1, 0x10000
	s_addc_u32 s59, s59, 0
	s_add_u32 s60, s60, 0x100
	s_addc_u32 s61, s61, 0
	s_add_u32 s46, s46, 0xffffff00
	s_addc_u32 s47, s47, -1
	v_lshl_add_u64 v[2:3], v[2:3], 0, s[40:41]
	s_cmpk_gt_u32 s0, 0xa9
	v_lshl_add_u64 v[148:149], v[148:149], 0, s[40:41]
	s_cbranch_scc0 .LBB0_896
	s_and_b64 vcc, exec, s[38:39]
	s_cbranch_vccz .LBB0_899
	s_barrier

.LBB0_1049:
	s_cmp_lg_u32 s45, 0
	s_mov_b32 s22, 0
	s_cbranch_scc0 .LBB0_1051
	ds_read_b128 v[2:5], v155
	ds_read_b128 v[6:9], v155 offset:1024
	ds_read_b128 v[10:13], v155 offset:2048
	ds_read_b128 v[14:17], v155 offset:3072
	ds_read_b128 v[18:21], v156
	ds_read_b128 v[22:25], v156 offset:1024
	ds_read_b128 v[26:29], v156 offset:2048
	ds_read_b128 v[30:33], v156 offset:3072
	s_add_u32 s0, s52, 0x10000
	s_addc_u32 s1, s53, 0
	ds_read_b128 v[34:37], v157
	ds_read_b128 v[38:41], v157 offset:1024
	ds_read_b128 v[42:45], v157 offset:2048
	ds_read_b128 v[46:49], v157 offset:3072
	ds_read_b128 v[50:53], v157 offset:4096
	ds_read_b128 v[54:57], v157 offset:5120
	ds_read_b128 v[58:61], v157 offset:6144
	ds_read_b128 v[62:65], v157 offset:7168
	s_waitcnt vmcnt(24) lgkmcnt(0)
	s_barrier
	v_mfma_f32_16x16x32_bf16 v[90:93], v[2:5], v[58:61], 0
	v_mfma_f32_16x16x32_bf16 v[66:69], v[2:5], v[34:37], 0
	v_mfma_f32_16x16x32_bf16 v[70:73], v[10:13], v[34:37], 0
	v_mfma_f32_16x16x32_bf16 v[74:77], v[2:5], v[42:45], 0
	v_mfma_f32_16x16x32_bf16 v[78:81], v[10:13], v[42:45], 0
	v_mfma_f32_16x16x32_bf16 v[82:85], v[2:5], v[50:53], 0
	v_mfma_f32_16x16x32_bf16 v[86:89], v[10:13], v[50:53], 0
	v_mfma_f32_16x16x32_bf16 v[100:103], v[6:9], v[62:65], v[90:93]
	v_mfma_f32_16x16x32_bf16 v[90:93], v[10:13], v[58:61], 0
	v_mfma_f32_16x16x32_bf16 v[66:69], v[6:9], v[38:41], v[66:69]
	v_mfma_f32_16x16x32_bf16 v[70:73], v[14:17], v[38:41], v[70:73]
	v_mfma_f32_16x16x32_bf16 v[74:77], v[6:9], v[46:49], v[74:77]
	v_mfma_f32_16x16x32_bf16 v[78:81], v[14:17], v[46:49], v[78:81]
	v_mfma_f32_16x16x32_bf16 v[82:85], v[6:9], v[54:57], v[82:85]
	v_mfma_f32_16x16x32_bf16 v[86:89], v[14:17], v[54:57], v[86:89]
	v_mfma_f32_16x16x32_bf16 v[104:107], v[14:17], v[62:65], v[90:93]
	v_mfma_f32_16x16x32_bf16 v[90:93], v[18:21], v[34:37], 0
	v_mfma_f32_16x16x32_bf16 v[34:37], v[26:29], v[34:37], 0
	v_mfma_f32_16x16x32_bf16 v[116:119], v[22:25], v[38:41], v[90:93]
	v_mfma_f32_16x16x32_bf16 v[34:37], v[30:33], v[38:41], v[34:37]
	v_mfma_f32_16x16x32_bf16 v[38:41], v[18:21], v[42:45], 0
	v_mfma_f32_16x16x32_bf16 v[42:45], v[26:29], v[42:45], 0
	v_mfma_f32_16x16x32_bf16 v[38:41], v[22:25], v[46:49], v[38:41]
	v_mfma_f32_16x16x32_bf16 v[42:45], v[30:33], v[46:49], v[42:45]
	v_mfma_f32_16x16x32_bf16 v[46:49], v[18:21], v[50:53], 0
	v_mfma_f32_16x16x32_bf16 v[50:53], v[26:29], v[50:53], 0
	v_mfma_f32_16x16x32_bf16 v[46:49], v[22:25], v[54:57], v[46:49]
	v_mfma_f32_16x16x32_bf16 v[50:53], v[30:33], v[54:57], v[50:53]
	v_mfma_f32_16x16x32_bf16 v[54:57], v[18:21], v[58:61], 0
	v_mfma_f32_16x16x32_bf16 v[58:61], v[26:29], v[58:61], 0
	v_mfma_f32_16x16x32_bf16 v[54:57], v[22:25], v[62:65], v[54:57]
	v_mfma_f32_16x16x32_bf16 v[58:61], v[30:33], v[62:65], v[58:61]
	s_barrier
	s_add_i32 s12, s58, s20
	v_lshl_add_u64 v[98:99], s[0:1], 0, v[134:135]
	s_mov_b32 m0, s12
	ds_read_b128 v[62:65], v157 offset:16384
	ds_read_b128 v[90:93], v157 offset:17408
	ds_read_b128 v[94:97], v157 offset:18432
	ds_read_b128 v[108:111], v157 offset:19456
	ds_read_b128 v[112:115], v157 offset:20480
	ds_read_b128 v[120:123], v157 offset:21504
	ds_read_b128 v[124:127], v157 offset:22528
	ds_read_b128 v[128:131], v157 offset:23552
	global_load_lds_dwordx4 v[98:99], off
	s_add_i32 m0, s12, 0x2000
	v_lshl_add_u64 v[98:99], s[0:1], 0, v[138:139]
	s_add_u32 s0, s52, 0x14000
	s_addc_u32 s1, s53, 0
	s_add_i32 s12, s59, s20
	global_load_lds_dwordx4 v[98:99], off
	v_lshl_add_u64 v[98:99], s[0:1], 0, v[134:135]
	s_mov_b32 m0, s12
	v_lshl_add_u64 v[150:151], s[6:7], 0, v[132:133]
	global_load_lds_dwordx4 v[98:99], off
	v_lshl_add_u64 v[98:99], s[0:1], 0, v[138:139]
	s_add_i32 m0, s12, 0x2000
	v_lshl_add_u64 v[252:253], s[6:7], 0, v[136:137]
	global_load_lds_dwordx4 v[98:99], off
	s_mov_b32 m0, s21
	v_lshl_add_u64 v[98:99], v[150:151], 0, s[36:37]
	global_load_lds_dwordx4 v[98:99], off
	s_mov_b32 m0, s24
	v_lshl_add_u64 v[98:99], v[252:253], 0, s[36:37]
	global_load_lds_dwordx4 v[98:99], off
	s_waitcnt vmcnt(24) lgkmcnt(0)
	s_barrier
	v_mfma_f32_16x16x32_bf16 v[160:163], v[2:5], v[62:65], 0
	v_mfma_f32_16x16x32_bf16 v[168:171], v[2:5], v[94:97], 0
	v_mfma_f32_16x16x32_bf16 v[176:179], v[2:5], v[112:115], 0
	v_mfma_f32_16x16x32_bf16 v[2:5], v[2:5], v[124:127], 0
	v_mfma_f32_16x16x32_bf16 v[160:163], v[6:9], v[90:93], v[160:163]
	v_mfma_f32_16x16x32_bf16 v[168:171], v[6:9], v[108:111], v[168:171]
	v_mfma_f32_16x16x32_bf16 v[176:179], v[6:9], v[120:123], v[176:179]
	v_mfma_f32_16x16x32_bf16 v[2:5], v[6:9], v[128:131], v[2:5]
	v_mfma_f32_16x16x32_bf16 v[6:9], v[10:13], v[124:127], 0
	v_mfma_f32_16x16x32_bf16 v[164:167], v[10:13], v[62:65], 0
	v_mfma_f32_16x16x32_bf16 v[172:175], v[10:13], v[94:97], 0
	v_mfma_f32_16x16x32_bf16 v[180:183], v[10:13], v[112:115], 0
	v_mfma_f32_16x16x32_bf16 v[6:9], v[14:17], v[128:131], v[6:9]
	v_mfma_f32_16x16x32_bf16 v[164:167], v[14:17], v[90:93], v[164:167]
	v_mfma_f32_16x16x32_bf16 v[172:175], v[14:17], v[108:111], v[172:175]
	v_mfma_f32_16x16x32_bf16 v[180:183], v[14:17], v[120:123], v[180:183]
	v_mfma_f32_16x16x32_bf16 v[10:13], v[18:21], v[62:65], 0
	v_mfma_f32_16x16x32_bf16 v[184:187], v[22:25], v[90:93], v[10:13]
	v_mfma_f32_16x16x32_bf16 v[10:13], v[26:29], v[62:65], 0
	v_mfma_f32_16x16x32_bf16 v[188:191], v[30:33], v[90:93], v[10:13]
	v_mfma_f32_16x16x32_bf16 v[10:13], v[18:21], v[94:97], 0
	v_mfma_f32_16x16x32_bf16 v[192:195], v[22:25], v[108:111], v[10:13]
	v_mfma_f32_16x16x32_bf16 v[10:13], v[26:29], v[94:97], 0
	v_mfma_f32_16x16x32_bf16 v[196:199], v[30:33], v[108:111], v[10:13]
	v_mfma_f32_16x16x32_bf16 v[10:13], v[18:21], v[112:115], 0
	v_mfma_f32_16x16x32_bf16 v[200:203], v[22:25], v[120:123], v[10:13]
	v_mfma_f32_16x16x32_bf16 v[10:13], v[26:29], v[112:115], 0
	v_mfma_f32_16x16x32_bf16 v[204:207], v[30:33], v[120:123], v[10:13]
	v_mfma_f32_16x16x32_bf16 v[10:13], v[18:21], v[124:127], 0
	v_mfma_f32_16x16x32_bf16 v[208:211], v[22:25], v[128:131], v[10:13]
	v_mfma_f32_16x16x32_bf16 v[10:13], v[26:29], v[124:127], 0
	v_mfma_f32_16x16x32_bf16 v[212:215], v[30:33], v[128:131], v[10:13]
	s_barrier
	s_add_i32 s12, 0, 0x18000
	v_add_u32_e32 v0, s12, v154
	s_add_i32 s13, 0, 0x1c000
	s_nop 1
	ds_read_b128 v[10:13], v0
	ds_read_b128 v[14:17], v0 offset:1024
	ds_read_b128 v[20:23], v0 offset:2048
	ds_read_b128 v[24:27], v0 offset:3072
	v_add_u32_e32 v0, s13, v154
	ds_read_b128 v[216:219], v0
	ds_read_b128 v[220:223], v0 offset:1024
	ds_read_b128 v[224:227], v0 offset:2048
	ds_read_b128 v[228:231], v0 offset:3072
	s_add_u32 s0, s6, 0x100100
	s_addc_u32 s1, s7, 0
	s_mov_b32 m0, s25
	v_lshl_add_u64 v[18:19], s[0:1], 0, v[132:133]
	ds_read_b128 v[28:31], v157 offset:32768
	ds_read_b128 v[62:65], v157 offset:33792
	ds_read_b128 v[232:235], v157 offset:34816
	ds_read_b128 v[236:239], v157 offset:35840
	ds_read_b128 v[240:243], v157 offset:36864
	ds_read_b128 v[244:247], v157 offset:37888
	ds_read_b128 v[248:251], v157 offset:38912
	ds_read_b128 v[146:149], v157 offset:39936
	global_load_lds_dwordx4 v[18:19], off
	s_mov_b32 m0, s33
	v_lshl_add_u64 v[18:19], s[0:1], 0, v[136:137]
	global_load_lds_dwordx4 v[18:19], off
	s_waitcnt vmcnt(24) lgkmcnt(0)
	s_barrier
	v_mfma_f32_16x16x32_bf16 v[66:69], v[10:13], v[28:31], v[66:69]
	v_mfma_f32_16x16x32_bf16 v[128:131], v[14:17], v[62:65], v[66:69]
	v_mfma_f32_16x16x32_bf16 v[66:69], v[20:23], v[28:31], v[70:73]
	v_mfma_f32_16x16x32_bf16 v[124:127], v[24:27], v[62:65], v[66:69]
	v_mfma_f32_16x16x32_bf16 v[66:69], v[10:13], v[232:235], v[74:77]
	v_mfma_f32_16x16x32_bf16 v[112:115], v[14:17], v[236:239], v[66:69]
	v_mfma_f32_16x16x32_bf16 v[66:69], v[20:23], v[232:235], v[78:81]
	v_mfma_f32_16x16x32_bf16 v[108:111], v[24:27], v[236:239], v[66:69]
	v_mfma_f32_16x16x32_bf16 v[66:69], v[10:13], v[240:243], v[82:85]
	v_mfma_f32_16x16x32_bf16 v[96:99], v[14:17], v[244:247], v[66:69]
	v_mfma_f32_16x16x32_bf16 v[66:69], v[20:23], v[240:243], v[86:89]
	v_mfma_f32_16x16x32_bf16 v[92:95], v[24:27], v[244:247], v[66:69]
	v_mfma_f32_16x16x32_bf16 v[66:69], v[10:13], v[248:251], v[100:103]
	v_mfma_f32_16x16x32_bf16 v[80:83], v[14:17], v[146:149], v[66:69]
	v_mfma_f32_16x16x32_bf16 v[66:69], v[20:23], v[248:251], v[104:107]
	v_mfma_f32_16x16x32_bf16 v[76:79], v[24:27], v[146:149], v[66:69]
	v_mfma_f32_16x16x32_bf16 v[66:69], v[216:219], v[28:31], v[116:119]
	v_mfma_f32_16x16x32_bf16 v[28:31], v[224:227], v[28:31], v[34:37]
	v_mfma_f32_16x16x32_bf16 v[116:119], v[228:231], v[62:65], v[28:31]
	v_mfma_f32_16x16x32_bf16 v[28:31], v[216:219], v[232:235], v[38:41]
	v_mfma_f32_16x16x32_bf16 v[104:107], v[220:223], v[236:239], v[28:31]
	v_mfma_f32_16x16x32_bf16 v[28:31], v[224:227], v[232:235], v[42:45]
	v_mfma_f32_16x16x32_bf16 v[100:103], v[228:231], v[236:239], v[28:31]
	v_mfma_f32_16x16x32_bf16 v[28:31], v[216:219], v[240:243], v[46:49]
	v_mfma_f32_16x16x32_bf16 v[88:91], v[220:223], v[244:247], v[28:31]
	v_mfma_f32_16x16x32_bf16 v[28:31], v[224:227], v[240:243], v[50:53]
	v_mfma_f32_16x16x32_bf16 v[84:87], v[228:231], v[244:247], v[28:31]
	v_mfma_f32_16x16x32_bf16 v[28:31], v[216:219], v[248:251], v[54:57]
	v_mfma_f32_16x16x32_bf16 v[120:123], v[220:223], v[62:65], v[66:69]
	v_mfma_f32_16x16x32_bf16 v[64:67], v[220:223], v[146:149], v[28:31]
	v_mfma_f32_16x16x32_bf16 v[28:31], v[224:227], v[248:251], v[58:61]
	v_mfma_f32_16x16x32_bf16 v[60:63], v[228:231], v[146:149], v[28:31]
	s_barrier
	s_add_u32 s0, s52, 0x18000
	s_addc_u32 s1, s53, 0
	s_add_i32 s12, s12, s20
	v_lshl_add_u64 v[18:19], s[0:1], 0, v[134:135]
	s_mov_b32 m0, s12
	ds_read_b128 v[36:39], v157 offset:49152
	ds_read_b128 v[40:43], v157 offset:50176
	ds_read_b128 v[146:149], v157 offset:51200
	ds_read_b128 v[232:235], v157 offset:52224
	ds_read_b128 v[236:239], v157 offset:53248
	ds_read_b128 v[240:243], v157 offset:54272
	ds_read_b128 v[244:247], v157 offset:55296
	ds_read_b128 v[248:251], v157 offset:56320
	global_load_lds_dwordx4 v[18:19], off
	s_add_i32 m0, s12, 0x2000
	v_lshl_add_u64 v[18:19], s[0:1], 0, v[138:139]
	s_add_u32 s0, s52, 0x1c000
	s_addc_u32 s1, s53, 0
	s_add_i32 s12, s13, s20
	global_load_lds_dwordx4 v[18:19], off
	s_mov_b32 m0, s12
	v_lshl_add_u64 v[18:19], s[0:1], 0, v[134:135]
	global_load_lds_dwordx4 v[18:19], off
	s_add_i32 m0, s12, 0x2000
	v_lshl_add_u64 v[18:19], s[0:1], 0, v[138:139]
	global_load_lds_dwordx4 v[18:19], off
	s_mov_b32 m0, s54
	v_lshl_add_u64 v[18:19], v[150:151], 0, s[38:39]
	global_load_lds_dwordx4 v[18:19], off
	s_mov_b32 m0, s55
	v_lshl_add_u64 v[18:19], v[252:253], 0, s[38:39]
	global_load_lds_dwordx4 v[18:19], off
	s_waitcnt vmcnt(8) lgkmcnt(0)
	s_barrier
	v_mfma_f32_16x16x32_bf16 v[28:31], v[10:13], v[36:39], v[160:163]
	v_mfma_f32_16x16x32_bf16 v[72:75], v[14:17], v[40:43], v[28:31]
	v_mfma_f32_16x16x32_bf16 v[28:31], v[20:23], v[36:39], v[164:167]
	v_mfma_f32_16x16x32_bf16 v[68:71], v[24:27], v[40:43], v[28:31]
	v_mfma_f32_16x16x32_bf16 v[28:31], v[10:13], v[146:149], v[168:171]
	v_mfma_f32_16x16x32_bf16 v[48:51], v[14:17], v[232:235], v[28:31]
	v_mfma_f32_16x16x32_bf16 v[28:31], v[20:23], v[146:149], v[172:175]
	v_mfma_f32_16x16x32_bf16 v[44:47], v[24:27], v[232:235], v[28:31]
	v_mfma_f32_16x16x32_bf16 v[28:31], v[10:13], v[236:239], v[176:179]
	v_mfma_f32_16x16x32_bf16 v[2:5], v[10:13], v[244:247], v[2:5]
	v_mfma_f32_16x16x32_bf16 v[32:35], v[14:17], v[240:243], v[28:31]
	v_mfma_f32_16x16x32_bf16 v[28:31], v[20:23], v[236:239], v[180:183]
	v_mfma_f32_16x16x32_bf16 v[16:19], v[14:17], v[248:251], v[2:5]
	v_mfma_f32_16x16x32_bf16 v[2:5], v[20:23], v[244:247], v[6:9]
	v_mfma_f32_16x16x32_bf16 v[28:31], v[24:27], v[240:243], v[28:31]
	v_mfma_f32_16x16x32_bf16 v[12:15], v[24:27], v[248:251], v[2:5]
	v_mfma_f32_16x16x32_bf16 v[2:5], v[216:219], v[36:39], v[184:187]
	v_mfma_f32_16x16x32_bf16 v[56:59], v[220:223], v[40:43], v[2:5]
	v_mfma_f32_16x16x32_bf16 v[2:5], v[224:227], v[36:39], v[188:191]
	v_mfma_f32_16x16x32_bf16 v[52:55], v[228:231], v[40:43], v[2:5]
	v_mfma_f32_16x16x32_bf16 v[2:5], v[216:219], v[146:149], v[192:195]
	v_mfma_f32_16x16x32_bf16 v[40:43], v[220:223], v[232:235], v[2:5]
	v_mfma_f32_16x16x32_bf16 v[2:5], v[224:227], v[146:149], v[196:199]
	v_mfma_f32_16x16x32_bf16 v[36:39], v[228:231], v[232:235], v[2:5]
	v_mfma_f32_16x16x32_bf16 v[2:5], v[216:219], v[236:239], v[200:203]
	v_mfma_f32_16x16x32_bf16 v[24:27], v[220:223], v[240:243], v[2:5]
	v_mfma_f32_16x16x32_bf16 v[2:5], v[224:227], v[236:239], v[204:207]
	v_mfma_f32_16x16x32_bf16 v[20:23], v[228:231], v[240:243], v[2:5]
	v_mfma_f32_16x16x32_bf16 v[2:5], v[216:219], v[244:247], v[208:211]
	v_mfma_f32_16x16x32_bf16 v[8:11], v[220:223], v[248:251], v[2:5]
	v_mfma_f32_16x16x32_bf16 v[2:5], v[224:227], v[244:247], v[212:215]
	v_mfma_f32_16x16x32_bf16 v[4:7], v[228:231], v[248:251], v[2:5]
	s_barrier
	s_mov_b32 s22, 2
	s_branch .LBB0_1052

.LBB0_1053:
	ds_read_b128 v[146:149], v155
	ds_read_b128 v[160:163], v155 offset:1024
	ds_read_b128 v[164:167], v155 offset:2048
	ds_read_b128 v[168:171], v155 offset:3072
	ds_read_b128 v[172:175], v156
	ds_read_b128 v[176:179], v156 offset:1024
	ds_read_b128 v[180:183], v156 offset:2048
	ds_read_b128 v[184:187], v156 offset:3072
	s_add_u32 s12, s68, s30
	s_addc_u32 s13, s69, 0
	s_cmp_eq_u32 s30, s6
	s_cselect_b32 s23, s0, s13
	s_cselect_b32 s22, s1, s12
	s_cselect_b32 s53, s41, s67
	s_cselect_b32 s52, s64, s66
	s_add_i32 s71, s21, 0xc000
	v_lshl_add_u64 v[220:221], v[2:3], 0, s[30:31]
	s_mov_b32 m0, s71
	s_add_i32 s70, s21, 0xe000
	ds_read_b128 v[188:191], v157
	ds_read_b128 v[192:195], v157 offset:1024
	ds_read_b128 v[196:199], v157 offset:2048
	ds_read_b128 v[200:203], v157 offset:3072
	ds_read_b128 v[204:207], v157 offset:4096
	ds_read_b128 v[208:211], v157 offset:5120
	ds_read_b128 v[212:215], v157 offset:6144
	ds_read_b128 v[216:219], v157 offset:7168
	global_load_lds_dwordx4 v[220:221], off
	s_mov_b32 m0, s70
	v_lshl_add_u64 v[220:221], v[150:151], 0, s[30:31]
	global_load_lds_dwordx4 v[220:221], off
	s_waitcnt vmcnt(8) lgkmcnt(0)
	s_barrier
	v_mfma_f32_16x16x32_bf16 v[128:131], v[146:149], v[188:191], v[128:131]
	v_mfma_f32_16x16x32_bf16 v[128:131], v[160:163], v[192:195], v[128:131]
	v_mfma_f32_16x16x32_bf16 v[124:127], v[164:167], v[188:191], v[124:127]
	v_mfma_f32_16x16x32_bf16 v[124:127], v[168:171], v[192:195], v[124:127]
	v_mfma_f32_16x16x32_bf16 v[108:111], v[164:167], v[196:199], v[108:111]
	v_mfma_f32_16x16x32_bf16 v[108:111], v[168:171], v[200:203], v[108:111]
	v_mfma_f32_16x16x32_bf16 v[112:115], v[146:149], v[196:199], v[112:115]
	v_mfma_f32_16x16x32_bf16 v[112:115], v[160:163], v[200:203], v[112:115]
	v_mfma_f32_16x16x32_bf16 v[96:99], v[146:149], v[204:207], v[96:99]
	v_mfma_f32_16x16x32_bf16 v[96:99], v[160:163], v[208:211], v[96:99]
	v_mfma_f32_16x16x32_bf16 v[92:95], v[164:167], v[204:207], v[92:95]
	v_mfma_f32_16x16x32_bf16 v[92:95], v[168:171], v[208:211], v[92:95]
	v_mfma_f32_16x16x32_bf16 v[76:79], v[164:167], v[212:215], v[76:79]
	v_mfma_f32_16x16x32_bf16 v[76:79], v[168:171], v[216:219], v[76:79]
	v_mfma_f32_16x16x32_bf16 v[80:83], v[146:149], v[212:215], v[80:83]
	v_mfma_f32_16x16x32_bf16 v[80:83], v[160:163], v[216:219], v[80:83]
	v_mfma_f32_16x16x32_bf16 v[64:67], v[172:175], v[212:215], v[64:67]
	v_mfma_f32_16x16x32_bf16 v[64:67], v[176:179], v[216:219], v[64:67]
	v_mfma_f32_16x16x32_bf16 v[60:63], v[180:183], v[212:215], v[60:63]
	v_mfma_f32_16x16x32_bf16 v[60:63], v[184:187], v[216:219], v[60:63]
	v_mfma_f32_16x16x32_bf16 v[84:87], v[180:183], v[204:207], v[84:87]
	v_mfma_f32_16x16x32_bf16 v[84:87], v[184:187], v[208:211], v[84:87]
	v_mfma_f32_16x16x32_bf16 v[88:91], v[172:175], v[204:207], v[88:91]
	v_mfma_f32_16x16x32_bf16 v[88:91], v[176:179], v[208:211], v[88:91]
	v_mfma_f32_16x16x32_bf16 v[104:107], v[172:175], v[196:199], v[104:107]
	v_mfma_f32_16x16x32_bf16 v[104:107], v[176:179], v[200:203], v[104:107]
	v_mfma_f32_16x16x32_bf16 v[100:103], v[180:183], v[196:199], v[100:103]
	v_mfma_f32_16x16x32_bf16 v[100:103], v[184:187], v[200:203], v[100:103]
	v_mfma_f32_16x16x32_bf16 v[116:119], v[180:183], v[188:191], v[116:119]
	v_mfma_f32_16x16x32_bf16 v[116:119], v[184:187], v[192:195], v[116:119]
	v_mfma_f32_16x16x32_bf16 v[120:123], v[172:175], v[188:191], v[120:123]
	v_mfma_f32_16x16x32_bf16 v[120:123], v[176:179], v[192:195], v[120:123]
	s_barrier
	s_add_i32 s12, s58, s20
	v_lshl_add_u64 v[220:221], s[52:53], 0, v[134:135]
	s_mov_b32 m0, s12
	ds_read_b128 v[188:191], v157 offset:16384
	ds_read_b128 v[192:195], v157 offset:17408
	ds_read_b128 v[196:199], v157 offset:18432
	ds_read_b128 v[200:203], v157 offset:19456
	ds_read_b128 v[204:207], v157 offset:20480
	ds_read_b128 v[208:211], v157 offset:21504
	ds_read_b128 v[212:215], v157 offset:22528
	ds_read_b128 v[216:219], v157 offset:23552
	global_load_lds_dwordx4 v[220:221], off
	s_add_i32 m0, s12, 0x2000
	s_add_u32 s12, s52, 0x4000
	v_lshl_add_u64 v[220:221], s[52:53], 0, v[138:139]
	s_addc_u32 s13, s53, 0
	s_add_i32 s14, s59, s20
	global_load_lds_dwordx4 v[220:221], off
	v_lshl_add_u64 v[220:221], s[12:13], 0, v[134:135]
	s_mov_b32 m0, s14
	v_lshl_add_u64 v[222:223], s[22:23], 0, v[136:137]
	global_load_lds_dwordx4 v[220:221], off
	s_add_i32 m0, s14, 0x2000
	v_lshl_add_u64 v[220:221], s[12:13], 0, v[138:139]
	global_load_lds_dwordx4 v[220:221], off
	s_mov_b32 m0, s21
	v_lshl_add_u64 v[220:221], s[22:23], 0, v[132:133]
	global_load_lds_dwordx4 v[220:221], off
	s_mov_b32 m0, s24
	s_nop 0
	global_load_lds_dwordx4 v[222:223], off
	s_waitcnt vmcnt(8) lgkmcnt(0)
	s_barrier
	v_mfma_f32_16x16x32_bf16 v[72:75], v[146:149], v[188:191], v[72:75]
	v_mfma_f32_16x16x32_bf16 v[72:75], v[160:163], v[192:195], v[72:75]
	v_mfma_f32_16x16x32_bf16 v[68:71], v[164:167], v[188:191], v[68:71]
	v_mfma_f32_16x16x32_bf16 v[68:71], v[168:171], v[192:195], v[68:71]
	v_mfma_f32_16x16x32_bf16 v[44:47], v[164:167], v[196:199], v[44:47]
	v_mfma_f32_16x16x32_bf16 v[44:47], v[168:171], v[200:203], v[44:47]
	v_mfma_f32_16x16x32_bf16 v[48:51], v[146:149], v[196:199], v[48:51]
	v_mfma_f32_16x16x32_bf16 v[48:51], v[160:163], v[200:203], v[48:51]
	v_mfma_f32_16x16x32_bf16 v[32:35], v[146:149], v[204:207], v[32:35]
	v_mfma_f32_16x16x32_bf16 v[32:35], v[160:163], v[208:211], v[32:35]
	v_mfma_f32_16x16x32_bf16 v[28:31], v[164:167], v[204:207], v[28:31]
	v_mfma_f32_16x16x32_bf16 v[28:31], v[168:171], v[208:211], v[28:31]
	v_mfma_f32_16x16x32_bf16 v[12:15], v[164:167], v[212:215], v[12:15]
	v_mfma_f32_16x16x32_bf16 v[12:15], v[168:171], v[216:219], v[12:15]
	v_mfma_f32_16x16x32_bf16 v[16:19], v[146:149], v[212:215], v[16:19]
	v_mfma_f32_16x16x32_bf16 v[16:19], v[160:163], v[216:219], v[16:19]
	v_mfma_f32_16x16x32_bf16 v[8:11], v[172:175], v[212:215], v[8:11]
	v_mfma_f32_16x16x32_bf16 v[8:11], v[176:179], v[216:219], v[8:11]
	v_mfma_f32_16x16x32_bf16 v[4:7], v[180:183], v[212:215], v[4:7]
	v_mfma_f32_16x16x32_bf16 v[4:7], v[184:187], v[216:219], v[4:7]
	v_mfma_f32_16x16x32_bf16 v[20:23], v[180:183], v[204:207], v[20:23]
	v_mfma_f32_16x16x32_bf16 v[20:23], v[184:187], v[208:211], v[20:23]
	v_mfma_f32_16x16x32_bf16 v[24:27], v[172:175], v[204:207], v[24:27]
	v_mfma_f32_16x16x32_bf16 v[24:27], v[176:179], v[208:211], v[24:27]
	v_mfma_f32_16x16x32_bf16 v[40:43], v[172:175], v[196:199], v[40:43]
	v_mfma_f32_16x16x32_bf16 v[40:43], v[176:179], v[200:203], v[40:43]
	v_mfma_f32_16x16x32_bf16 v[36:39], v[180:183], v[196:199], v[36:39]
	v_mfma_f32_16x16x32_bf16 v[36:39], v[184:187], v[200:203], v[36:39]
	v_mfma_f32_16x16x32_bf16 v[52:55], v[180:183], v[188:191], v[52:55]
	v_mfma_f32_16x16x32_bf16 v[52:55], v[184:187], v[192:195], v[52:55]
	v_mfma_f32_16x16x32_bf16 v[56:59], v[172:175], v[188:191], v[56:59]
	v_mfma_f32_16x16x32_bf16 v[56:59], v[176:179], v[192:195], v[56:59]
	s_barrier
	s_add_i32 s14, 0, 0x18000
	v_add_u32_e32 v0, s14, v154
	s_add_i32 s72, 0, 0x1c000
	ds_read_b128 v[146:149], v0
	ds_read_b128 v[160:163], v0 offset:1024
	ds_read_b128 v[164:167], v0 offset:2048
	ds_read_b128 v[168:171], v0 offset:3072
	v_add_u32_e32 v0, s72, v154
	ds_read_b128 v[172:175], v0
	ds_read_b128 v[176:179], v0 offset:1024
	ds_read_b128 v[180:183], v0 offset:2048
	ds_read_b128 v[184:187], v0 offset:3072
	s_add_u32 s12, s22, 0x100000
	s_addc_u32 s13, s23, 0
	s_mov_b32 m0, s25
	v_lshl_add_u64 v[224:225], s[12:13], 0, v[132:133]
	ds_read_b128 v[188:191], v157 offset:32768
	ds_read_b128 v[192:195], v157 offset:33792
	ds_read_b128 v[196:199], v157 offset:34816
	ds_read_b128 v[200:203], v157 offset:35840
	ds_read_b128 v[204:207], v157 offset:36864
	ds_read_b128 v[208:211], v157 offset:37888
	ds_read_b128 v[212:215], v157 offset:38912
	ds_read_b128 v[216:219], v157 offset:39936
	global_load_lds_dwordx4 v[224:225], off
	s_mov_b32 m0, s33
	v_lshl_add_u64 v[224:225], s[12:13], 0, v[136:137]
	global_load_lds_dwordx4 v[224:225], off
	s_waitcnt vmcnt(8) lgkmcnt(0)
	s_barrier
	v_mfma_f32_16x16x32_bf16 v[128:131], v[146:149], v[188:191], v[128:131]
	v_mfma_f32_16x16x32_bf16 v[128:131], v[160:163], v[192:195], v[128:131]
	v_mfma_f32_16x16x32_bf16 v[124:127], v[164:167], v[188:191], v[124:127]
	v_mfma_f32_16x16x32_bf16 v[124:127], v[168:171], v[192:195], v[124:127]
	v_mfma_f32_16x16x32_bf16 v[108:111], v[164:167], v[196:199], v[108:111]
	v_mfma_f32_16x16x32_bf16 v[108:111], v[168:171], v[200:203], v[108:111]
	v_mfma_f32_16x16x32_bf16 v[112:115], v[146:149], v[196:199], v[112:115]
	v_mfma_f32_16x16x32_bf16 v[112:115], v[160:163], v[200:203], v[112:115]
	v_mfma_f32_16x16x32_bf16 v[96:99], v[146:149], v[204:207], v[96:99]
	v_mfma_f32_16x16x32_bf16 v[96:99], v[160:163], v[208:211], v[96:99]
	v_mfma_f32_16x16x32_bf16 v[92:95], v[164:167], v[204:207], v[92:95]
	v_mfma_f32_16x16x32_bf16 v[92:95], v[168:171], v[208:211], v[92:95]
	v_mfma_f32_16x16x32_bf16 v[76:79], v[164:167], v[212:215], v[76:79]
	v_mfma_f32_16x16x32_bf16 v[76:79], v[168:171], v[216:219], v[76:79]
	v_mfma_f32_16x16x32_bf16 v[80:83], v[146:149], v[212:215], v[80:83]
	v_mfma_f32_16x16x32_bf16 v[80:83], v[160:163], v[216:219], v[80:83]
	v_mfma_f32_16x16x32_bf16 v[64:67], v[172:175], v[212:215], v[64:67]
	v_mfma_f32_16x16x32_bf16 v[64:67], v[176:179], v[216:219], v[64:67]
	v_mfma_f32_16x16x32_bf16 v[60:63], v[180:183], v[212:215], v[60:63]
	v_mfma_f32_16x16x32_bf16 v[60:63], v[184:187], v[216:219], v[60:63]
	v_mfma_f32_16x16x32_bf16 v[84:87], v[180:183], v[204:207], v[84:87]
	v_mfma_f32_16x16x32_bf16 v[84:87], v[184:187], v[208:211], v[84:87]
	v_mfma_f32_16x16x32_bf16 v[88:91], v[172:175], v[204:207], v[88:91]
	v_mfma_f32_16x16x32_bf16 v[88:91], v[176:179], v[208:211], v[88:91]
	v_mfma_f32_16x16x32_bf16 v[104:107], v[172:175], v[196:199], v[104:107]
	v_mfma_f32_16x16x32_bf16 v[104:107], v[176:179], v[200:203], v[104:107]
	v_mfma_f32_16x16x32_bf16 v[100:103], v[180:183], v[196:199], v[100:103]
	v_mfma_f32_16x16x32_bf16 v[100:103], v[184:187], v[200:203], v[100:103]
	v_mfma_f32_16x16x32_bf16 v[116:119], v[180:183], v[188:191], v[116:119]
	v_mfma_f32_16x16x32_bf16 v[116:119], v[184:187], v[192:195], v[116:119]
	v_mfma_f32_16x16x32_bf16 v[120:123], v[172:175], v[188:191], v[120:123]
	v_mfma_f32_16x16x32_bf16 v[120:123], v[176:179], v[192:195], v[120:123]
	s_barrier
	s_add_u32 s12, s52, 0x8000
	s_addc_u32 s13, s53, 0
	s_add_i32 s14, s14, s20
	v_lshl_add_u64 v[224:225], s[12:13], 0, v[134:135]
	s_mov_b32 m0, s14
	ds_read_b128 v[188:191], v157 offset:49152
	ds_read_b128 v[192:195], v157 offset:50176
	ds_read_b128 v[196:199], v157 offset:51200
	ds_read_b128 v[200:203], v157 offset:52224
	ds_read_b128 v[204:207], v157 offset:53248
	ds_read_b128 v[208:211], v157 offset:54272
	ds_read_b128 v[212:215], v157 offset:55296
	ds_read_b128 v[216:219], v157 offset:56320
	global_load_lds_dwordx4 v[224:225], off
	s_add_i32 m0, s14, 0x2000
	v_lshl_add_u64 v[224:225], s[12:13], 0, v[138:139]
	s_add_u32 s12, s52, 0xc000
	s_addc_u32 s13, s53, 0
	s_add_i32 s14, s72, s20
	global_load_lds_dwordx4 v[224:225], off
	v_lshl_add_u64 v[224:225], s[12:13], 0, v[134:135]
	s_mov_b32 m0, s14
	v_lshl_add_u64 v[220:221], v[220:221], 0, s[28:29]
	global_load_lds_dwordx4 v[224:225], off
	s_add_i32 m0, s14, 0x2000
	v_lshl_add_u64 v[224:225], s[12:13], 0, v[138:139]
	global_load_lds_dwordx4 v[224:225], off
	s_mov_b32 m0, s54
	s_nop 0
	global_load_lds_dwordx4 v[220:221], off
	s_mov_b32 m0, s55
	v_lshl_add_u64 v[220:221], v[222:223], 0, s[28:29]
	global_load_lds_dwordx4 v[220:221], off
	s_waitcnt vmcnt(8) lgkmcnt(0)
	s_barrier
	v_mfma_f32_16x16x32_bf16 v[72:75], v[146:149], v[188:191], v[72:75]
	v_mfma_f32_16x16x32_bf16 v[72:75], v[160:163], v[192:195], v[72:75]
	v_mfma_f32_16x16x32_bf16 v[68:71], v[164:167], v[188:191], v[68:71]
	v_mfma_f32_16x16x32_bf16 v[68:71], v[168:171], v[192:195], v[68:71]
	v_mfma_f32_16x16x32_bf16 v[44:47], v[164:167], v[196:199], v[44:47]
	v_mfma_f32_16x16x32_bf16 v[44:47], v[168:171], v[200:203], v[44:47]
	v_mfma_f32_16x16x32_bf16 v[48:51], v[146:149], v[196:199], v[48:51]
	v_mfma_f32_16x16x32_bf16 v[48:51], v[160:163], v[200:203], v[48:51]
	v_mfma_f32_16x16x32_bf16 v[32:35], v[146:149], v[204:207], v[32:35]
	v_mfma_f32_16x16x32_bf16 v[32:35], v[160:163], v[208:211], v[32:35]
	v_mfma_f32_16x16x32_bf16 v[28:31], v[164:167], v[204:207], v[28:31]
	v_mfma_f32_16x16x32_bf16 v[28:31], v[168:171], v[208:211], v[28:31]
	v_mfma_f32_16x16x32_bf16 v[12:15], v[164:167], v[212:215], v[12:15]
	v_mfma_f32_16x16x32_bf16 v[12:15], v[168:171], v[216:219], v[12:15]
	v_mfma_f32_16x16x32_bf16 v[16:19], v[146:149], v[212:215], v[16:19]
	v_mfma_f32_16x16x32_bf16 v[16:19], v[160:163], v[216:219], v[16:19]
	v_mfma_f32_16x16x32_bf16 v[8:11], v[172:175], v[212:215], v[8:11]
	v_mfma_f32_16x16x32_bf16 v[8:11], v[176:179], v[216:219], v[8:11]
	v_mfma_f32_16x16x32_bf16 v[4:7], v[180:183], v[212:215], v[4:7]
	v_mfma_f32_16x16x32_bf16 v[4:7], v[184:187], v[216:219], v[4:7]
	v_mfma_f32_16x16x32_bf16 v[20:23], v[180:183], v[204:207], v[20:23]
	v_mfma_f32_16x16x32_bf16 v[20:23], v[184:187], v[208:211], v[20:23]
	v_mfma_f32_16x16x32_bf16 v[24:27], v[172:175], v[204:207], v[24:27]
	v_mfma_f32_16x16x32_bf16 v[24:27], v[176:179], v[208:211], v[24:27]
	v_mfma_f32_16x16x32_bf16 v[40:43], v[172:175], v[196:199], v[40:43]
	v_mfma_f32_16x16x32_bf16 v[40:43], v[176:179], v[200:203], v[40:43]
	v_mfma_f32_16x16x32_bf16 v[36:39], v[180:183], v[196:199], v[36:39]
	v_mfma_f32_16x16x32_bf16 v[36:39], v[184:187], v[200:203], v[36:39]
	v_mfma_f32_16x16x32_bf16 v[52:55], v[180:183], v[188:191], v[52:55]
	v_mfma_f32_16x16x32_bf16 v[52:55], v[184:187], v[192:195], v[52:55]
	v_mfma_f32_16x16x32_bf16 v[56:59], v[172:175], v[188:191], v[56:59]
	v_mfma_f32_16x16x32_bf16 v[56:59], v[176:179], v[192:195], v[56:59]
	s_barrier
	s_add_i32 s65, s65, 2
	s_add_u32 s66, s66, 0x10000
	s_addc_u32 s67, s67, 0
	s_add_u32 s68, s68, 0x100
	s_addc_u32 s69, s69, 0
	s_add_u32 s6, s6, 0xffffff00
	s_addc_u32 s7, s7, -1
	v_lshl_add_u64 v[2:3], v[2:3], 0, s[36:37]
	s_cmp_gt_u32 s65, 61
	v_lshl_add_u64 v[150:151], v[150:151], 0, s[36:37]
	s_cbranch_scc0 .LBB0_1053
	s_and_b64 vcc, exec, s[34:35]
	s_cbranch_vccnz .LBB0_1061
	s_and_b64 s[0:1], s[10:11], s[4:5]
	s_andn2_b64 vcc, exec, s[0:1]
	s_cbranch_vccz .LBB0_1062

.LBB0_1139:
	s_or_b32 s0, s18, 1
	s_cmp_ge_u32 s0, s16
	s_cbranch_scc1 .LBB0_1141
	s_add_u32 s0, s8, s76
	s_addc_u32 s1, s9, s77
	v_lshl_add_u64 v[192:193], s[0:1], 0, v[250:251]
	v_lshl_add_u64 v[194:195], v[192:193], 0, s[30:31]
	s_add_i32 m0, s83, 0x14000
	v_lshl_add_u64 v[192:193], v[192:193], 0, s[34:35]
	global_load_lds_dwordx4 v[194:195], off
	s_add_i32 m0, s83, 0x16000
	s_nop 0
	global_load_lds_dwordx4 v[192:193], off
	s_add_u32 s0, s86, s76
	s_addc_u32 s1, s90, s77
	v_lshl_add_u64 v[192:193], s[0:1], 0, v[252:253]
	s_add_i32 m0, s83, 0x8000
	v_lshl_add_u64 v[194:195], v[192:193], 0, s[36:37]
	global_load_lds_dwordx4 v[194:195], off
	s_add_i32 m0, s83, 0xa000
	v_lshl_add_u64 v[194:195], v[192:193], 0, s[38:39]
	global_load_lds_dwordx4 v[194:195], off
	v_lshl_add_u64 v[194:195], v[192:193], 0, s[40:41]
	s_add_i32 m0, s83, 0xc000
	v_lshl_add_u64 v[192:193], v[192:193], 0, s[42:43]
	global_load_lds_dwordx4 v[194:195], off
	s_add_i32 m0, s83, 0xe000
	s_nop 0
	global_load_lds_dwordx4 v[192:193], off

.LBB0_1148:
	ds_read_b128 v[202:205], v227 offset:0x7000
	ds_read_b128 v[206:209], v227 offset:0x7800
	s_waitcnt lgkmcnt(4)
	ds_read_b128 v[220:223], v227 offset:0x7400
	v_mfma_f32_16x16x32_bf16 v[210:213], v[192:195], v[0:3], v[176:179]
	ds_read_b128 v[230:233], v227 offset:0x7c00
	s_waitcnt lgkmcnt(4)
	v_mfma_f32_16x16x32_bf16 v[192:195], v[192:195], v[16:19], v[180:183]
	v_mfma_f32_16x16x32_bf16 v[176:179], v[188:191], v[0:3], v[176:179]
	v_mfma_f32_16x16x32_bf16 v[180:183], v[188:191], v[16:19], v[180:183]
	v_mfma_f32_16x16x32_bf16 v[188:191], v[196:199], v[4:7], v[210:213]
	s_waitcnt lgkmcnt(2)
	v_mfma_f32_16x16x32_bf16 v[176:179], v[184:187], v[4:7], v[176:179]
	v_mfma_f32_16x16x32_bf16 v[180:183], v[184:187], v[20:23], v[180:183]
	v_mfma_f32_16x16x32_bf16 v[192:195], v[196:199], v[20:23], v[192:195]
	v_mfma_f32_16x16x32_bf16 v[184:187], v[202:205], v[8:11], v[188:191]
	s_waitcnt lgkmcnt(0)
	v_mfma_f32_16x16x32_bf16 v[176:179], v[206:209], v[8:11], v[176:179]
	v_mfma_f32_16x16x32_bf16 v[192:195], v[202:205], v[24:27], v[192:195]
	v_mfma_f32_16x16x32_bf16 v[196:199], v[206:209], v[24:27], v[180:183]
	v_mfma_f32_16x16x32_bf16 v[188:191], v[220:223], v[12:15], v[184:187]
	v_mfma_f32_16x16x32_bf16 v[180:183], v[220:223], v[28:31], v[192:195]
	v_mfma_f32_16x16x32_bf16 v[184:187], v[230:233], v[12:15], v[176:179]
	v_mfma_f32_16x16x32_bf16 v[176:179], v[230:233], v[28:31], v[196:199]
	s_add_i32 s18, s18, 2
	s_cmp_ge_u32 s18, s16
	s_cselect_b64 s[4:5], -1, 0
	s_and_b64 vcc, exec, s[4:5]
	s_cbranch_vccnz .LBB0_1150
	s_add_u32 s0, s8, s76
	s_addc_u32 s1, s9, s77
	v_lshl_add_u64 v[192:193], s[0:1], 0, v[250:251]
	v_lshl_add_u64 v[194:195], v[192:193], 0, s[44:45]
	s_add_i32 m0, s83, 0x10000
	v_lshl_add_u64 v[192:193], v[192:193], 0, s[46:47]
	global_load_lds_dwordx4 v[194:195], off
	s_add_i32 m0, s83, 0x12000
	s_nop 0
	global_load_lds_dwordx4 v[192:193], off
	s_add_u32 s0, s86, s76
	s_addc_u32 s1, s90, s77
	v_lshl_add_u64 v[192:193], s[0:1], 0, v[252:253]
	s_mov_b32 m0, s83
	v_lshl_add_u64 v[194:195], v[192:193], 0, s[48:49]
	global_load_lds_dwordx4 v[194:195], off
	s_mov_b32 m0, s15
	v_lshl_add_u64 v[194:195], v[192:193], 0, s[50:51]
	global_load_lds_dwordx4 v[194:195], off
	v_lshl_add_u64 v[194:195], v[192:193], 0, s[52:53]
	s_mov_b32 m0, s20
	v_lshl_add_u64 v[192:193], v[192:193], 0, s[54:55]
	global_load_lds_dwordx4 v[194:195], off
	s_mov_b32 m0, s21
	s_nop 0
	global_load_lds_dwordx4 v[192:193], off

.LBB0_1175:
	s_or_b32 s0, s10, 1
	s_cmp_ge_u32 s0, s28
	s_cbranch_scc1 .LBB0_1177
	s_add_u32 s0, s8, s74
	s_addc_u32 s1, s9, s75
	v_lshl_add_u64 v[192:193], s[0:1], 0, v[250:251]
	v_lshl_add_u64 v[194:195], v[192:193], 0, s[30:31]
	s_add_i32 m0, s83, 0x14000
	v_lshl_add_u64 v[192:193], v[192:193], 0, s[34:35]
	global_load_lds_dwordx4 v[194:195], off
	s_add_i32 m0, s83, 0x16000
	s_nop 0
	global_load_lds_dwordx4 v[192:193], off
	s_add_u32 s0, s86, s74
	s_addc_u32 s1, s90, s75
	v_lshl_add_u64 v[192:193], s[0:1], 0, v[252:253]
	s_add_i32 m0, s83, 0x8000
	v_lshl_add_u64 v[194:195], v[192:193], 0, s[36:37]
	global_load_lds_dwordx4 v[194:195], off
	s_add_i32 m0, s83, 0xa000
	v_lshl_add_u64 v[194:195], v[192:193], 0, s[38:39]
	global_load_lds_dwordx4 v[194:195], off
	v_lshl_add_u64 v[194:195], v[192:193], 0, s[40:41]
	s_add_i32 m0, s83, 0xc000
	v_lshl_add_u64 v[192:193], v[192:193], 0, s[42:43]
	global_load_lds_dwordx4 v[194:195], off
	s_add_i32 m0, s83, 0xe000
	s_nop 0
	global_load_lds_dwordx4 v[192:193], off

.LBB0_1184:
	ds_read_b128 v[202:205], v227 offset:0x7000
	ds_read_b128 v[206:209], v227 offset:0x7800
	s_waitcnt lgkmcnt(4)
	ds_read_b128 v[220:223], v227 offset:0x7400
	v_mfma_f32_16x16x32_bf16 v[210:213], v[192:195], v[0:3], v[176:179]
	ds_read_b128 v[230:233], v227 offset:0x7c00
	s_waitcnt lgkmcnt(4)
	v_mfma_f32_16x16x32_bf16 v[192:195], v[192:195], v[16:19], v[180:183]
	v_mfma_f32_16x16x32_bf16 v[176:179], v[188:191], v[0:3], v[176:179]
	v_mfma_f32_16x16x32_bf16 v[180:183], v[188:191], v[16:19], v[180:183]
	v_mfma_f32_16x16x32_bf16 v[188:191], v[196:199], v[4:7], v[210:213]
	s_waitcnt lgkmcnt(2)
	v_mfma_f32_16x16x32_bf16 v[176:179], v[184:187], v[4:7], v[176:179]
	v_mfma_f32_16x16x32_bf16 v[180:183], v[184:187], v[20:23], v[180:183]
	v_mfma_f32_16x16x32_bf16 v[192:195], v[196:199], v[20:23], v[192:195]
	v_mfma_f32_16x16x32_bf16 v[184:187], v[202:205], v[8:11], v[188:191]
	s_waitcnt lgkmcnt(0)
	v_mfma_f32_16x16x32_bf16 v[176:179], v[206:209], v[8:11], v[176:179]
	v_mfma_f32_16x16x32_bf16 v[192:195], v[202:205], v[24:27], v[192:195]
	v_mfma_f32_16x16x32_bf16 v[196:199], v[206:209], v[24:27], v[180:183]
	v_mfma_f32_16x16x32_bf16 v[188:191], v[220:223], v[12:15], v[184:187]
	v_mfma_f32_16x16x32_bf16 v[180:183], v[220:223], v[28:31], v[192:195]
	v_mfma_f32_16x16x32_bf16 v[184:187], v[230:233], v[12:15], v[176:179]
	v_mfma_f32_16x16x32_bf16 v[176:179], v[230:233], v[28:31], v[196:199]
	s_add_i32 s10, s10, 2
	s_cmp_ge_u32 s10, s28
	s_cselect_b64 s[4:5], -1, 0
	s_and_b64 vcc, exec, s[4:5]
	s_cbranch_vccnz .LBB0_1186
	s_add_u32 s0, s8, s74
	s_addc_u32 s1, s9, s75
	v_lshl_add_u64 v[192:193], s[0:1], 0, v[250:251]
	v_lshl_add_u64 v[194:195], v[192:193], 0, s[44:45]
	s_add_i32 m0, s83, 0x10000
	v_lshl_add_u64 v[192:193], v[192:193], 0, s[46:47]
	global_load_lds_dwordx4 v[194:195], off
	s_add_i32 m0, s83, 0x12000
	s_nop 0
	global_load_lds_dwordx4 v[192:193], off
	s_add_u32 s0, s86, s74
	s_addc_u32 s1, s90, s75
	v_lshl_add_u64 v[192:193], s[0:1], 0, v[252:253]
	s_mov_b32 m0, s83
	v_lshl_add_u64 v[194:195], v[192:193], 0, s[48:49]
	global_load_lds_dwordx4 v[194:195], off
	s_mov_b32 m0, s15
	v_lshl_add_u64 v[194:195], v[192:193], 0, s[50:51]
	global_load_lds_dwordx4 v[194:195], off
	v_lshl_add_u64 v[194:195], v[192:193], 0, s[52:53]
	s_mov_b32 m0, s20
	v_lshl_add_u64 v[192:193], v[192:193], 0, s[54:55]
	global_load_lds_dwordx4 v[194:195], off
	s_mov_b32 m0, s21
	s_nop 0
	global_load_lds_dwordx4 v[192:193], off

.LBB0_1211:
	s_or_b32 s0, s11, 1
	s_cmp_ge_u32 s0, s16
	s_cbranch_scc1 .LBB0_1213
	s_add_u32 s0, s8, s74
	s_addc_u32 s1, s9, s75
	v_lshl_add_u64 v[192:193], s[0:1], 0, v[250:251]
	v_lshl_add_u64 v[194:195], v[192:193], 0, s[56:57]
	s_add_i32 m0, s83, 0x14000
	v_lshl_add_u64 v[192:193], v[192:193], 0, s[58:59]
	global_load_lds_dwordx4 v[194:195], off
	s_add_i32 m0, s83, 0x16000
	s_nop 0
	global_load_lds_dwordx4 v[192:193], off
	s_add_u32 s0, s86, s74
	s_addc_u32 s1, s90, s75
	v_lshl_add_u64 v[192:193], s[0:1], 0, v[252:253]
	s_add_i32 m0, s83, 0x8000
	v_lshl_add_u64 v[194:195], v[192:193], 0, s[36:37]
	global_load_lds_dwordx4 v[194:195], off
	s_add_i32 m0, s83, 0xa000
	v_lshl_add_u64 v[194:195], v[192:193], 0, s[38:39]
	global_load_lds_dwordx4 v[194:195], off
	v_lshl_add_u64 v[194:195], v[192:193], 0, s[40:41]
	s_add_i32 m0, s83, 0xc000
	v_lshl_add_u64 v[192:193], v[192:193], 0, s[42:43]
	global_load_lds_dwordx4 v[194:195], off
	s_add_i32 m0, s83, 0xe000
	s_nop 0
	global_load_lds_dwordx4 v[192:193], off

.LBB0_1220:
	ds_read_b128 v[202:205], v227 offset:0x7000
	ds_read_b128 v[206:209], v227 offset:0x7800
	s_waitcnt lgkmcnt(4)
	ds_read_b128 v[220:223], v227 offset:0x7400
	v_mfma_f32_16x16x32_bf16 v[210:213], v[192:195], v[0:3], v[176:179]
	ds_read_b128 v[230:233], v227 offset:0x7c00
	s_waitcnt lgkmcnt(4)
	v_mfma_f32_16x16x32_bf16 v[192:195], v[192:195], v[16:19], v[180:183]
	v_mfma_f32_16x16x32_bf16 v[176:179], v[188:191], v[0:3], v[176:179]
	v_mfma_f32_16x16x32_bf16 v[180:183], v[188:191], v[16:19], v[180:183]
	v_mfma_f32_16x16x32_bf16 v[188:191], v[196:199], v[4:7], v[210:213]
	s_waitcnt lgkmcnt(2)
	v_mfma_f32_16x16x32_bf16 v[176:179], v[184:187], v[4:7], v[176:179]
	v_mfma_f32_16x16x32_bf16 v[180:183], v[184:187], v[20:23], v[180:183]
	v_mfma_f32_16x16x32_bf16 v[192:195], v[196:199], v[20:23], v[192:195]
	v_mfma_f32_16x16x32_bf16 v[184:187], v[202:205], v[8:11], v[188:191]
	s_waitcnt lgkmcnt(0)
	v_mfma_f32_16x16x32_bf16 v[176:179], v[206:209], v[8:11], v[176:179]
	v_mfma_f32_16x16x32_bf16 v[192:195], v[202:205], v[24:27], v[192:195]
	v_mfma_f32_16x16x32_bf16 v[196:199], v[206:209], v[24:27], v[180:183]
	v_mfma_f32_16x16x32_bf16 v[188:191], v[220:223], v[12:15], v[184:187]
	v_mfma_f32_16x16x32_bf16 v[180:183], v[220:223], v[28:31], v[192:195]
	v_mfma_f32_16x16x32_bf16 v[184:187], v[230:233], v[12:15], v[176:179]
	v_mfma_f32_16x16x32_bf16 v[176:179], v[230:233], v[28:31], v[196:199]
	s_add_i32 s11, s11, 2
	s_cmp_ge_u32 s11, s16
	s_cselect_b64 s[4:5], -1, 0
	s_and_b64 vcc, exec, s[4:5]
	s_cbranch_vccnz .LBB0_1222
	s_add_u32 s0, s8, s74
	s_addc_u32 s1, s9, s75
	v_lshl_add_u64 v[192:193], s[0:1], 0, v[250:251]
	v_lshl_add_u64 v[194:195], v[192:193], 0, s[60:61]
	s_add_i32 m0, s83, 0x10000
	v_lshl_add_u64 v[192:193], v[192:193], 0, s[62:63]
	global_load_lds_dwordx4 v[194:195], off
	s_add_i32 m0, s83, 0x12000
	s_nop 0
	global_load_lds_dwordx4 v[192:193], off
	s_add_u32 s0, s86, s74
	s_addc_u32 s1, s90, s75
	v_lshl_add_u64 v[192:193], s[0:1], 0, v[252:253]
	s_mov_b32 m0, s83
	v_lshl_add_u64 v[194:195], v[192:193], 0, s[48:49]
	global_load_lds_dwordx4 v[194:195], off
	s_mov_b32 m0, s15
	v_lshl_add_u64 v[194:195], v[192:193], 0, s[50:51]
	global_load_lds_dwordx4 v[194:195], off
	v_lshl_add_u64 v[194:195], v[192:193], 0, s[52:53]
	s_mov_b32 m0, s20
	v_lshl_add_u64 v[192:193], v[192:193], 0, s[54:55]
	global_load_lds_dwordx4 v[194:195], off
	s_mov_b32 m0, s21
	s_nop 0
	global_load_lds_dwordx4 v[192:193], off

.LBB0_1247:
	s_or_b32 s0, s10, 1
	s_cmp_ge_u32 s0, s28
	s_cbranch_scc1 .LBB0_1249
	s_add_u32 s0, s8, s64
	s_addc_u32 s1, s9, s65
	v_lshl_add_u64 v[192:193], s[0:1], 0, v[250:251]
	v_lshl_add_u64 v[194:195], v[192:193], 0, s[56:57]
	s_add_i32 m0, s83, 0x14000
	v_lshl_add_u64 v[192:193], v[192:193], 0, s[58:59]
	global_load_lds_dwordx4 v[194:195], off
	s_add_i32 m0, s83, 0x16000
	s_nop 0
	global_load_lds_dwordx4 v[192:193], off
	s_add_u32 s0, s86, s64
	s_addc_u32 s1, s90, s65
	v_lshl_add_u64 v[192:193], s[0:1], 0, v[252:253]
	s_add_i32 m0, s83, 0x8000
	v_lshl_add_u64 v[194:195], v[192:193], 0, s[36:37]
	global_load_lds_dwordx4 v[194:195], off
	s_add_i32 m0, s83, 0xa000
	v_lshl_add_u64 v[194:195], v[192:193], 0, s[38:39]
	global_load_lds_dwordx4 v[194:195], off
	v_lshl_add_u64 v[194:195], v[192:193], 0, s[40:41]
	s_add_i32 m0, s83, 0xc000
	v_lshl_add_u64 v[192:193], v[192:193], 0, s[42:43]
	global_load_lds_dwordx4 v[194:195], off
	s_add_i32 m0, s83, 0xe000
	s_nop 0
	global_load_lds_dwordx4 v[192:193], off

.LBB0_1256:
	ds_read_b128 v[202:205], v227 offset:0x7000
	ds_read_b128 v[206:209], v227 offset:0x7800
	s_waitcnt lgkmcnt(4)
	ds_read_b128 v[220:223], v227 offset:0x7400
	v_mfma_f32_16x16x32_bf16 v[210:213], v[192:195], v[0:3], v[176:179]
	ds_read_b128 v[230:233], v227 offset:0x7c00
	s_waitcnt lgkmcnt(4)
	v_mfma_f32_16x16x32_bf16 v[192:195], v[192:195], v[16:19], v[180:183]
	v_mfma_f32_16x16x32_bf16 v[176:179], v[188:191], v[0:3], v[176:179]
	v_mfma_f32_16x16x32_bf16 v[180:183], v[188:191], v[16:19], v[180:183]
	v_mfma_f32_16x16x32_bf16 v[188:191], v[196:199], v[4:7], v[210:213]
	s_waitcnt lgkmcnt(2)
	v_mfma_f32_16x16x32_bf16 v[176:179], v[184:187], v[4:7], v[176:179]
	v_mfma_f32_16x16x32_bf16 v[180:183], v[184:187], v[20:23], v[180:183]
	v_mfma_f32_16x16x32_bf16 v[192:195], v[196:199], v[20:23], v[192:195]
	v_mfma_f32_16x16x32_bf16 v[184:187], v[202:205], v[8:11], v[188:191]
	s_waitcnt lgkmcnt(0)
	v_mfma_f32_16x16x32_bf16 v[176:179], v[206:209], v[8:11], v[176:179]
	v_mfma_f32_16x16x32_bf16 v[192:195], v[202:205], v[24:27], v[192:195]
	v_mfma_f32_16x16x32_bf16 v[196:199], v[206:209], v[24:27], v[180:183]
	v_mfma_f32_16x16x32_bf16 v[188:191], v[220:223], v[12:15], v[184:187]
	v_mfma_f32_16x16x32_bf16 v[180:183], v[220:223], v[28:31], v[192:195]
	v_mfma_f32_16x16x32_bf16 v[184:187], v[230:233], v[12:15], v[176:179]
	v_mfma_f32_16x16x32_bf16 v[176:179], v[230:233], v[28:31], v[196:199]
	s_add_i32 s10, s10, 2
	s_cmp_ge_u32 s10, s28
	s_cselect_b64 s[4:5], -1, 0
	s_and_b64 vcc, exec, s[4:5]
	s_cbranch_vccnz .LBB0_1258
	s_add_u32 s0, s8, s64
	s_addc_u32 s1, s9, s65
	v_lshl_add_u64 v[192:193], s[0:1], 0, v[250:251]
	v_lshl_add_u64 v[194:195], v[192:193], 0, s[60:61]
	s_add_i32 m0, s83, 0x10000
	v_lshl_add_u64 v[192:193], v[192:193], 0, s[62:63]
	global_load_lds_dwordx4 v[194:195], off
	s_add_i32 m0, s83, 0x12000
	s_nop 0
	global_load_lds_dwordx4 v[192:193], off
	s_add_u32 s0, s86, s64
	s_addc_u32 s1, s90, s65
	v_lshl_add_u64 v[192:193], s[0:1], 0, v[252:253]
	s_mov_b32 m0, s83
	v_lshl_add_u64 v[194:195], v[192:193], 0, s[48:49]
	global_load_lds_dwordx4 v[194:195], off
	s_mov_b32 m0, s15
	v_lshl_add_u64 v[194:195], v[192:193], 0, s[50:51]
	global_load_lds_dwordx4 v[194:195], off
	v_lshl_add_u64 v[194:195], v[192:193], 0, s[52:53]
	s_mov_b32 m0, s20
	v_lshl_add_u64 v[192:193], v[192:193], 0, s[54:55]
	global_load_lds_dwordx4 v[194:195], off
	s_mov_b32 m0, s21
	s_nop 0
	global_load_lds_dwordx4 v[192:193], off

.LBB0_1729:
	ds_read_b128 v[2:5], v153
	ds_read_b128 v[6:9], v153 offset:1024
	ds_read_b128 v[10:13], v153 offset:2048
	ds_read_b128 v[14:17], v153 offset:3072
	ds_read_b128 v[18:21], v154
	ds_read_b128 v[22:25], v154 offset:1024
	ds_read_b128 v[26:29], v154 offset:2048
	ds_read_b128 v[30:33], v154 offset:3072
	s_add_u32 s0, s44, 0x10000
	s_addc_u32 s1, s45, 0
	ds_read_b128 v[34:37], v155
	ds_read_b128 v[38:41], v155 offset:1024
	ds_read_b128 v[42:45], v155 offset:2048
	ds_read_b128 v[46:49], v155 offset:3072
	ds_read_b128 v[50:53], v155 offset:4096
	ds_read_b128 v[54:57], v155 offset:5120
	ds_read_b128 v[58:61], v155 offset:6144
	ds_read_b128 v[62:65], v155 offset:7168
	s_waitcnt vmcnt(24) lgkmcnt(0)
	s_barrier
	v_mfma_f32_16x16x32_bf16 v[66:69], v[2:5], v[34:37], 0
	v_mfma_f32_16x16x32_bf16 v[70:73], v[10:13], v[34:37], 0
	v_mfma_f32_16x16x32_bf16 v[74:77], v[2:5], v[42:45], 0
	v_mfma_f32_16x16x32_bf16 v[78:81], v[10:13], v[42:45], 0
	v_mfma_f32_16x16x32_bf16 v[82:85], v[2:5], v[50:53], 0
	v_mfma_f32_16x16x32_bf16 v[86:89], v[10:13], v[50:53], 0
	v_mfma_f32_16x16x32_bf16 v[90:93], v[2:5], v[58:61], 0
	v_mfma_f32_16x16x32_bf16 v[94:97], v[10:13], v[58:61], 0
	v_mfma_f32_16x16x32_bf16 v[66:69], v[6:9], v[38:41], v[66:69]
	v_mfma_f32_16x16x32_bf16 v[70:73], v[14:17], v[38:41], v[70:73]
	v_mfma_f32_16x16x32_bf16 v[74:77], v[6:9], v[46:49], v[74:77]
	v_mfma_f32_16x16x32_bf16 v[78:81], v[14:17], v[46:49], v[78:81]
	v_mfma_f32_16x16x32_bf16 v[82:85], v[6:9], v[54:57], v[82:85]
	v_mfma_f32_16x16x32_bf16 v[86:89], v[14:17], v[54:57], v[86:89]
	v_mfma_f32_16x16x32_bf16 v[90:93], v[6:9], v[62:65], v[90:93]
	v_mfma_f32_16x16x32_bf16 v[104:107], v[14:17], v[62:65], v[94:97]
	v_mfma_f32_16x16x32_bf16 v[94:97], v[18:21], v[34:37], 0
	v_mfma_f32_16x16x32_bf16 v[34:37], v[26:29], v[34:37], 0
	v_mfma_f32_16x16x32_bf16 v[108:111], v[22:25], v[38:41], v[94:97]
	v_mfma_f32_16x16x32_bf16 v[34:37], v[30:33], v[38:41], v[34:37]
	v_mfma_f32_16x16x32_bf16 v[38:41], v[18:21], v[42:45], 0
	v_mfma_f32_16x16x32_bf16 v[42:45], v[26:29], v[42:45], 0
	v_mfma_f32_16x16x32_bf16 v[38:41], v[22:25], v[46:49], v[38:41]
	v_mfma_f32_16x16x32_bf16 v[42:45], v[30:33], v[46:49], v[42:45]
	v_mfma_f32_16x16x32_bf16 v[46:49], v[18:21], v[50:53], 0
	v_mfma_f32_16x16x32_bf16 v[50:53], v[26:29], v[50:53], 0
	v_mfma_f32_16x16x32_bf16 v[46:49], v[22:25], v[54:57], v[46:49]
	v_mfma_f32_16x16x32_bf16 v[50:53], v[30:33], v[54:57], v[50:53]
	v_mfma_f32_16x16x32_bf16 v[54:57], v[18:21], v[58:61], 0
	v_mfma_f32_16x16x32_bf16 v[58:61], v[26:29], v[58:61], 0
	v_mfma_f32_16x16x32_bf16 v[54:57], v[22:25], v[62:65], v[54:57]
	v_mfma_f32_16x16x32_bf16 v[58:61], v[30:33], v[62:65], v[58:61]
	s_barrier
	s_add_i32 s12, s52, s17
	v_lshl_add_u64 v[102:103], s[0:1], 0, v[134:135]
	s_mov_b32 m0, s12
	ds_read_b128 v[62:65], v155 offset:16384
	ds_read_b128 v[94:97], v155 offset:17408
	ds_read_b128 v[98:101], v155 offset:18432
	ds_read_b128 v[112:115], v155 offset:19456
	ds_read_b128 v[116:119], v155 offset:20480
	ds_read_b128 v[120:123], v155 offset:21504
	ds_read_b128 v[124:127], v155 offset:22528
	ds_read_b128 v[128:131], v155 offset:23552
	global_load_lds_dwordx4 v[102:103], off
	s_add_i32 m0, s12, 0x2000
	v_lshl_add_u64 v[102:103], s[0:1], 0, v[138:139]
	s_add_u32 s0, s44, 0x14000
	s_addc_u32 s1, s45, 0
	s_add_i32 s12, s53, s17
	global_load_lds_dwordx4 v[102:103], off
	v_lshl_add_u64 v[102:103], s[0:1], 0, v[134:135]
	s_mov_b32 m0, s12
	v_lshl_add_u64 v[148:149], s[46:47], 0, v[132:133]
	global_load_lds_dwordx4 v[102:103], off
	v_lshl_add_u64 v[102:103], s[0:1], 0, v[138:139]
	s_add_i32 m0, s12, 0x2000
	v_lshl_add_u64 v[144:145], s[46:47], 0, v[136:137]
	global_load_lds_dwordx4 v[102:103], off
	s_mov_b32 m0, s18
	v_lshl_add_u64 v[102:103], v[148:149], 0, s[38:39]
	global_load_lds_dwordx4 v[102:103], off
	s_mov_b32 m0, s19
	v_lshl_add_u64 v[102:103], v[144:145], 0, s[38:39]
	global_load_lds_dwordx4 v[102:103], off
	s_waitcnt vmcnt(24) lgkmcnt(0)
	s_barrier
	v_mfma_f32_16x16x32_bf16 v[158:161], v[2:5], v[62:65], 0
	v_mfma_f32_16x16x32_bf16 v[166:169], v[2:5], v[98:101], 0
	v_mfma_f32_16x16x32_bf16 v[174:177], v[2:5], v[116:119], 0
	v_mfma_f32_16x16x32_bf16 v[2:5], v[2:5], v[124:127], 0
	v_mfma_f32_16x16x32_bf16 v[158:161], v[6:9], v[94:97], v[158:161]
	v_mfma_f32_16x16x32_bf16 v[166:169], v[6:9], v[112:115], v[166:169]
	v_mfma_f32_16x16x32_bf16 v[174:177], v[6:9], v[120:123], v[174:177]
	v_mfma_f32_16x16x32_bf16 v[2:5], v[6:9], v[128:131], v[2:5]
	v_mfma_f32_16x16x32_bf16 v[6:9], v[10:13], v[124:127], 0
	v_mfma_f32_16x16x32_bf16 v[162:165], v[10:13], v[62:65], 0
	v_mfma_f32_16x16x32_bf16 v[170:173], v[10:13], v[98:101], 0
	v_mfma_f32_16x16x32_bf16 v[178:181], v[10:13], v[116:119], 0
	v_mfma_f32_16x16x32_bf16 v[6:9], v[14:17], v[128:131], v[6:9]
	v_mfma_f32_16x16x32_bf16 v[162:165], v[14:17], v[94:97], v[162:165]
	v_mfma_f32_16x16x32_bf16 v[170:173], v[14:17], v[112:115], v[170:173]
	v_mfma_f32_16x16x32_bf16 v[178:181], v[14:17], v[120:123], v[178:181]
	v_mfma_f32_16x16x32_bf16 v[14:17], v[26:29], v[62:65], 0
	v_mfma_f32_16x16x32_bf16 v[182:185], v[30:33], v[94:97], v[14:17]
	v_mfma_f32_16x16x32_bf16 v[14:17], v[18:21], v[98:101], 0
	v_mfma_f32_16x16x32_bf16 v[186:189], v[22:25], v[112:115], v[14:17]
	v_mfma_f32_16x16x32_bf16 v[14:17], v[26:29], v[98:101], 0
	v_mfma_f32_16x16x32_bf16 v[190:193], v[30:33], v[112:115], v[14:17]
	v_mfma_f32_16x16x32_bf16 v[14:17], v[18:21], v[116:119], 0
	v_mfma_f32_16x16x32_bf16 v[194:197], v[22:25], v[120:123], v[14:17]
	v_mfma_f32_16x16x32_bf16 v[14:17], v[26:29], v[116:119], 0
	v_mfma_f32_16x16x32_bf16 v[10:13], v[18:21], v[62:65], 0
	v_mfma_f32_16x16x32_bf16 v[198:201], v[30:33], v[120:123], v[14:17]
	v_mfma_f32_16x16x32_bf16 v[14:17], v[18:21], v[124:127], 0
	v_mfma_f32_16x16x32_bf16 v[10:13], v[22:25], v[94:97], v[10:13]
	v_mfma_f32_16x16x32_bf16 v[202:205], v[22:25], v[128:131], v[14:17]
	v_mfma_f32_16x16x32_bf16 v[14:17], v[26:29], v[124:127], 0
	v_mfma_f32_16x16x32_bf16 v[206:209], v[30:33], v[128:131], v[14:17]
	s_barrier
	s_add_i32 s12, 0, 0x18000
	v_add_u32_e32 v1, s12, v151
	s_add_i32 s13, 0, 0x1c000
	s_nop 1
	ds_read_b128 v[14:17], v1
	ds_read_b128 v[24:27], v1 offset:1024
	ds_read_b128 v[28:31], v1 offset:2048
	ds_read_b128 v[210:213], v1 offset:3072
	v_add_u32_e32 v1, s13, v151
	ds_read_b128 v[214:217], v1
	ds_read_b128 v[218:221], v1 offset:1024
	ds_read_b128 v[222:225], v1 offset:2048
	ds_read_b128 v[226:229], v1 offset:3072
	s_add_u32 s0, s46, 0x2b0100
	s_addc_u32 s1, s47, 0
	s_mov_b32 m0, s20
	v_lshl_add_u64 v[22:23], s[0:1], 0, v[132:133]
	ds_read_b128 v[18:21], v155 offset:32768
	ds_read_b128 v[120:123], v155 offset:33792
	ds_read_b128 v[230:233], v155 offset:34816
	ds_read_b128 v[234:237], v155 offset:35840
	ds_read_b128 v[238:241], v155 offset:36864
	ds_read_b128 v[242:245], v155 offset:37888
	ds_read_b128 v[246:249], v155 offset:38912
	ds_read_b128 v[250:253], v155 offset:39936
	global_load_lds_dwordx4 v[22:23], off
	s_mov_b32 m0, s21
	v_lshl_add_u64 v[22:23], s[0:1], 0, v[136:137]
	global_load_lds_dwordx4 v[22:23], off
	s_waitcnt vmcnt(24) lgkmcnt(0)
	s_barrier
	v_mfma_f32_16x16x32_bf16 v[62:65], v[14:17], v[18:21], v[66:69]
	v_mfma_f32_16x16x32_bf16 v[128:131], v[24:27], v[120:123], v[62:65]
	v_mfma_f32_16x16x32_bf16 v[62:65], v[28:31], v[18:21], v[70:73]
	v_mfma_f32_16x16x32_bf16 v[116:119], v[210:213], v[120:123], v[62:65]
	v_mfma_f32_16x16x32_bf16 v[62:65], v[14:17], v[230:233], v[74:77]
	v_mfma_f32_16x16x32_bf16 v[112:115], v[24:27], v[234:237], v[62:65]
	v_mfma_f32_16x16x32_bf16 v[62:65], v[28:31], v[230:233], v[78:81]
	v_mfma_f32_16x16x32_bf16 v[100:103], v[210:213], v[234:237], v[62:65]
	v_mfma_f32_16x16x32_bf16 v[62:65], v[14:17], v[238:241], v[82:85]
	v_mfma_f32_16x16x32_bf16 v[96:99], v[24:27], v[242:245], v[62:65]
	v_mfma_f32_16x16x32_bf16 v[62:65], v[28:31], v[238:241], v[86:89]
	v_mfma_f32_16x16x32_bf16 v[84:87], v[210:213], v[242:245], v[62:65]
	v_mfma_f32_16x16x32_bf16 v[62:65], v[14:17], v[246:249], v[90:93]
	v_mfma_f32_16x16x32_bf16 v[80:83], v[24:27], v[250:253], v[62:65]
	v_mfma_f32_16x16x32_bf16 v[62:65], v[28:31], v[246:249], v[104:107]
	v_mfma_f32_16x16x32_bf16 v[64:67], v[210:213], v[250:253], v[62:65]
	v_mfma_f32_16x16x32_bf16 v[68:71], v[214:217], v[18:21], v[108:111]
	v_mfma_f32_16x16x32_bf16 v[18:21], v[222:225], v[18:21], v[34:37]
	v_mfma_f32_16x16x32_bf16 v[124:127], v[218:221], v[120:123], v[68:71]
	v_mfma_f32_16x16x32_bf16 v[120:123], v[226:229], v[120:123], v[18:21]
	v_mfma_f32_16x16x32_bf16 v[18:21], v[214:217], v[230:233], v[38:41]
	v_mfma_f32_16x16x32_bf16 v[108:111], v[218:221], v[234:237], v[18:21]
	v_mfma_f32_16x16x32_bf16 v[18:21], v[222:225], v[230:233], v[42:45]
	v_mfma_f32_16x16x32_bf16 v[104:107], v[226:229], v[234:237], v[18:21]
	v_mfma_f32_16x16x32_bf16 v[18:21], v[214:217], v[238:241], v[46:49]
	v_mfma_f32_16x16x32_bf16 v[92:95], v[218:221], v[242:245], v[18:21]
	v_mfma_f32_16x16x32_bf16 v[18:21], v[222:225], v[238:241], v[50:53]
	v_mfma_f32_16x16x32_bf16 v[88:91], v[226:229], v[242:245], v[18:21]
	v_mfma_f32_16x16x32_bf16 v[18:21], v[214:217], v[246:249], v[54:57]
	v_mfma_f32_16x16x32_bf16 v[72:75], v[218:221], v[250:253], v[18:21]
	v_mfma_f32_16x16x32_bf16 v[18:21], v[222:225], v[246:249], v[58:61]
	v_mfma_f32_16x16x32_bf16 v[68:71], v[226:229], v[250:253], v[18:21]
	s_barrier
	s_add_u32 s0, s44, 0x18000
	s_addc_u32 s1, s45, 0
	s_add_i32 s12, s12, s17
	s_nop 1
	v_lshl_add_u64 v[18:19], s[0:1], 0, v[134:135]
	s_mov_b32 m0, s12
	ds_read_b128 v[40:43], v155 offset:49152
	ds_read_b128 v[44:47], v155 offset:50176
	ds_read_b128 v[230:233], v155 offset:51200
	ds_read_b128 v[234:237], v155 offset:52224
	ds_read_b128 v[238:241], v155 offset:53248
	ds_read_b128 v[242:245], v155 offset:54272
	ds_read_b128 v[246:249], v155 offset:55296
	ds_read_b128 v[250:253], v155 offset:56320
	global_load_lds_dwordx4 v[18:19], off
	s_add_i32 m0, s12, 0x2000
	v_lshl_add_u64 v[18:19], s[0:1], 0, v[138:139]
	s_add_u32 s0, s44, 0x1c000
	s_addc_u32 s1, s45, 0
	s_add_i32 s12, s13, s17
	global_load_lds_dwordx4 v[18:19], off
	s_mov_b32 m0, s12
	v_lshl_add_u64 v[18:19], s[0:1], 0, v[134:135]
	global_load_lds_dwordx4 v[18:19], off
	s_add_i32 m0, s12, 0x2000
	v_lshl_add_u64 v[18:19], s[0:1], 0, v[138:139]
	global_load_lds_dwordx4 v[18:19], off
	s_mov_b32 m0, s48
	v_lshl_add_u64 v[18:19], v[148:149], 0, s[40:41]
	global_load_lds_dwordx4 v[18:19], off
	s_mov_b32 m0, s49
	v_lshl_add_u64 v[18:19], v[144:145], 0, s[40:41]
	global_load_lds_dwordx4 v[18:19], off
	s_waitcnt vmcnt(8) lgkmcnt(0)
	s_barrier
	v_mfma_f32_16x16x32_bf16 v[18:21], v[14:17], v[40:43], v[158:161]
	v_mfma_f32_16x16x32_bf16 v[76:79], v[24:27], v[44:47], v[18:21]
	v_mfma_f32_16x16x32_bf16 v[18:21], v[28:31], v[40:43], v[162:165]
	v_mfma_f32_16x16x32_bf16 v[52:55], v[210:213], v[44:47], v[18:21]
	v_mfma_f32_16x16x32_bf16 v[18:21], v[14:17], v[230:233], v[166:169]
	v_mfma_f32_16x16x32_bf16 v[48:51], v[24:27], v[234:237], v[18:21]
	v_mfma_f32_16x16x32_bf16 v[18:21], v[28:31], v[230:233], v[170:173]
	v_mfma_f32_16x16x32_bf16 v[36:39], v[210:213], v[234:237], v[18:21]
	v_mfma_f32_16x16x32_bf16 v[18:21], v[14:17], v[238:241], v[174:177]
	v_mfma_f32_16x16x32_bf16 v[32:35], v[24:27], v[242:245], v[18:21]
	v_mfma_f32_16x16x32_bf16 v[18:21], v[28:31], v[238:241], v[178:181]
	v_mfma_f32_16x16x32_bf16 v[2:5], v[14:17], v[246:249], v[2:5]
	v_mfma_f32_16x16x32_bf16 v[20:23], v[210:213], v[242:245], v[18:21]
	v_mfma_f32_16x16x32_bf16 v[16:19], v[24:27], v[250:253], v[2:5]
	v_mfma_f32_16x16x32_bf16 v[2:5], v[28:31], v[246:249], v[6:9]
	v_mfma_f32_16x16x32_bf16 v[4:7], v[210:213], v[250:253], v[2:5]
	v_mfma_f32_16x16x32_bf16 v[8:11], v[214:217], v[40:43], v[10:13]
	v_mfma_f32_16x16x32_bf16 v[60:63], v[218:221], v[44:47], v[8:11]
	v_mfma_f32_16x16x32_bf16 v[8:11], v[222:225], v[40:43], v[182:185]
	v_mfma_f32_16x16x32_bf16 v[56:59], v[226:229], v[44:47], v[8:11]
	v_mfma_f32_16x16x32_bf16 v[8:11], v[214:217], v[230:233], v[186:189]
	v_mfma_f32_16x16x32_bf16 v[44:47], v[218:221], v[234:237], v[8:11]
	v_mfma_f32_16x16x32_bf16 v[8:11], v[222:225], v[230:233], v[190:193]
	v_mfma_f32_16x16x32_bf16 v[40:43], v[226:229], v[234:237], v[8:11]
	v_mfma_f32_16x16x32_bf16 v[8:11], v[214:217], v[238:241], v[194:197]
	v_mfma_f32_16x16x32_bf16 v[28:31], v[218:221], v[242:245], v[8:11]
	v_mfma_f32_16x16x32_bf16 v[8:11], v[222:225], v[238:241], v[198:201]
	v_mfma_f32_16x16x32_bf16 v[24:27], v[226:229], v[242:245], v[8:11]
	v_mfma_f32_16x16x32_bf16 v[8:11], v[214:217], v[246:249], v[202:205]
	v_mfma_f32_16x16x32_bf16 v[12:15], v[218:221], v[250:253], v[8:11]
	v_mfma_f32_16x16x32_bf16 v[8:11], v[222:225], v[246:249], v[206:209]
	v_mfma_f32_16x16x32_bf16 v[8:11], v[226:229], v[250:253], v[8:11]
	s_barrier
	s_mov_b32 s22, 2
	s_branch .LBB0_1733

.LBB0_1734:
	ds_read_b128 v[158:161], v153
	ds_read_b128 v[162:165], v153 offset:1024
	ds_read_b128 v[166:169], v153 offset:2048
	ds_read_b128 v[170:173], v153 offset:3072
	ds_read_b128 v[174:177], v154
	ds_read_b128 v[178:181], v154 offset:1024
	ds_read_b128 v[182:185], v154 offset:2048
	ds_read_b128 v[186:189], v154 offset:3072
	s_add_u32 s12, s60, s24
	s_addc_u32 s13, s61, 0
	s_cmp_eq_u32 s24, s44
	s_cselect_b32 s23, s9, s13
	s_cselect_b32 s22, s8, s12
	s_cselect_b32 s47, s43, s59
	s_cselect_b32 s46, s42, s1
	s_add_i32 s63, s18, 0xc000
	v_lshl_add_u64 v[144:145], v[2:3], 0, s[24:25]
	s_mov_b32 m0, s63
	s_add_i32 s62, s18, 0xe000
	ds_read_b128 v[190:193], v155
	ds_read_b128 v[194:197], v155 offset:1024
	ds_read_b128 v[198:201], v155 offset:2048
	ds_read_b128 v[202:205], v155 offset:3072
	ds_read_b128 v[206:209], v155 offset:4096
	ds_read_b128 v[210:213], v155 offset:5120
	ds_read_b128 v[214:217], v155 offset:6144
	ds_read_b128 v[218:221], v155 offset:7168
	global_load_lds_dwordx4 v[144:145], off
	s_mov_b32 m0, s62
	v_lshl_add_u64 v[144:145], v[148:149], 0, s[24:25]
	global_load_lds_dwordx4 v[144:145], off
	s_waitcnt vmcnt(8) lgkmcnt(0)
	s_barrier
	v_mfma_f32_16x16x32_bf16 v[128:131], v[158:161], v[190:193], v[128:131]
	v_mfma_f32_16x16x32_bf16 v[128:131], v[162:165], v[194:197], v[128:131]
	v_mfma_f32_16x16x32_bf16 v[116:119], v[166:169], v[190:193], v[116:119]
	v_mfma_f32_16x16x32_bf16 v[116:119], v[170:173], v[194:197], v[116:119]
	v_mfma_f32_16x16x32_bf16 v[100:103], v[166:169], v[198:201], v[100:103]
	v_mfma_f32_16x16x32_bf16 v[100:103], v[170:173], v[202:205], v[100:103]
	v_mfma_f32_16x16x32_bf16 v[112:115], v[158:161], v[198:201], v[112:115]
	v_mfma_f32_16x16x32_bf16 v[112:115], v[162:165], v[202:205], v[112:115]
	v_mfma_f32_16x16x32_bf16 v[96:99], v[158:161], v[206:209], v[96:99]
	v_mfma_f32_16x16x32_bf16 v[96:99], v[162:165], v[210:213], v[96:99]
	v_mfma_f32_16x16x32_bf16 v[84:87], v[166:169], v[206:209], v[84:87]
	v_mfma_f32_16x16x32_bf16 v[84:87], v[170:173], v[210:213], v[84:87]
	v_mfma_f32_16x16x32_bf16 v[64:67], v[166:169], v[214:217], v[64:67]
	v_mfma_f32_16x16x32_bf16 v[64:67], v[170:173], v[218:221], v[64:67]
	v_mfma_f32_16x16x32_bf16 v[80:83], v[158:161], v[214:217], v[80:83]
	v_mfma_f32_16x16x32_bf16 v[80:83], v[162:165], v[218:221], v[80:83]
	v_mfma_f32_16x16x32_bf16 v[72:75], v[174:177], v[214:217], v[72:75]
	v_mfma_f32_16x16x32_bf16 v[72:75], v[178:181], v[218:221], v[72:75]
	v_mfma_f32_16x16x32_bf16 v[68:71], v[182:185], v[214:217], v[68:71]
	v_mfma_f32_16x16x32_bf16 v[68:71], v[186:189], v[218:221], v[68:71]
	v_mfma_f32_16x16x32_bf16 v[88:91], v[182:185], v[206:209], v[88:91]
	v_mfma_f32_16x16x32_bf16 v[88:91], v[186:189], v[210:213], v[88:91]
	v_mfma_f32_16x16x32_bf16 v[92:95], v[174:177], v[206:209], v[92:95]
	v_mfma_f32_16x16x32_bf16 v[92:95], v[178:181], v[210:213], v[92:95]
	v_mfma_f32_16x16x32_bf16 v[108:111], v[174:177], v[198:201], v[108:111]
	v_mfma_f32_16x16x32_bf16 v[108:111], v[178:181], v[202:205], v[108:111]
	v_mfma_f32_16x16x32_bf16 v[104:107], v[182:185], v[198:201], v[104:107]
	v_mfma_f32_16x16x32_bf16 v[104:107], v[186:189], v[202:205], v[104:107]
	v_mfma_f32_16x16x32_bf16 v[120:123], v[182:185], v[190:193], v[120:123]
	v_mfma_f32_16x16x32_bf16 v[120:123], v[186:189], v[194:197], v[120:123]
	v_mfma_f32_16x16x32_bf16 v[124:127], v[174:177], v[190:193], v[124:127]
	v_mfma_f32_16x16x32_bf16 v[124:127], v[178:181], v[194:197], v[124:127]
	s_barrier
	s_add_i32 s12, s52, s17
	v_lshl_add_u64 v[144:145], s[46:47], 0, v[134:135]
	s_mov_b32 m0, s12
	ds_read_b128 v[190:193], v155 offset:16384
	ds_read_b128 v[194:197], v155 offset:17408
	ds_read_b128 v[198:201], v155 offset:18432
	ds_read_b128 v[202:205], v155 offset:19456
	ds_read_b128 v[206:209], v155 offset:20480
	ds_read_b128 v[210:213], v155 offset:21504
	ds_read_b128 v[214:217], v155 offset:22528
	ds_read_b128 v[218:221], v155 offset:23552
	global_load_lds_dwordx4 v[144:145], off
	s_add_i32 m0, s12, 0x2000
	s_add_u32 s12, s46, 0x4000
	v_lshl_add_u64 v[144:145], s[46:47], 0, v[138:139]
	s_addc_u32 s13, s47, 0
	s_add_i32 s14, s53, s17
	global_load_lds_dwordx4 v[144:145], off
	v_lshl_add_u64 v[144:145], s[12:13], 0, v[134:135]
	s_mov_b32 m0, s14
	v_lshl_add_u64 v[222:223], s[22:23], 0, v[136:137]
	global_load_lds_dwordx4 v[144:145], off
	s_add_i32 m0, s14, 0x2000
	v_lshl_add_u64 v[144:145], s[12:13], 0, v[138:139]
	global_load_lds_dwordx4 v[144:145], off
	s_mov_b32 m0, s18
	v_lshl_add_u64 v[144:145], s[22:23], 0, v[132:133]
	global_load_lds_dwordx4 v[144:145], off
	s_mov_b32 m0, s19
	s_nop 0
	global_load_lds_dwordx4 v[222:223], off
	s_waitcnt vmcnt(8) lgkmcnt(0)
	s_barrier
	v_mfma_f32_16x16x32_bf16 v[76:79], v[158:161], v[190:193], v[76:79]
	v_mfma_f32_16x16x32_bf16 v[76:79], v[162:165], v[194:197], v[76:79]
	v_mfma_f32_16x16x32_bf16 v[52:55], v[166:169], v[190:193], v[52:55]
	v_mfma_f32_16x16x32_bf16 v[52:55], v[170:173], v[194:197], v[52:55]
	v_mfma_f32_16x16x32_bf16 v[36:39], v[166:169], v[198:201], v[36:39]
	v_mfma_f32_16x16x32_bf16 v[36:39], v[170:173], v[202:205], v[36:39]
	v_mfma_f32_16x16x32_bf16 v[48:51], v[158:161], v[198:201], v[48:51]
	v_mfma_f32_16x16x32_bf16 v[48:51], v[162:165], v[202:205], v[48:51]
	v_mfma_f32_16x16x32_bf16 v[32:35], v[158:161], v[206:209], v[32:35]
	v_mfma_f32_16x16x32_bf16 v[32:35], v[162:165], v[210:213], v[32:35]
	v_mfma_f32_16x16x32_bf16 v[20:23], v[166:169], v[206:209], v[20:23]
	v_mfma_f32_16x16x32_bf16 v[20:23], v[170:173], v[210:213], v[20:23]
	v_mfma_f32_16x16x32_bf16 v[4:7], v[166:169], v[214:217], v[4:7]
	v_mfma_f32_16x16x32_bf16 v[4:7], v[170:173], v[218:221], v[4:7]
	v_mfma_f32_16x16x32_bf16 v[16:19], v[158:161], v[214:217], v[16:19]
	v_mfma_f32_16x16x32_bf16 v[16:19], v[162:165], v[218:221], v[16:19]
	v_mfma_f32_16x16x32_bf16 v[12:15], v[174:177], v[214:217], v[12:15]
	v_mfma_f32_16x16x32_bf16 v[12:15], v[178:181], v[218:221], v[12:15]
	v_mfma_f32_16x16x32_bf16 v[8:11], v[182:185], v[214:217], v[8:11]
	v_mfma_f32_16x16x32_bf16 v[8:11], v[186:189], v[218:221], v[8:11]
	v_mfma_f32_16x16x32_bf16 v[24:27], v[182:185], v[206:209], v[24:27]
	v_mfma_f32_16x16x32_bf16 v[24:27], v[186:189], v[210:213], v[24:27]
	v_mfma_f32_16x16x32_bf16 v[28:31], v[174:177], v[206:209], v[28:31]
	v_mfma_f32_16x16x32_bf16 v[28:31], v[178:181], v[210:213], v[28:31]
	v_mfma_f32_16x16x32_bf16 v[44:47], v[174:177], v[198:201], v[44:47]
	v_mfma_f32_16x16x32_bf16 v[44:47], v[178:181], v[202:205], v[44:47]
	v_mfma_f32_16x16x32_bf16 v[40:43], v[182:185], v[198:201], v[40:43]
	v_mfma_f32_16x16x32_bf16 v[40:43], v[186:189], v[202:205], v[40:43]
	v_mfma_f32_16x16x32_bf16 v[56:59], v[182:185], v[190:193], v[56:59]
	v_mfma_f32_16x16x32_bf16 v[56:59], v[186:189], v[194:197], v[56:59]
	v_mfma_f32_16x16x32_bf16 v[60:63], v[174:177], v[190:193], v[60:63]
	v_mfma_f32_16x16x32_bf16 v[60:63], v[178:181], v[194:197], v[60:63]
	s_barrier
	s_add_i32 s14, 0, 0x18000
	v_add_u32_e32 v1, s14, v151
	s_add_i32 s64, 0, 0x1c000
	ds_read_b128 v[158:161], v1
	ds_read_b128 v[162:165], v1 offset:1024
	ds_read_b128 v[166:169], v1 offset:2048
	ds_read_b128 v[170:173], v1 offset:3072
	v_add_u32_e32 v1, s64, v151
	ds_read_b128 v[174:177], v1
	ds_read_b128 v[178:181], v1 offset:1024
	ds_read_b128 v[182:185], v1 offset:2048
	ds_read_b128 v[186:189], v1 offset:3072
	s_add_u32 s12, s22, 0x2b0000
	s_addc_u32 s13, s23, 0
	s_mov_b32 m0, s20
	v_lshl_add_u64 v[224:225], s[12:13], 0, v[132:133]
	ds_read_b128 v[190:193], v155 offset:32768
	ds_read_b128 v[194:197], v155 offset:33792
	ds_read_b128 v[198:201], v155 offset:34816
	ds_read_b128 v[202:205], v155 offset:35840
	ds_read_b128 v[206:209], v155 offset:36864
	ds_read_b128 v[210:213], v155 offset:37888
	ds_read_b128 v[214:217], v155 offset:38912
	ds_read_b128 v[218:221], v155 offset:39936
	global_load_lds_dwordx4 v[224:225], off
	s_mov_b32 m0, s21
	v_lshl_add_u64 v[224:225], s[12:13], 0, v[136:137]
	global_load_lds_dwordx4 v[224:225], off
	s_waitcnt vmcnt(8) lgkmcnt(0)
	s_barrier
	v_mfma_f32_16x16x32_bf16 v[128:131], v[158:161], v[190:193], v[128:131]
	v_mfma_f32_16x16x32_bf16 v[128:131], v[162:165], v[194:197], v[128:131]
	v_mfma_f32_16x16x32_bf16 v[116:119], v[166:169], v[190:193], v[116:119]
	v_mfma_f32_16x16x32_bf16 v[116:119], v[170:173], v[194:197], v[116:119]
	v_mfma_f32_16x16x32_bf16 v[100:103], v[166:169], v[198:201], v[100:103]
	v_mfma_f32_16x16x32_bf16 v[100:103], v[170:173], v[202:205], v[100:103]
	v_mfma_f32_16x16x32_bf16 v[112:115], v[158:161], v[198:201], v[112:115]
	v_mfma_f32_16x16x32_bf16 v[112:115], v[162:165], v[202:205], v[112:115]
	v_mfma_f32_16x16x32_bf16 v[96:99], v[158:161], v[206:209], v[96:99]
	v_mfma_f32_16x16x32_bf16 v[96:99], v[162:165], v[210:213], v[96:99]
	v_mfma_f32_16x16x32_bf16 v[84:87], v[166:169], v[206:209], v[84:87]
	v_mfma_f32_16x16x32_bf16 v[84:87], v[170:173], v[210:213], v[84:87]
	v_mfma_f32_16x16x32_bf16 v[64:67], v[166:169], v[214:217], v[64:67]
	v_mfma_f32_16x16x32_bf16 v[64:67], v[170:173], v[218:221], v[64:67]
	v_mfma_f32_16x16x32_bf16 v[80:83], v[158:161], v[214:217], v[80:83]
	v_mfma_f32_16x16x32_bf16 v[80:83], v[162:165], v[218:221], v[80:83]
	v_mfma_f32_16x16x32_bf16 v[72:75], v[174:177], v[214:217], v[72:75]
	v_mfma_f32_16x16x32_bf16 v[72:75], v[178:181], v[218:221], v[72:75]
	v_mfma_f32_16x16x32_bf16 v[68:71], v[182:185], v[214:217], v[68:71]
	v_mfma_f32_16x16x32_bf16 v[68:71], v[186:189], v[218:221], v[68:71]
	v_mfma_f32_16x16x32_bf16 v[88:91], v[182:185], v[206:209], v[88:91]
	v_mfma_f32_16x16x32_bf16 v[88:91], v[186:189], v[210:213], v[88:91]
	v_mfma_f32_16x16x32_bf16 v[92:95], v[174:177], v[206:209], v[92:95]
	v_mfma_f32_16x16x32_bf16 v[92:95], v[178:181], v[210:213], v[92:95]
	v_mfma_f32_16x16x32_bf16 v[108:111], v[174:177], v[198:201], v[108:111]
	v_mfma_f32_16x16x32_bf16 v[108:111], v[178:181], v[202:205], v[108:111]
	v_mfma_f32_16x16x32_bf16 v[104:107], v[182:185], v[198:201], v[104:107]
	v_mfma_f32_16x16x32_bf16 v[104:107], v[186:189], v[202:205], v[104:107]
	v_mfma_f32_16x16x32_bf16 v[120:123], v[182:185], v[190:193], v[120:123]
	v_mfma_f32_16x16x32_bf16 v[120:123], v[186:189], v[194:197], v[120:123]
	v_mfma_f32_16x16x32_bf16 v[124:127], v[174:177], v[190:193], v[124:127]
	v_mfma_f32_16x16x32_bf16 v[124:127], v[178:181], v[194:197], v[124:127]
	s_barrier
	s_add_u32 s12, s46, 0x8000
	s_addc_u32 s13, s47, 0
	s_add_i32 s14, s14, s17
	v_lshl_add_u64 v[224:225], s[12:13], 0, v[134:135]
	s_mov_b32 m0, s14
	ds_read_b128 v[190:193], v155 offset:49152
	ds_read_b128 v[194:197], v155 offset:50176
	ds_read_b128 v[198:201], v155 offset:51200
	ds_read_b128 v[202:205], v155 offset:52224
	ds_read_b128 v[206:209], v155 offset:53248
	ds_read_b128 v[210:213], v155 offset:54272
	ds_read_b128 v[214:217], v155 offset:55296
	ds_read_b128 v[218:221], v155 offset:56320
	global_load_lds_dwordx4 v[224:225], off
	s_add_i32 m0, s14, 0x2000
	v_lshl_add_u64 v[224:225], s[12:13], 0, v[138:139]
	s_add_u32 s12, s46, 0xc000
	s_addc_u32 s13, s47, 0
	s_add_i32 s14, s64, s17
	global_load_lds_dwordx4 v[224:225], off
	v_lshl_add_u64 v[224:225], s[12:13], 0, v[134:135]
	s_mov_b32 m0, s14
	v_lshl_add_u64 v[144:145], v[144:145], 0, s[34:35]
	global_load_lds_dwordx4 v[224:225], off
	s_add_i32 m0, s14, 0x2000
	v_lshl_add_u64 v[224:225], s[12:13], 0, v[138:139]
	global_load_lds_dwordx4 v[224:225], off
	s_mov_b32 m0, s48
	s_nop 0
	global_load_lds_dwordx4 v[144:145], off
	s_mov_b32 m0, s49
	v_lshl_add_u64 v[144:145], v[222:223], 0, s[34:35]
	global_load_lds_dwordx4 v[144:145], off
	s_waitcnt vmcnt(8) lgkmcnt(0)
	s_barrier
	v_mfma_f32_16x16x32_bf16 v[76:79], v[158:161], v[190:193], v[76:79]
	v_mfma_f32_16x16x32_bf16 v[76:79], v[162:165], v[194:197], v[76:79]
	v_mfma_f32_16x16x32_bf16 v[52:55], v[166:169], v[190:193], v[52:55]
	v_mfma_f32_16x16x32_bf16 v[52:55], v[170:173], v[194:197], v[52:55]
	v_mfma_f32_16x16x32_bf16 v[36:39], v[166:169], v[198:201], v[36:39]
	v_mfma_f32_16x16x32_bf16 v[36:39], v[170:173], v[202:205], v[36:39]
	v_mfma_f32_16x16x32_bf16 v[48:51], v[158:161], v[198:201], v[48:51]
	v_mfma_f32_16x16x32_bf16 v[48:51], v[162:165], v[202:205], v[48:51]
	v_mfma_f32_16x16x32_bf16 v[32:35], v[158:161], v[206:209], v[32:35]
	v_mfma_f32_16x16x32_bf16 v[32:35], v[162:165], v[210:213], v[32:35]
	v_mfma_f32_16x16x32_bf16 v[20:23], v[166:169], v[206:209], v[20:23]
	v_mfma_f32_16x16x32_bf16 v[20:23], v[170:173], v[210:213], v[20:23]
	v_mfma_f32_16x16x32_bf16 v[4:7], v[166:169], v[214:217], v[4:7]
	v_mfma_f32_16x16x32_bf16 v[4:7], v[170:173], v[218:221], v[4:7]
	v_mfma_f32_16x16x32_bf16 v[16:19], v[158:161], v[214:217], v[16:19]
	v_mfma_f32_16x16x32_bf16 v[16:19], v[162:165], v[218:221], v[16:19]
	v_mfma_f32_16x16x32_bf16 v[12:15], v[174:177], v[214:217], v[12:15]
	v_mfma_f32_16x16x32_bf16 v[12:15], v[178:181], v[218:221], v[12:15]
	v_mfma_f32_16x16x32_bf16 v[8:11], v[182:185], v[214:217], v[8:11]
	v_mfma_f32_16x16x32_bf16 v[8:11], v[186:189], v[218:221], v[8:11]
	v_mfma_f32_16x16x32_bf16 v[24:27], v[182:185], v[206:209], v[24:27]
	v_mfma_f32_16x16x32_bf16 v[24:27], v[186:189], v[210:213], v[24:27]
	v_mfma_f32_16x16x32_bf16 v[28:31], v[174:177], v[206:209], v[28:31]
	v_mfma_f32_16x16x32_bf16 v[28:31], v[178:181], v[210:213], v[28:31]
	v_mfma_f32_16x16x32_bf16 v[44:47], v[174:177], v[198:201], v[44:47]
	v_mfma_f32_16x16x32_bf16 v[44:47], v[178:181], v[202:205], v[44:47]
	v_mfma_f32_16x16x32_bf16 v[40:43], v[182:185], v[198:201], v[40:43]
	v_mfma_f32_16x16x32_bf16 v[40:43], v[186:189], v[202:205], v[40:43]
	v_mfma_f32_16x16x32_bf16 v[56:59], v[182:185], v[190:193], v[56:59]
	v_mfma_f32_16x16x32_bf16 v[56:59], v[186:189], v[194:197], v[56:59]
	v_mfma_f32_16x16x32_bf16 v[60:63], v[174:177], v[190:193], v[60:63]
	v_mfma_f32_16x16x32_bf16 v[60:63], v[178:181], v[194:197], v[60:63]
	s_barrier
	s_add_i32 s0, s0, 2
	s_add_u32 s1, s1, 0x10000
	s_addc_u32 s59, s59, 0
	s_add_u32 s60, s60, 0x100
	s_addc_u32 s61, s61, 0
	s_add_u32 s44, s44, 0xffffff00
	s_addc_u32 s45, s45, -1
	v_lshl_add_u64 v[2:3], v[2:3], 0, s[38:39]
	s_cmpk_gt_u32 s0, 0xa9
	v_lshl_add_u64 v[148:149], v[148:149], 0, s[38:39]
	s_cbranch_scc0 .LBB0_1734
	s_and_b64 vcc, exec, s[36:37]
	s_cbranch_vccz .LBB0_1737
	s_barrier
